# GEMM K-loops: post-barrier address/M0 setup moved in front of the segment barrier (loop-edge / segment-head edit)
# baseline (speedup 1.0000x reference)
; #define G_STAGE(bufoff, gbase, voff) do { _Pragma("unroll") for (int _i = 0; _i < 2; ++_i) \
;     __builtin_amdgcn_global_load_lds((const unsigned*)((const char*)(gbase) + (voff)[_i]), (LAS unsigned*)(lds + (bufoff) + ldsw + _i * 8192), 16, 0, 0); } while (0)
; #define G_LDA(dst, b, h) do { _Pragma("unroll") for (int m = 0; m < 4; ++m) _Pragma("unroll") for (int k = 0; k < 2; ++k) dst[m][k] = *(const LAS bf16x8*)(lds + G_SA(b, h) + aoff + m * 2048 + k * 1024); } while (0)
; #define G_WAIT_V(n) asm volatile("s_waitcnt vmcnt(" #n ")" ::: "memory")
; #define G_WAIT_L(n) asm volatile("s_waitcnt lgkmcnt(" #n ")" ::: "memory")
; #define G_BAR __builtin_amdgcn_s_barrier()
; template <class Epi>
; __device__ __forceinline__ void gemm_phase(LAS unsigned char* lds, const u16* gA, const u16* gBt, int M, int N, int K, const Epi& E) {
;     ...
;     const bool has_next = S.next(ui + 1, nxt);
;     const char* nA = has_next ? (const char*)gA + (size_t)nxt.pm * tstep : cA; const char* nB = has_next ? (const char*)gBt + (size_t)nxt.pn * tstep : cB;
;     for (int t = 0; t < nt; t += 2) {
;       const bool last = (t == nt - 2);
;       const char* a1 = cA + (size_t)(t + 1) * kstep;
;       const char* a2 = last ? nA : cA + (size_t)(t + 2) * kstep; const char* b2 = last ? nB : cB + (size_t)(t + 2) * kstep;
;       const char* a3 = a2 + kstep; const char* b3 = b2 + kstep;
;       G_LDB(B0, 0, 0); G_SCHED; G_LDA(At, 0, 0); G_STAGE(G_SA(1, 1), a1 + hstep, voffA);
;       G_WAIT_L(8); G_BAR; G_WAIT_L(0); G_MMA(0, 0, At, B0); G_BAR; G_SCHED;
;       G_LDB(B1, 0, 1); G_STAGE(G_SB(0, 0), b2, voffB);
;       G_BAR; G_WAIT_L(0); G_MMA(0, 1, At, B1); G_BAR;
;       G_LDA(At, 0, 1); G_STAGE(G_SA(0, 0), a2, voffA);
;       G_BAR; G_WAIT_L(0); G_MMA(1, 0, At, B0); G_BAR; G_SCHED;
;       G_STAGE(G_SB(0, 1), b2 + hstep, voffB);
;       G_WAIT_V(6); G_BAR; G_MMA(1, 1, At, B1); G_BAR;
;       G_LDB(B0, 1, 0); G_SCHED; G_LDA(At, 1, 0); G_STAGE(G_SA(0, 1), a2 + hstep, voffA);
;       G_WAIT_L(8); G_BAR; G_WAIT_L(0); G_MMA(0, 0, At, B0); G_BAR; G_SCHED;
;       G_LDB(B1, 1, 1); G_STAGE(G_SB(1, 0), b3, voffB);
;       G_BAR; G_WAIT_L(0); G_MMA(0, 1, At, B1); G_BAR;
;       G_LDA(At, 1, 1); G_STAGE(G_SA(1, 0), a3, voffA);
;       G_BAR; G_WAIT_L(0); G_MMA(1, 0, At, B0); G_BAR; G_SCHED;
;       G_STAGE(G_SB(1, 1), b3 + hstep, voffB);
;       G_WAIT_V(6); G_BAR; G_MMA(1, 1, At, B1); G_BAR;
.LBB0_42:
	s_add_u32 s40, s46, 0x100
	s_addc_u32 s41, s47, 0
	s_add_i32 s20, 0, 0x10000
	v_add_u32_e32 v140, s20, v143
	ds_read_b128 v[146:149], v140
	ds_read_b128 v[150:153], v140 offset:1024
	ds_read_b128 v[154:157], v140 offset:2048
	ds_read_b128 v[158:161], v140 offset:3072
	s_cmpk_eq_i32 s31, 0x54
	s_cselect_b32 s51, s1, s41
	s_cselect_b32 s50, s0, s40
	s_cselect_b32 s49, s3, s30
	s_cselect_b32 s48, s2, s27
	v_lshl_add_u64 v[140:141], s[46:47], 0, v[136:137]
	s_add_i32 m0, s54, 0xc000
	ds_read_b128 v[162:165], v145
	ds_read_b128 v[190:193], v145 offset:1024
	ds_read_b128 v[194:197], v145 offset:2048
	ds_read_b128 v[198:201], v145 offset:3072
	ds_read_b128 v[202:205], v145 offset:4096
	ds_read_b128 v[206:209], v145 offset:5120
	ds_read_b128 v[210:213], v145 offset:6144
	ds_read_b128 v[214:217], v145 offset:7168
	global_load_lds_dwordx4 v[140:141], off
	v_lshl_add_u64 v[140:141], s[46:47], 0, v[138:139]
	s_add_i32 m0, s54, 0xe000
	s_nop 0
	global_load_lds_dwordx4 v[140:141], off
	s_waitcnt lgkmcnt(8)
	s_barrier
	s_waitcnt lgkmcnt(0)
	s_setprio 1
	s_waitcnt lgkmcnt(0)
	v_mfma_f32_16x16x32_bf16 v[124:127], v[146:149], v[162:165], v[124:127]
	v_mfma_f32_16x16x32_bf16 v[120:123], v[154:157], v[162:165], v[120:123]
	v_mfma_f32_16x16x32_bf16 v[108:111], v[146:149], v[194:197], v[108:111]
	v_mfma_f32_16x16x32_bf16 v[104:107], v[154:157], v[194:197], v[104:107]
	v_mfma_f32_16x16x32_bf16 v[92:95], v[146:149], v[202:205], v[92:95]
	v_mfma_f32_16x16x32_bf16 v[88:91], v[154:157], v[202:205], v[88:91]
	v_mfma_f32_16x16x32_bf16 v[76:79], v[146:149], v[210:213], v[76:79]
	v_mfma_f32_16x16x32_bf16 v[72:75], v[154:157], v[210:213], v[72:75]
	v_mfma_f32_16x16x32_bf16 v[124:127], v[150:153], v[190:193], v[124:127]
	v_mfma_f32_16x16x32_bf16 v[120:123], v[158:161], v[190:193], v[120:123]
	v_mfma_f32_16x16x32_bf16 v[108:111], v[150:153], v[198:201], v[108:111]
	v_mfma_f32_16x16x32_bf16 v[104:107], v[158:161], v[198:201], v[104:107]
	v_mfma_f32_16x16x32_bf16 v[92:95], v[150:153], v[206:209], v[92:95]
	v_mfma_f32_16x16x32_bf16 v[88:91], v[158:161], v[206:209], v[88:91]
	v_mfma_f32_16x16x32_bf16 v[76:79], v[150:153], v[214:217], v[76:79]
	v_mfma_f32_16x16x32_bf16 v[72:75], v[158:161], v[214:217], v[72:75]
	s_setprio 0
	s_add_i32 s22, 0, 0x14000
	v_add_u32_e32 v140, s22, v143
	s_add_i32 s20, s20, s53
	s_barrier
	ds_read_b128 v[218:221], v140
	ds_read_b128 v[222:225], v140 offset:1024
	ds_read_b128 v[226:229], v140 offset:2048
	ds_read_b128 v[230:233], v140 offset:3072
	v_lshl_add_u64 v[140:141], s[48:49], 0, v[128:129]
	s_mov_b32 m0, s20
	v_lshl_add_u64 v[166:167], s[48:49], 0, v[134:135]
	global_load_lds_dwordx4 v[140:141], off
	s_add_i32 m0, s20, 0x2000
	s_nop 0
	global_load_lds_dwordx4 v[166:167], off
	s_barrier
	s_waitcnt lgkmcnt(0)
	s_setprio 1
	s_waitcnt lgkmcnt(0)
	v_mfma_f32_16x16x32_bf16 v[116:119], v[218:221], v[162:165], v[116:119]
	v_mfma_f32_16x16x32_bf16 v[112:115], v[226:229], v[162:165], v[112:115]
	v_mfma_f32_16x16x32_bf16 v[100:103], v[218:221], v[194:197], v[100:103]
	v_mfma_f32_16x16x32_bf16 v[96:99], v[226:229], v[194:197], v[96:99]
	v_mfma_f32_16x16x32_bf16 v[84:87], v[218:221], v[202:205], v[84:87]
	v_mfma_f32_16x16x32_bf16 v[80:83], v[226:229], v[202:205], v[80:83]
	v_mfma_f32_16x16x32_bf16 v[68:71], v[218:221], v[210:213], v[68:71]
	v_mfma_f32_16x16x32_bf16 v[64:67], v[226:229], v[210:213], v[64:67]
	v_mfma_f32_16x16x32_bf16 v[116:119], v[222:225], v[190:193], v[116:119]
	v_mfma_f32_16x16x32_bf16 v[112:115], v[230:233], v[190:193], v[112:115]
	v_mfma_f32_16x16x32_bf16 v[100:103], v[222:225], v[198:201], v[100:103]
	v_mfma_f32_16x16x32_bf16 v[96:99], v[230:233], v[198:201], v[96:99]
	v_mfma_f32_16x16x32_bf16 v[84:87], v[222:225], v[206:209], v[84:87]
	v_mfma_f32_16x16x32_bf16 v[80:83], v[230:233], v[206:209], v[80:83]
	v_mfma_f32_16x16x32_bf16 v[68:71], v[222:225], v[214:217], v[68:71]
	v_mfma_f32_16x16x32_bf16 v[64:67], v[230:233], v[214:217], v[64:67]
	s_setprio 0
	s_mov_b32 m0, s54
	v_lshl_add_u64 v[234:235], s[50:51], 0, v[128:129]
	s_barrier
	ds_read_b128 v[162:165], v145 offset:16384
	ds_read_b128 v[190:193], v145 offset:17408
	ds_read_b128 v[194:197], v145 offset:18432
	ds_read_b128 v[198:201], v145 offset:19456
	ds_read_b128 v[202:205], v145 offset:20480
	ds_read_b128 v[206:209], v145 offset:21504
	ds_read_b128 v[210:213], v145 offset:22528
	ds_read_b128 v[214:217], v145 offset:23552
	global_load_lds_dwordx4 v[234:235], off
	v_lshl_add_u64 v[236:237], s[50:51], 0, v[134:135]
	s_mov_b32 m0, s55
	s_nop 0
	global_load_lds_dwordx4 v[236:237], off
	s_barrier
	s_waitcnt lgkmcnt(0)
	s_setprio 1
	s_waitcnt lgkmcnt(0)
	v_mfma_f32_16x16x32_bf16 v[60:63], v[146:149], v[162:165], v[60:63]
	v_mfma_f32_16x16x32_bf16 v[56:59], v[154:157], v[162:165], v[56:59]
	v_mfma_f32_16x16x32_bf16 v[44:47], v[146:149], v[194:197], v[44:47]
	v_mfma_f32_16x16x32_bf16 v[40:43], v[154:157], v[194:197], v[40:43]
	v_mfma_f32_16x16x32_bf16 v[28:31], v[146:149], v[202:205], v[28:31]
	v_mfma_f32_16x16x32_bf16 v[24:27], v[154:157], v[202:205], v[24:27]
	v_mfma_f32_16x16x32_bf16 v[12:15], v[146:149], v[210:213], v[12:15]
	v_mfma_f32_16x16x32_bf16 v[8:11], v[154:157], v[210:213], v[8:11]
	v_mfma_f32_16x16x32_bf16 v[60:63], v[150:153], v[190:193], v[60:63]
	v_mfma_f32_16x16x32_bf16 v[56:59], v[158:161], v[190:193], v[56:59]
	v_mfma_f32_16x16x32_bf16 v[44:47], v[150:153], v[198:201], v[44:47]
	v_mfma_f32_16x16x32_bf16 v[40:43], v[158:161], v[198:201], v[40:43]
	v_mfma_f32_16x16x32_bf16 v[28:31], v[150:153], v[206:209], v[28:31]
	v_mfma_f32_16x16x32_bf16 v[24:27], v[158:161], v[206:209], v[24:27]
	v_mfma_f32_16x16x32_bf16 v[12:15], v[150:153], v[214:217], v[12:15]
	v_mfma_f32_16x16x32_bf16 v[8:11], v[158:161], v[214:217], v[8:11]
	s_setprio 0
	s_add_u32 s24, s48, 0x160000
	s_addc_u32 s25, s49, 0
	s_add_i32 s20, s22, s53
	v_lshl_add_u64 v[146:147], s[24:25], 0, v[128:129]
	s_mov_b32 m0, s20
	s_barrier
; #define G_STAGE(bufoff, gbase, voff) do { _Pragma("unroll") for (int _i = 0; _i < 2; ++_i) \
;     __builtin_amdgcn_global_load_lds((const unsigned*)((const char*)(gbase) + (voff)[_i]), (LAS unsigned*)(lds + (bufoff) + ldsw + _i * 8192), 16, 0, 0); } while (0)
; #define G_LDA(dst, b, h) do { _Pragma("unroll") for (int m = 0; m < 4; ++m) _Pragma("unroll") for (int k = 0; k < 2; ++k) dst[m][k] = *(const LAS bf16x8*)(lds + G_SA(b, h) + aoff + m * 2048 + k * 1024); } while (0)
; #define G_LDB(dst, b, h) do { _Pragma("unroll") for (int n = 0; n < 2; ++n) _Pragma("unroll") for (int k = 0; k < 2; ++k) dst[n][k] = *(const LAS bf16x8*)(lds + G_SB(b, h) + boff + n * 2048 + k * 1024); } while (0)
; #define G_MMA(ai, bj, At, Bt) do { __builtin_amdgcn_s_setprio(1); _Pragma("unroll") for (int m = 0; m < 4; ++m) _Pragma("unroll") for (int n = 0; n < 2; ++n) _Pragma("unroll") for (int k = 0; k < 2; ++k) \
;     acc[ai][bj][m][n] = __builtin_amdgcn_mfma_f32_16x16x32_bf16(Bt[n][k], At[m][k], acc[ai][bj][m][n], 0, 0, 0); __builtin_amdgcn_s_setprio(0); } while (0)
; #define G_WAIT_V(n) asm volatile("s_waitcnt vmcnt(" #n ")" ::: "memory")
; #define G_WAIT_L(n) asm volatile("s_waitcnt lgkmcnt(" #n ")" ::: "memory")
; template <class Epi>
; __device__ __forceinline__ void gemm_phase(LAS unsigned char* lds, const u16* gA, const u16* gBt, int M, int N, int K, const Epi& E) {
;     ...
;       G_LDB(B0, 0, 0); G_SCHED; G_LDA(At, 0, 0); G_STAGE(G_SA(1, 1), a1 + hstep, voffA);
;       G_WAIT_L(8); G_BAR; G_WAIT_L(0); G_MMA(0, 0, At, B0); G_BAR; G_SCHED;
;       G_LDB(B1, 0, 1); G_STAGE(G_SB(0, 0), b2, voffB);
;       G_BAR; G_WAIT_L(0); G_MMA(0, 1, At, B1); G_BAR;
;       G_LDA(At, 0, 1); G_STAGE(G_SA(0, 0), a2, voffA);
;       G_BAR; G_WAIT_L(0); G_MMA(1, 0, At, B0); G_BAR; G_SCHED;
;       G_STAGE(G_SB(0, 1), b2 + hstep, voffB);
;       G_WAIT_V(6); G_BAR; G_MMA(1, 1, At, B1); G_BAR;
;       G_LDB(B0, 1, 0); G_SCHED; G_LDA(At, 1, 0); G_STAGE(G_SA(0, 1), a2 + hstep, voffA);
;       G_WAIT_L(8); G_BAR; G_WAIT_L(0); G_MMA(0, 0, At, B0); G_BAR; G_SCHED;
;       G_LDB(B1, 1, 1); G_STAGE(G_SB(1, 0), b3, voffB);
;       G_BAR; G_WAIT_L(0); G_MMA(0, 1, At, B1); G_BAR;
;       G_LDA(At, 1, 1); G_STAGE(G_SA(1, 0), a3, voffA);
;       G_BAR; G_WAIT_L(0); G_MMA(1, 0, At, B0); G_BAR; G_SCHED;
;       G_STAGE(G_SB(1, 1), b3 + hstep, voffB);
;       G_WAIT_V(6); G_BAR; G_MMA(1, 1, At, B1); G_BAR;
	s_nop 0
	global_load_lds_dwordx4 v[146:147], off
	v_lshl_add_u64 v[146:147], s[24:25], 0, v[134:135]
	s_add_i32 m0, s20, 0x2000
	s_nop 0
	global_load_lds_dwordx4 v[146:147], off
	s_waitcnt vmcnt(6)
	s_barrier
	s_setprio 1
	v_mfma_f32_16x16x32_bf16 v[52:55], v[218:221], v[162:165], v[52:55]
	v_mfma_f32_16x16x32_bf16 v[48:51], v[226:229], v[162:165], v[48:51]
	v_mfma_f32_16x16x32_bf16 v[36:39], v[218:221], v[194:197], v[36:39]
	v_mfma_f32_16x16x32_bf16 v[32:35], v[226:229], v[194:197], v[32:35]
	v_mfma_f32_16x16x32_bf16 v[20:23], v[218:221], v[202:205], v[20:23]
	v_mfma_f32_16x16x32_bf16 v[16:19], v[226:229], v[202:205], v[16:19]
	v_mfma_f32_16x16x32_bf16 v[4:7], v[218:221], v[210:213], v[4:7]
	v_mfma_f32_16x16x32_bf16 v[0:3], v[226:229], v[210:213], v[0:3]
	v_mfma_f32_16x16x32_bf16 v[52:55], v[222:225], v[190:193], v[52:55]
	v_mfma_f32_16x16x32_bf16 v[48:51], v[230:233], v[190:193], v[48:51]
	v_mfma_f32_16x16x32_bf16 v[36:39], v[222:225], v[198:201], v[36:39]
	v_mfma_f32_16x16x32_bf16 v[32:35], v[230:233], v[198:201], v[32:35]
	v_mfma_f32_16x16x32_bf16 v[20:23], v[222:225], v[206:209], v[20:23]
	v_mfma_f32_16x16x32_bf16 v[16:19], v[230:233], v[206:209], v[16:19]
	v_mfma_f32_16x16x32_bf16 v[4:7], v[222:225], v[214:217], v[4:7]
	v_mfma_f32_16x16x32_bf16 v[0:3], v[230:233], v[214:217], v[0:3]
	s_setprio 0
	s_add_i32 s20, 0, 0x18000
	v_add_u32_e32 v158, s20, v143
	s_barrier
	ds_read_b128 v[146:149], v158
	ds_read_b128 v[150:153], v158 offset:1024
	ds_read_b128 v[154:157], v158 offset:2048
	ds_read_b128 v[158:161], v158 offset:3072
	s_add_u32 s24, s50, 0x160000
	s_addc_u32 s25, s51, 0
	s_mov_b32 m0, s63
	v_lshl_add_u64 v[218:219], s[24:25], 0, v[128:129]
	ds_read_b128 v[162:165], v145 offset:32768
	ds_read_b128 v[190:193], v145 offset:33792
	ds_read_b128 v[194:197], v145 offset:34816
	ds_read_b128 v[198:201], v145 offset:35840
	ds_read_b128 v[202:205], v145 offset:36864
	ds_read_b128 v[206:209], v145 offset:37888
	ds_read_b128 v[210:213], v145 offset:38912
	ds_read_b128 v[214:217], v145 offset:39936
	global_load_lds_dwordx4 v[218:219], off
	v_lshl_add_u64 v[218:219], s[24:25], 0, v[134:135]
	s_mov_b32 m0, s64
	s_nop 0
	global_load_lds_dwordx4 v[218:219], off
	s_waitcnt lgkmcnt(8)
	s_barrier
	s_waitcnt lgkmcnt(0)
	s_setprio 1
	s_waitcnt lgkmcnt(0)
	v_mfma_f32_16x16x32_bf16 v[124:127], v[146:149], v[162:165], v[124:127]
	v_mfma_f32_16x16x32_bf16 v[120:123], v[154:157], v[162:165], v[120:123]
	v_mfma_f32_16x16x32_bf16 v[108:111], v[146:149], v[194:197], v[108:111]
	v_mfma_f32_16x16x32_bf16 v[104:107], v[154:157], v[194:197], v[104:107]
	v_mfma_f32_16x16x32_bf16 v[92:95], v[146:149], v[202:205], v[92:95]
	v_mfma_f32_16x16x32_bf16 v[88:91], v[154:157], v[202:205], v[88:91]
	v_mfma_f32_16x16x32_bf16 v[76:79], v[146:149], v[210:213], v[76:79]
	v_mfma_f32_16x16x32_bf16 v[72:75], v[154:157], v[210:213], v[72:75]
	v_mfma_f32_16x16x32_bf16 v[124:127], v[150:153], v[190:193], v[124:127]
	v_mfma_f32_16x16x32_bf16 v[120:123], v[158:161], v[190:193], v[120:123]
	v_mfma_f32_16x16x32_bf16 v[108:111], v[150:153], v[198:201], v[108:111]
	v_mfma_f32_16x16x32_bf16 v[104:107], v[158:161], v[198:201], v[104:107]
	v_mfma_f32_16x16x32_bf16 v[92:95], v[150:153], v[206:209], v[92:95]
	v_mfma_f32_16x16x32_bf16 v[88:91], v[158:161], v[206:209], v[88:91]
	v_mfma_f32_16x16x32_bf16 v[76:79], v[150:153], v[214:217], v[76:79]
	v_mfma_f32_16x16x32_bf16 v[72:75], v[158:161], v[214:217], v[72:75]
	s_setprio 0
	s_add_i32 s22, 0, 0x1c000
	s_add_i32 s20, s20, s53
	v_add_u32_e32 v230, s22, v143
	v_lshl_add_u64 v[140:141], v[140:141], 0, s[34:35]
	s_mov_b32 m0, s20
	s_barrier
	ds_read_b128 v[218:221], v230
	ds_read_b128 v[222:225], v230 offset:1024
	ds_read_b128 v[226:229], v230 offset:2048
	ds_read_b128 v[230:233], v230 offset:3072
	global_load_lds_dwordx4 v[140:141], off
	v_lshl_add_u64 v[140:141], v[166:167], 0, s[34:35]
	s_add_i32 m0, s20, 0x2000
	s_nop 0
	global_load_lds_dwordx4 v[140:141], off
	s_barrier
	s_waitcnt lgkmcnt(0)
	s_setprio 1
	s_waitcnt lgkmcnt(0)
	v_mfma_f32_16x16x32_bf16 v[116:119], v[218:221], v[162:165], v[116:119]
	v_mfma_f32_16x16x32_bf16 v[112:115], v[226:229], v[162:165], v[112:115]
	v_mfma_f32_16x16x32_bf16 v[100:103], v[218:221], v[194:197], v[100:103]
	v_mfma_f32_16x16x32_bf16 v[96:99], v[226:229], v[194:197], v[96:99]
	v_mfma_f32_16x16x32_bf16 v[84:87], v[218:221], v[202:205], v[84:87]
	v_mfma_f32_16x16x32_bf16 v[80:83], v[226:229], v[202:205], v[80:83]
	v_mfma_f32_16x16x32_bf16 v[68:71], v[218:221], v[210:213], v[68:71]
	v_mfma_f32_16x16x32_bf16 v[64:67], v[226:229], v[210:213], v[64:67]
	v_mfma_f32_16x16x32_bf16 v[116:119], v[222:225], v[190:193], v[116:119]
	v_mfma_f32_16x16x32_bf16 v[112:115], v[230:233], v[190:193], v[112:115]
	v_mfma_f32_16x16x32_bf16 v[100:103], v[222:225], v[198:201], v[100:103]
	v_mfma_f32_16x16x32_bf16 v[96:99], v[230:233], v[198:201], v[96:99]
	v_mfma_f32_16x16x32_bf16 v[84:87], v[222:225], v[206:209], v[84:87]
	v_mfma_f32_16x16x32_bf16 v[80:83], v[230:233], v[206:209], v[80:83]
	v_mfma_f32_16x16x32_bf16 v[68:71], v[222:225], v[214:217], v[68:71]
	v_mfma_f32_16x16x32_bf16 v[64:67], v[230:233], v[214:217], v[64:67]
	s_setprio 0
	s_mov_b32 m0, s66
	v_lshl_add_u64 v[140:141], v[234:235], 0, s[34:35]
	s_barrier
	ds_read_b128 v[162:165], v145 offset:49152
	ds_read_b128 v[190:193], v145 offset:50176
	ds_read_b128 v[194:197], v145 offset:51200
	ds_read_b128 v[198:201], v145 offset:52224
	ds_read_b128 v[202:205], v145 offset:53248
	ds_read_b128 v[206:209], v145 offset:54272
	ds_read_b128 v[210:213], v145 offset:55296
	ds_read_b128 v[214:217], v145 offset:56320
	global_load_lds_dwordx4 v[140:141], off
	v_lshl_add_u64 v[140:141], v[236:237], 0, s[34:35]
	s_mov_b32 m0, s67
	s_nop 0
	global_load_lds_dwordx4 v[140:141], off
	s_barrier
; #define G_STAGE(bufoff, gbase, voff) do { _Pragma("unroll") for (int _i = 0; _i < 2; ++_i) \
;     __builtin_amdgcn_global_load_lds((const unsigned*)((const char*)(gbase) + (voff)[_i]), (LAS unsigned*)(lds + (bufoff) + ldsw + _i * 8192), 16, 0, 0); } while (0)
; #define G_LDA(dst, b, h) do { _Pragma("unroll") for (int m = 0; m < 4; ++m) _Pragma("unroll") for (int k = 0; k < 2; ++k) dst[m][k] = *(const LAS bf16x8*)(lds + G_SA(b, h) + aoff + m * 2048 + k * 1024); } while (0)
; #define G_BAR __builtin_amdgcn_s_barrier()
;   __device__ __forceinline__ void operator()(const f32x4 (&acc)[2][2][4][2], const Unit& u, int wr, int wc, int fr, int fq) const {
;     const int row0 = u.pm * BM + wr * 64 + fr, col0 = u.pn * BM + wc * 32 + 4 * fq;
; #pragma unroll
;     for (int ai = 0; ai < 2; ++ai)
; #pragma unroll
;       for (int m = 0; m < 4; ++m) {
;         const int row = row0 + ai * HALF + m * 16;
;         const float* gp = gate + (size_t)condof(row) * 6 * D + col0;
;         const float* hold; float* hnew;
;         if (row < NX) { hnew = out + (size_t)row * D + col0; hold = xin ? xin + (size_t)row * D + col0 : hnew; }
;         else { hnew = hc + (size_t)(row - NX) * D + col0; hold = cin ? cin + (size_t)(row - NX) * D + col0 : hnew; }
; #pragma unroll
;         for (int bj = 0; bj < 2; ++bj)
; #pragma unroll
;           for (int n = 0; n < 2; ++n) {
;             f32x4 h = *reinterpret_cast<const f32x4*>(hold + bj * HALF + n * 16);
;             f32x4 g = *reinterpret_cast<const f32x4*>(gp + bj * HALF + n * 16);
;             *reinterpret_cast<f32x4*>(hnew + bj * HALF + n * 16) = h + g * acc[ai][bj][m][n];
;           }
;       }
; template <class Epi>
; __device__ __forceinline__ void gemm_phase(LAS unsigned char* lds, const u16* gA, const u16* gBt, int M, int N, int K, const Epi& E) {
;     ...
;       G_LDB(B0, 1, 0); G_SCHED; G_LDA(At, 1, 0); G_STAGE(G_SA(0, 1), a2 + hstep, voffA);
;       G_WAIT_L(8); G_BAR; G_WAIT_L(0); G_MMA(0, 0, At, B0); G_BAR; G_SCHED;
;       G_LDB(B1, 1, 1); G_STAGE(G_SB(1, 0), b3, voffB);
;       G_BAR; G_WAIT_L(0); G_MMA(0, 1, At, B1); G_BAR;
;       G_LDA(At, 1, 1); G_STAGE(G_SA(1, 0), a3, voffA);
;       G_BAR; G_WAIT_L(0); G_MMA(1, 0, At, B0); G_BAR; G_SCHED;
;       G_STAGE(G_SB(1, 1), b3 + hstep, voffB);
;       G_WAIT_V(6); G_BAR; G_MMA(1, 1, At, B1); G_BAR;
;     }
;     E(acc, cur, wr, wc, fr, fq);
;     if (!has_next) break;
	s_waitcnt lgkmcnt(0)
	s_setprio 1
	s_waitcnt lgkmcnt(0)
	v_mfma_f32_16x16x32_bf16 v[60:63], v[146:149], v[162:165], v[60:63]
	v_mfma_f32_16x16x32_bf16 v[56:59], v[154:157], v[162:165], v[56:59]
	v_mfma_f32_16x16x32_bf16 v[44:47], v[146:149], v[194:197], v[44:47]
	v_mfma_f32_16x16x32_bf16 v[40:43], v[154:157], v[194:197], v[40:43]
	v_mfma_f32_16x16x32_bf16 v[28:31], v[146:149], v[202:205], v[28:31]
	v_mfma_f32_16x16x32_bf16 v[24:27], v[154:157], v[202:205], v[24:27]
	v_mfma_f32_16x16x32_bf16 v[12:15], v[146:149], v[210:213], v[12:15]
	v_mfma_f32_16x16x32_bf16 v[8:11], v[154:157], v[210:213], v[8:11]
	v_mfma_f32_16x16x32_bf16 v[60:63], v[150:153], v[190:193], v[60:63]
	v_mfma_f32_16x16x32_bf16 v[56:59], v[158:161], v[190:193], v[56:59]
	v_mfma_f32_16x16x32_bf16 v[44:47], v[150:153], v[198:201], v[44:47]
	v_mfma_f32_16x16x32_bf16 v[40:43], v[158:161], v[198:201], v[40:43]
	v_mfma_f32_16x16x32_bf16 v[28:31], v[150:153], v[206:209], v[28:31]
	v_mfma_f32_16x16x32_bf16 v[24:27], v[158:161], v[206:209], v[24:27]
	v_mfma_f32_16x16x32_bf16 v[12:15], v[150:153], v[214:217], v[12:15]
	v_mfma_f32_16x16x32_bf16 v[8:11], v[158:161], v[214:217], v[8:11]
	s_setprio 0
	s_add_u32 s24, s48, 0x160080
	s_addc_u32 s25, s49, 0
	s_add_i32 s20, s22, s53
	v_lshl_add_u64 v[140:141], s[24:25], 0, v[128:129]
	s_mov_b32 m0, s20
	s_barrier
	s_nop 0
	global_load_lds_dwordx4 v[140:141], off
	v_lshl_add_u64 v[140:141], s[24:25], 0, v[134:135]
	s_add_i32 m0, s20, 0x2000
	s_nop 0
	global_load_lds_dwordx4 v[140:141], off
	s_waitcnt vmcnt(6)
	s_barrier
	s_setprio 1
	v_mfma_f32_16x16x32_bf16 v[52:55], v[218:221], v[162:165], v[52:55]
	v_mfma_f32_16x16x32_bf16 v[48:51], v[226:229], v[162:165], v[48:51]
	v_mfma_f32_16x16x32_bf16 v[36:39], v[218:221], v[194:197], v[36:39]
	v_mfma_f32_16x16x32_bf16 v[32:35], v[226:229], v[194:197], v[32:35]
	v_mfma_f32_16x16x32_bf16 v[20:23], v[218:221], v[202:205], v[20:23]
	v_mfma_f32_16x16x32_bf16 v[16:19], v[226:229], v[202:205], v[16:19]
	v_mfma_f32_16x16x32_bf16 v[4:7], v[218:221], v[210:213], v[4:7]
	v_mfma_f32_16x16x32_bf16 v[0:3], v[226:229], v[210:213], v[0:3]
	v_mfma_f32_16x16x32_bf16 v[52:55], v[222:225], v[190:193], v[52:55]
	v_mfma_f32_16x16x32_bf16 v[48:51], v[230:233], v[190:193], v[48:51]
	v_mfma_f32_16x16x32_bf16 v[36:39], v[222:225], v[198:201], v[36:39]
	v_mfma_f32_16x16x32_bf16 v[32:35], v[230:233], v[198:201], v[32:35]
	v_mfma_f32_16x16x32_bf16 v[20:23], v[222:225], v[206:209], v[20:23]
	v_mfma_f32_16x16x32_bf16 v[16:19], v[230:233], v[206:209], v[16:19]
	v_mfma_f32_16x16x32_bf16 v[4:7], v[222:225], v[214:217], v[4:7]
	v_mfma_f32_16x16x32_bf16 v[0:3], v[230:233], v[214:217], v[0:3]
	s_setprio 0
	s_add_i32 s31, s31, 2
	s_add_u32 s27, s27, 0x100
	s_addc_u32 s30, s30, 0
	s_cmpk_gt_u32 s31, 0x55
	s_mov_b64 s[46:47], s[40:41]
	s_barrier
	s_cbranch_scc0 .LBB0_42
	v_lshl_add_u32 v146, s23, 8, v142
	v_min_i32_e32 v147, 0x4000, v146
	v_lshl_or_b32 v140, s26, 8, v144
	v_ashrrev_i32_e32 v147, 12, v147
	v_ashrrev_i32_e32 v141, 31, v140
	v_mul_hi_i32_i24_e32 v149, 0xc000, v147
	v_mul_i32_i24_e32 v148, 0xc000, v147
	v_lshl_add_u64 v[148:149], s[44:45], 0, v[148:149]
	v_lshlrev_b64 v[140:141], 2, v[140:141]
	s_movk_i32 s20, 0x4000
	v_lshl_add_u64 v[160:161], v[148:149], 0, v[140:141]
	global_load_dwordx4 v[190:193], v[160:161], off
	global_load_dwordx4 v[194:197], v[160:161], off offset:64
	global_load_dwordx4 v[198:201], v[160:161], off offset:512
	global_load_dwordx4 v[202:205], v[160:161], off offset:576
	v_cmp_gt_i32_e32 vcc, s20, v146
	v_add_u32_e32 v147, 0xffffc000, v146
	v_mov_b32_e32 v151, s7
	v_mov_b32_e32 v148, s83
	v_mov_b32_e32 v149, s6
	v_mov_b32_e32 v150, s82
	v_cndmask_b32_e32 v166, v147, v146, vcc
	v_cndmask_b32_e32 v155, v151, v148, vcc
	v_cndmask_b32_e32 v154, v149, v150, vcc
	v_mov_b32_e32 v165, 0
	v_lshl_add_u64 v[162:163], v[154:155], 0, v[140:141]
	s_mov_b32 s26, s70
	s_mov_b32 s23, s71
	s_mov_b64 s[48:49], s[2:3]
	s_mov_b64 s[46:47], s[0:1]
	v_mov_b32_e32 v164, v166
	v_lshlrev_b64 v[152:153], 13, v[164:165]
	v_lshl_add_u64 v[244:245], v[152:153], 0, v[162:163]
	global_load_dwordx4 v[206:209], v[244:245], off
	global_load_dwordx4 v[210:213], v[244:245], off offset:64
	global_load_dwordx4 v[214:217], v[244:245], off offset:512
	global_load_dwordx4 v[218:221], v[244:245], off offset:576
	v_add_u32_e32 v164, 0x10, v166
	v_lshlrev_b64 v[152:153], 13, v[164:165]
	v_lshl_add_u64 v[246:247], v[152:153], 0, v[162:163]
	global_load_dwordx4 v[222:225], v[246:247], off
	global_load_dwordx4 v[226:229], v[246:247], off offset:64
	global_load_dwordx4 v[230:233], v[246:247], off offset:512
	global_load_dwordx4 v[234:237], v[246:247], off offset:576
	v_add_u32_e32 v164, 0x20, v166
	v_lshlrev_b64 v[152:153], 13, v[164:165]
	v_lshl_add_u64 v[248:249], v[152:153], 0, v[162:163]
	v_add_u32_e32 v164, 0x30, v166
	v_lshlrev_b64 v[152:153], 13, v[164:165]
	v_lshl_add_u64 v[250:251], v[152:153], 0, v[162:163]
	v_add_u32_e32 v164, 0x80, v166
	v_lshlrev_b64 v[152:153], 13, v[164:165]
	v_lshl_add_u64 v[252:253], v[152:153], 0, v[162:163]
	v_add_u32_e32 v164, 0x90, v166
	v_lshlrev_b64 v[152:153], 13, v[164:165]
	v_lshl_add_u64 v[254:255], v[152:153], 0, v[162:163]
	v_add_u32_e32 v164, 0xa0, v166
	v_lshlrev_b64 v[152:153], 13, v[164:165]
	v_lshl_add_u64 v[156:157], v[152:153], 0, v[162:163]
	v_add_u32_e32 v164, 0xb0, v166
	v_lshlrev_b64 v[152:153], 13, v[164:165]
	v_lshl_add_u64 v[158:159], v[152:153], 0, v[162:163]
	s_waitcnt vmcnt(4)
;   __device__ __forceinline__ void operator()(const f32x4 (&acc)[2][2][4][2], const Unit& u, int wr, int wc, int fr, int fq) const {
;     ...
; #pragma unroll
;     for (int ai = 0; ai < 2; ++ai)
; #pragma unroll
;       for (int m = 0; m < 4; ++m) {
;         const int row = row0 + ai * HALF + m * 16;
;         const float* gp = gate + (size_t)condof(row) * 6 * D + col0;
;         const float* hold; float* hnew;
;         if (row < NX) { hnew = out + (size_t)row * D + col0; hold = xin ? xin + (size_t)row * D + col0 : hnew; }
;         else { hnew = hc + (size_t)(row - NX) * D + col0; hold = cin ? cin + (size_t)(row - NX) * D + col0 : hnew; }
; #pragma unroll
;         for (int bj = 0; bj < 2; ++bj)
; #pragma unroll
;           for (int n = 0; n < 2; ++n) {
;             f32x4 h = *reinterpret_cast<const f32x4*>(hold + bj * HALF + n * 16);
;             f32x4 g = *reinterpret_cast<const f32x4*>(gp + bj * HALF + n * 16);
;             *reinterpret_cast<f32x4*>(hnew + bj * HALF + n * 16) = h + g * acc[ai][bj][m][n];
;           }
;       }
	v_pk_fma_f32 v[126:127], v[126:127], v[192:193], v[208:209]
	v_pk_fma_f32 v[124:125], v[124:125], v[190:191], v[206:207]
	v_pk_fma_f32 v[122:123], v[122:123], v[196:197], v[212:213]
	v_pk_fma_f32 v[120:121], v[120:121], v[194:195], v[210:211]
	v_pk_fma_f32 v[118:119], v[118:119], v[200:201], v[216:217]
	v_pk_fma_f32 v[116:117], v[116:117], v[198:199], v[214:215]
	v_pk_fma_f32 v[114:115], v[114:115], v[204:205], v[220:221]
	v_pk_fma_f32 v[112:113], v[112:113], v[202:203], v[218:219]
	global_store_dwordx4 v[244:245], v[124:127], off
	global_store_dwordx4 v[244:245], v[120:123], off offset:64
	global_store_dwordx4 v[244:245], v[116:119], off offset:512
	global_store_dwordx4 v[244:245], v[112:115], off offset:576
	global_load_dwordx4 v[206:209], v[248:249], off
	global_load_dwordx4 v[210:213], v[248:249], off offset:64
	global_load_dwordx4 v[214:217], v[248:249], off offset:512
	global_load_dwordx4 v[218:221], v[248:249], off offset:576
	s_waitcnt vmcnt(4)
	v_pk_fma_f32 v[110:111], v[110:111], v[192:193], v[224:225]
	v_pk_fma_f32 v[108:109], v[108:109], v[190:191], v[222:223]
	v_pk_fma_f32 v[106:107], v[106:107], v[196:197], v[228:229]
	v_pk_fma_f32 v[104:105], v[104:105], v[194:195], v[226:227]
	v_pk_fma_f32 v[102:103], v[102:103], v[200:201], v[232:233]
	v_pk_fma_f32 v[100:101], v[100:101], v[198:199], v[230:231]
	v_pk_fma_f32 v[98:99], v[98:99], v[204:205], v[236:237]
	v_pk_fma_f32 v[96:97], v[96:97], v[202:203], v[234:235]
	global_store_dwordx4 v[246:247], v[108:111], off
	global_store_dwordx4 v[246:247], v[104:107], off offset:64
	global_store_dwordx4 v[246:247], v[100:103], off offset:512
	global_store_dwordx4 v[246:247], v[96:99], off offset:576
	global_load_dwordx4 v[222:225], v[250:251], off
	global_load_dwordx4 v[226:229], v[250:251], off offset:64
	global_load_dwordx4 v[230:233], v[250:251], off offset:512
	global_load_dwordx4 v[234:237], v[250:251], off offset:576
	s_waitcnt vmcnt(4)
	v_pk_fma_f32 v[94:95], v[94:95], v[192:193], v[208:209]
	v_pk_fma_f32 v[92:93], v[92:93], v[190:191], v[206:207]
	v_pk_fma_f32 v[90:91], v[90:91], v[196:197], v[212:213]
	v_pk_fma_f32 v[88:89], v[88:89], v[194:195], v[210:211]
	v_pk_fma_f32 v[86:87], v[86:87], v[200:201], v[216:217]
	v_pk_fma_f32 v[84:85], v[84:85], v[198:199], v[214:215]
	v_pk_fma_f32 v[82:83], v[82:83], v[204:205], v[220:221]
	v_pk_fma_f32 v[80:81], v[80:81], v[202:203], v[218:219]
	global_store_dwordx4 v[248:249], v[92:95], off
	global_store_dwordx4 v[248:249], v[88:91], off offset:64
	global_store_dwordx4 v[248:249], v[84:87], off offset:512
	global_store_dwordx4 v[248:249], v[80:83], off offset:576
	global_load_dwordx4 v[206:209], v[252:253], off
	global_load_dwordx4 v[210:213], v[252:253], off offset:64
	global_load_dwordx4 v[214:217], v[252:253], off offset:512
	global_load_dwordx4 v[218:221], v[252:253], off offset:576
	s_waitcnt vmcnt(4)
	v_pk_fma_f32 v[78:79], v[78:79], v[192:193], v[224:225]
	v_pk_fma_f32 v[76:77], v[76:77], v[190:191], v[222:223]
	v_pk_fma_f32 v[74:75], v[74:75], v[196:197], v[228:229]
	v_pk_fma_f32 v[72:73], v[72:73], v[194:195], v[226:227]
	v_pk_fma_f32 v[70:71], v[70:71], v[200:201], v[232:233]
	v_pk_fma_f32 v[68:69], v[68:69], v[198:199], v[230:231]
	v_pk_fma_f32 v[66:67], v[66:67], v[204:205], v[236:237]
	v_pk_fma_f32 v[64:65], v[64:65], v[202:203], v[234:235]
	global_store_dwordx4 v[250:251], v[76:79], off
	global_store_dwordx4 v[250:251], v[72:75], off offset:64
	global_store_dwordx4 v[250:251], v[68:71], off offset:512
	global_store_dwordx4 v[250:251], v[64:67], off offset:576
	global_load_dwordx4 v[222:225], v[254:255], off
	global_load_dwordx4 v[226:229], v[254:255], off offset:64
	global_load_dwordx4 v[230:233], v[254:255], off offset:512
	global_load_dwordx4 v[234:237], v[254:255], off offset:576
	s_waitcnt vmcnt(4)
	v_pk_fma_f32 v[62:63], v[62:63], v[192:193], v[208:209]
	v_pk_fma_f32 v[60:61], v[60:61], v[190:191], v[206:207]
	v_pk_fma_f32 v[58:59], v[58:59], v[196:197], v[212:213]
	v_pk_fma_f32 v[56:57], v[56:57], v[194:195], v[210:211]
	v_pk_fma_f32 v[54:55], v[54:55], v[200:201], v[216:217]
	v_pk_fma_f32 v[52:53], v[52:53], v[198:199], v[214:215]
	v_pk_fma_f32 v[50:51], v[50:51], v[204:205], v[220:221]
	v_pk_fma_f32 v[48:49], v[48:49], v[202:203], v[218:219]
	global_store_dwordx4 v[252:253], v[60:63], off
	global_store_dwordx4 v[252:253], v[56:59], off offset:64
	global_store_dwordx4 v[252:253], v[52:55], off offset:512
	global_store_dwordx4 v[252:253], v[48:51], off offset:576
	global_load_dwordx4 v[206:209], v[156:157], off
	global_load_dwordx4 v[210:213], v[156:157], off offset:64
	global_load_dwordx4 v[214:217], v[156:157], off offset:512
	global_load_dwordx4 v[218:221], v[156:157], off offset:576
	s_waitcnt vmcnt(4)
	v_pk_fma_f32 v[46:47], v[46:47], v[192:193], v[224:225]
	v_pk_fma_f32 v[44:45], v[44:45], v[190:191], v[222:223]
	v_pk_fma_f32 v[42:43], v[42:43], v[196:197], v[228:229]
	v_pk_fma_f32 v[40:41], v[40:41], v[194:195], v[226:227]
	v_pk_fma_f32 v[38:39], v[38:39], v[200:201], v[232:233]
	v_pk_fma_f32 v[36:37], v[36:37], v[198:199], v[230:231]
	v_pk_fma_f32 v[34:35], v[34:35], v[204:205], v[236:237]
	v_pk_fma_f32 v[32:33], v[32:33], v[202:203], v[234:235]
	global_store_dwordx4 v[254:255], v[44:47], off
	global_store_dwordx4 v[254:255], v[40:43], off offset:64
	global_store_dwordx4 v[254:255], v[36:39], off offset:512
	global_store_dwordx4 v[254:255], v[32:35], off offset:576
	global_load_dwordx4 v[222:225], v[158:159], off
	global_load_dwordx4 v[226:229], v[158:159], off offset:64
	global_load_dwordx4 v[230:233], v[158:159], off offset:512
	global_load_dwordx4 v[234:237], v[158:159], off offset:576
	s_waitcnt vmcnt(4)
	v_pk_fma_f32 v[30:31], v[30:31], v[192:193], v[208:209]
	v_pk_fma_f32 v[28:29], v[28:29], v[190:191], v[206:207]
	v_pk_fma_f32 v[26:27], v[26:27], v[196:197], v[212:213]
	v_pk_fma_f32 v[24:25], v[24:25], v[194:195], v[210:211]
	v_pk_fma_f32 v[22:23], v[22:23], v[200:201], v[216:217]
	v_pk_fma_f32 v[20:21], v[20:21], v[198:199], v[214:215]
	v_pk_fma_f32 v[18:19], v[18:19], v[204:205], v[220:221]
	v_pk_fma_f32 v[16:17], v[16:17], v[202:203], v[218:219]
	global_store_dwordx4 v[156:157], v[28:31], off
	global_store_dwordx4 v[156:157], v[24:27], off offset:64
	global_store_dwordx4 v[156:157], v[20:23], off offset:512
	global_store_dwordx4 v[156:157], v[16:19], off offset:576
	s_waitcnt vmcnt(0)
	v_pk_fma_f32 v[14:15], v[14:15], v[192:193], v[224:225]
	v_pk_fma_f32 v[12:13], v[12:13], v[190:191], v[222:223]
	v_pk_fma_f32 v[10:11], v[10:11], v[196:197], v[228:229]
	v_pk_fma_f32 v[8:9], v[8:9], v[194:195], v[226:227]
	v_pk_fma_f32 v[6:7], v[6:7], v[200:201], v[232:233]
	v_pk_fma_f32 v[4:5], v[4:5], v[198:199], v[230:231]
	v_pk_fma_f32 v[2:3], v[2:3], v[204:205], v[236:237]
	v_pk_fma_f32 v[0:1], v[0:1], v[202:203], v[234:235]
	global_store_dwordx4 v[158:159], v[12:15], off
	global_store_dwordx4 v[158:159], v[8:11], off offset:64
	global_store_dwordx4 v[158:159], v[4:7], off offset:512
	global_store_dwordx4 v[158:159], v[0:3], off offset:576
	s_and_b64 vcc, exec, s[38:39]
	s_cbranch_vccz .LBB0_35
; #define G_WAIT_V(n) asm volatile("s_waitcnt vmcnt(" #n ")" ::: "memory")
; #define G_BAR __builtin_amdgcn_s_barrier()
; template <class Epi>
; __device__ __forceinline__ void gemm_phase(LAS unsigned char* lds, const u16* gA, const u16* gBt, int M, int N, int K, const Epi& E) {
;     ...
;   G_WAIT_V(0);
;   if (wr == 0) G_BAR;
;   G_BAR;
	s_waitcnt vmcnt(0)
	s_cmpk_gt_u32 s52, 0xff
	s_cbranch_scc1 .LBB0_46
	s_barrier

; #define G_STAGE(bufoff, gbase, voff) do { _Pragma("unroll") for (int _i = 0; _i < 2; ++_i) \
;     __builtin_amdgcn_global_load_lds((const unsigned*)((const char*)(gbase) + (voff)[_i]), (LAS unsigned*)(lds + (bufoff) + ldsw + _i * 8192), 16, 0, 0); } while (0)
; #define G_LDA(dst, b, h) do { _Pragma("unroll") for (int m = 0; m < 4; ++m) _Pragma("unroll") for (int k = 0; k < 2; ++k) dst[m][k] = *(const LAS bf16x8*)(lds + G_SA(b, h) + aoff + m * 2048 + k * 1024); } while (0)
; #define G_LDB(dst, b, h) do { _Pragma("unroll") for (int n = 0; n < 2; ++n) _Pragma("unroll") for (int k = 0; k < 2; ++k) dst[n][k] = *(const LAS bf16x8*)(lds + G_SB(b, h) + boff + n * 2048 + k * 1024); } while (0)
; #define G_WAIT_V(n) asm volatile("s_waitcnt vmcnt(" #n ")" ::: "memory")
; #define G_WAIT_L(n) asm volatile("s_waitcnt lgkmcnt(" #n ")" ::: "memory")
; #define G_BAR __builtin_amdgcn_s_barrier()
; template <class Epi>
; __device__ __forceinline__ void gemm_phase(LAS unsigned char* lds, const u16* gA, const u16* gBt, int M, int N, int K, const Epi& E) {
;     ...
;     for (int t = 0; t < nt; t += 2) {
;       const bool last = (t == nt - 2);
;       const char* a1 = cA + (size_t)(t + 1) * kstep;
;       const char* a2 = last ? nA : cA + (size_t)(t + 2) * kstep; const char* b2 = last ? nB : cB + (size_t)(t + 2) * kstep;
;       const char* a3 = a2 + kstep; const char* b3 = b2 + kstep;
;       G_LDB(B0, 0, 0); G_SCHED; G_LDA(At, 0, 0); G_STAGE(G_SA(1, 1), a1 + hstep, voffA);
;       G_WAIT_L(8); G_BAR; G_WAIT_L(0); G_MMA(0, 0, At, B0); G_BAR; G_SCHED;
;       G_LDB(B1, 0, 1); G_STAGE(G_SB(0, 0), b2, voffB);
;       G_BAR; G_WAIT_L(0); G_MMA(0, 1, At, B1); G_BAR;
;       G_LDA(At, 0, 1); G_STAGE(G_SA(0, 0), a2, voffA);
;       G_BAR; G_WAIT_L(0); G_MMA(1, 0, At, B0); G_BAR; G_SCHED;
;       G_STAGE(G_SB(0, 1), b2 + hstep, voffB);
;       G_WAIT_V(6); G_BAR; G_MMA(1, 1, At, B1); G_BAR;
;       G_LDB(B0, 1, 0); G_SCHED; G_LDA(At, 1, 0); G_STAGE(G_SA(0, 1), a2 + hstep, voffA);
;       G_WAIT_L(8); G_BAR; G_WAIT_L(0); G_MMA(0, 0, At, B0); G_BAR; G_SCHED;
;       G_LDB(B1, 1, 1); G_STAGE(G_SB(1, 0), b3, voffB);
;       G_BAR; G_WAIT_L(0); G_MMA(0, 1, At, B1); G_BAR;
;       G_LDA(At, 1, 1); G_STAGE(G_SA(1, 0), a3, voffA);
;       G_BAR; G_WAIT_L(0); G_MMA(1, 0, At, B0); G_BAR; G_SCHED;
;       G_STAGE(G_SB(1, 1), b3 + hstep, voffB);
;       G_WAIT_V(6); G_BAR; G_MMA(1, 1, At, B1); G_BAR;
.LBB0_56:
	s_add_u32 s20, s50, 0xfff80080
	s_addc_u32 s22, s51, -1
	s_add_i32 s24, 0, 0x10000
	v_add_u32_e32 v144, s24, v147
	ds_read_b128 v[140:143], v144
	ds_read_b128 v[150:153], v144 offset:1024
	ds_read_b128 v[154:157], v144 offset:2048
	ds_read_b128 v[158:161], v144 offset:3072
	s_cmp_eq_u32 s45, 28
	s_cselect_b32 s55, s26, s22
	s_cselect_b32 s54, s27, s20
	s_cselect_b32 s53, s30, s41
	s_cselect_b32 s52, s31, s33
	v_lshl_add_u64 v[144:145], s[50:51], 0, v[136:137]
	s_add_i32 m0, s3, 0xc000
	ds_read_b128 v[162:165], v149
	ds_read_b128 v[190:193], v149 offset:1024
	ds_read_b128 v[194:197], v149 offset:2048
	ds_read_b128 v[198:201], v149 offset:3072
	ds_read_b128 v[202:205], v149 offset:4096
	ds_read_b128 v[206:209], v149 offset:5120
	ds_read_b128 v[210:213], v149 offset:6144
	ds_read_b128 v[214:217], v149 offset:7168
	global_load_lds_dwordx4 v[144:145], off
	v_lshl_add_u64 v[144:145], s[50:51], 0, v[138:139]
	s_add_i32 m0, s3, 0xe000
	s_nop 0
	global_load_lds_dwordx4 v[144:145], off
	s_waitcnt lgkmcnt(8)
	s_barrier
	s_waitcnt lgkmcnt(0)
	s_setprio 1
	s_waitcnt lgkmcnt(0)
	v_mfma_f32_16x16x32_bf16 v[124:127], v[140:143], v[162:165], v[124:127]
	v_mfma_f32_16x16x32_bf16 v[116:119], v[154:157], v[162:165], v[116:119]
	v_mfma_f32_16x16x32_bf16 v[108:111], v[140:143], v[194:197], v[108:111]
	v_mfma_f32_16x16x32_bf16 v[100:103], v[154:157], v[194:197], v[100:103]
	v_mfma_f32_16x16x32_bf16 v[92:95], v[140:143], v[202:205], v[92:95]
	v_mfma_f32_16x16x32_bf16 v[84:87], v[154:157], v[202:205], v[84:87]
	v_mfma_f32_16x16x32_bf16 v[76:79], v[140:143], v[210:213], v[76:79]
	v_mfma_f32_16x16x32_bf16 v[68:71], v[154:157], v[210:213], v[68:71]
	v_mfma_f32_16x16x32_bf16 v[124:127], v[150:153], v[190:193], v[124:127]
	v_mfma_f32_16x16x32_bf16 v[116:119], v[158:161], v[190:193], v[116:119]
	v_mfma_f32_16x16x32_bf16 v[108:111], v[150:153], v[198:201], v[108:111]
	v_mfma_f32_16x16x32_bf16 v[100:103], v[158:161], v[198:201], v[100:103]
	v_mfma_f32_16x16x32_bf16 v[92:95], v[150:153], v[206:209], v[92:95]
	v_mfma_f32_16x16x32_bf16 v[84:87], v[158:161], v[206:209], v[84:87]
	v_mfma_f32_16x16x32_bf16 v[76:79], v[150:153], v[214:217], v[76:79]
	v_mfma_f32_16x16x32_bf16 v[68:71], v[158:161], v[214:217], v[68:71]
	s_setprio 0
	s_add_i32 s20, 0, 0x14000
	v_add_u32_e32 v144, s20, v147
	s_add_i32 s22, s24, s64
	s_barrier
	ds_read_b128 v[218:221], v144
	ds_read_b128 v[222:225], v144 offset:1024
	ds_read_b128 v[226:229], v144 offset:2048
	ds_read_b128 v[230:233], v144 offset:3072
	v_lshl_add_u64 v[144:145], s[52:53], 0, v[128:129]
	s_mov_b32 m0, s22
	v_lshl_add_u64 v[166:167], s[52:53], 0, v[134:135]
	global_load_lds_dwordx4 v[144:145], off
	s_add_i32 m0, s22, 0x2000
	s_nop 0
	global_load_lds_dwordx4 v[166:167], off
	s_barrier
	s_waitcnt lgkmcnt(0)
	s_setprio 1
	s_waitcnt lgkmcnt(0)
	v_mfma_f32_16x16x32_bf16 v[120:123], v[218:221], v[162:165], v[120:123]
	v_mfma_f32_16x16x32_bf16 v[112:115], v[226:229], v[162:165], v[112:115]
	v_mfma_f32_16x16x32_bf16 v[104:107], v[218:221], v[194:197], v[104:107]
	v_mfma_f32_16x16x32_bf16 v[96:99], v[226:229], v[194:197], v[96:99]
	v_mfma_f32_16x16x32_bf16 v[88:91], v[218:221], v[202:205], v[88:91]
	v_mfma_f32_16x16x32_bf16 v[80:83], v[226:229], v[202:205], v[80:83]
	v_mfma_f32_16x16x32_bf16 v[72:75], v[218:221], v[210:213], v[72:75]
	v_mfma_f32_16x16x32_bf16 v[64:67], v[226:229], v[210:213], v[64:67]
	v_mfma_f32_16x16x32_bf16 v[120:123], v[222:225], v[190:193], v[120:123]
	v_mfma_f32_16x16x32_bf16 v[112:115], v[230:233], v[190:193], v[112:115]
	v_mfma_f32_16x16x32_bf16 v[104:107], v[222:225], v[198:201], v[104:107]
	v_mfma_f32_16x16x32_bf16 v[96:99], v[230:233], v[198:201], v[96:99]
	v_mfma_f32_16x16x32_bf16 v[88:91], v[222:225], v[206:209], v[88:91]
	v_mfma_f32_16x16x32_bf16 v[80:83], v[230:233], v[206:209], v[80:83]
	v_mfma_f32_16x16x32_bf16 v[72:75], v[222:225], v[214:217], v[72:75]
	v_mfma_f32_16x16x32_bf16 v[64:67], v[230:233], v[214:217], v[64:67]
	s_setprio 0
	s_mov_b32 m0, s3
	v_lshl_add_u64 v[234:235], s[54:55], 0, v[128:129]
	s_barrier
	ds_read_b128 v[162:165], v149 offset:16384
	ds_read_b128 v[190:193], v149 offset:17408
	ds_read_b128 v[194:197], v149 offset:18432
	ds_read_b128 v[198:201], v149 offset:19456
	ds_read_b128 v[202:205], v149 offset:20480
	ds_read_b128 v[206:209], v149 offset:21504
	ds_read_b128 v[210:213], v149 offset:22528
	ds_read_b128 v[214:217], v149 offset:23552
	global_load_lds_dwordx4 v[234:235], off
	v_lshl_add_u64 v[236:237], s[54:55], 0, v[134:135]
	s_mov_b32 m0, s67
	s_nop 0
	global_load_lds_dwordx4 v[236:237], off
	s_barrier
	s_waitcnt lgkmcnt(0)
	s_setprio 1
	s_waitcnt lgkmcnt(0)
	v_mfma_f32_16x16x32_bf16 v[60:63], v[140:143], v[162:165], v[60:63]
	v_mfma_f32_16x16x32_bf16 v[52:55], v[154:157], v[162:165], v[52:55]
	v_mfma_f32_16x16x32_bf16 v[44:47], v[140:143], v[194:197], v[44:47]
	v_mfma_f32_16x16x32_bf16 v[36:39], v[154:157], v[194:197], v[36:39]
	v_mfma_f32_16x16x32_bf16 v[28:31], v[140:143], v[202:205], v[28:31]
	v_mfma_f32_16x16x32_bf16 v[20:23], v[154:157], v[202:205], v[20:23]
	v_mfma_f32_16x16x32_bf16 v[12:15], v[140:143], v[210:213], v[12:15]
	v_mfma_f32_16x16x32_bf16 v[4:7], v[154:157], v[210:213], v[4:7]
	v_mfma_f32_16x16x32_bf16 v[60:63], v[150:153], v[190:193], v[60:63]
	v_mfma_f32_16x16x32_bf16 v[52:55], v[158:161], v[190:193], v[52:55]
	v_mfma_f32_16x16x32_bf16 v[44:47], v[150:153], v[198:201], v[44:47]
	v_mfma_f32_16x16x32_bf16 v[36:39], v[158:161], v[198:201], v[36:39]
	v_mfma_f32_16x16x32_bf16 v[28:31], v[150:153], v[206:209], v[28:31]
	v_mfma_f32_16x16x32_bf16 v[20:23], v[158:161], v[206:209], v[20:23]
	v_mfma_f32_16x16x32_bf16 v[12:15], v[150:153], v[214:217], v[12:15]
	v_mfma_f32_16x16x32_bf16 v[4:7], v[158:161], v[214:217], v[4:7]
	s_setprio 0
	s_add_u32 s24, s52, 0x80000
	s_addc_u32 s25, s53, 0
	s_add_i32 s20, s20, s64
	v_lshl_add_u64 v[140:141], s[24:25], 0, v[128:129]
	s_mov_b32 m0, s20
	s_barrier
; #define G_STAGE(bufoff, gbase, voff) do { _Pragma("unroll") for (int _i = 0; _i < 2; ++_i) \
;     __builtin_amdgcn_global_load_lds((const unsigned*)((const char*)(gbase) + (voff)[_i]), (LAS unsigned*)(lds + (bufoff) + ldsw + _i * 8192), 16, 0, 0); } while (0)
; #define G_LDA(dst, b, h) do { _Pragma("unroll") for (int m = 0; m < 4; ++m) _Pragma("unroll") for (int k = 0; k < 2; ++k) dst[m][k] = *(const LAS bf16x8*)(lds + G_SA(b, h) + aoff + m * 2048 + k * 1024); } while (0)
; #define G_LDB(dst, b, h) do { _Pragma("unroll") for (int n = 0; n < 2; ++n) _Pragma("unroll") for (int k = 0; k < 2; ++k) dst[n][k] = *(const LAS bf16x8*)(lds + G_SB(b, h) + boff + n * 2048 + k * 1024); } while (0)
; #define G_MMA(ai, bj, At, Bt) do { __builtin_amdgcn_s_setprio(1); _Pragma("unroll") for (int m = 0; m < 4; ++m) _Pragma("unroll") for (int n = 0; n < 2; ++n) _Pragma("unroll") for (int k = 0; k < 2; ++k) \
;     acc[ai][bj][m][n] = __builtin_amdgcn_mfma_f32_16x16x32_bf16(Bt[n][k], At[m][k], acc[ai][bj][m][n], 0, 0, 0); __builtin_amdgcn_s_setprio(0); } while (0)
; #define G_WAIT_V(n) asm volatile("s_waitcnt vmcnt(" #n ")" ::: "memory")
; #define G_WAIT_L(n) asm volatile("s_waitcnt lgkmcnt(" #n ")" ::: "memory")
; template <class Epi>
; __device__ __forceinline__ void gemm_phase(LAS unsigned char* lds, const u16* gA, const u16* gBt, int M, int N, int K, const Epi& E) {
;     ...
;       G_LDB(B0, 0, 0); G_SCHED; G_LDA(At, 0, 0); G_STAGE(G_SA(1, 1), a1 + hstep, voffA);
;       G_WAIT_L(8); G_BAR; G_WAIT_L(0); G_MMA(0, 0, At, B0); G_BAR; G_SCHED;
;       G_LDB(B1, 0, 1); G_STAGE(G_SB(0, 0), b2, voffB);
;       G_BAR; G_WAIT_L(0); G_MMA(0, 1, At, B1); G_BAR;
;       G_LDA(At, 0, 1); G_STAGE(G_SA(0, 0), a2, voffA);
;       G_BAR; G_WAIT_L(0); G_MMA(1, 0, At, B0); G_BAR; G_SCHED;
;       G_STAGE(G_SB(0, 1), b2 + hstep, voffB);
;       G_WAIT_V(6); G_BAR; G_MMA(1, 1, At, B1); G_BAR;
;       G_LDB(B0, 1, 0); G_SCHED; G_LDA(At, 1, 0); G_STAGE(G_SA(0, 1), a2 + hstep, voffA);
;       G_WAIT_L(8); G_BAR; G_WAIT_L(0); G_MMA(0, 0, At, B0); G_BAR; G_SCHED;
;       G_LDB(B1, 1, 1); G_STAGE(G_SB(1, 0), b3, voffB);
;       G_BAR; G_WAIT_L(0); G_MMA(0, 1, At, B1); G_BAR;
;       G_LDA(At, 1, 1); G_STAGE(G_SA(1, 0), a3, voffA);
;       G_BAR; G_WAIT_L(0); G_MMA(1, 0, At, B0); G_BAR; G_SCHED;
;       G_STAGE(G_SB(1, 1), b3 + hstep, voffB);
;       G_WAIT_V(6); G_BAR; G_MMA(1, 1, At, B1); G_BAR;
	s_nop 0
	global_load_lds_dwordx4 v[140:141], off
	v_lshl_add_u64 v[140:141], s[24:25], 0, v[134:135]
	s_add_i32 m0, s20, 0x2000
	s_nop 0
	global_load_lds_dwordx4 v[140:141], off
	s_waitcnt vmcnt(6)
	s_barrier
	s_setprio 1
	v_mfma_f32_16x16x32_bf16 v[56:59], v[218:221], v[162:165], v[56:59]
	v_mfma_f32_16x16x32_bf16 v[48:51], v[226:229], v[162:165], v[48:51]
	v_mfma_f32_16x16x32_bf16 v[40:43], v[218:221], v[194:197], v[40:43]
	v_mfma_f32_16x16x32_bf16 v[32:35], v[226:229], v[194:197], v[32:35]
	v_mfma_f32_16x16x32_bf16 v[24:27], v[218:221], v[202:205], v[24:27]
	v_mfma_f32_16x16x32_bf16 v[16:19], v[226:229], v[202:205], v[16:19]
	v_mfma_f32_16x16x32_bf16 v[8:11], v[218:221], v[210:213], v[8:11]
	v_mfma_f32_16x16x32_bf16 v[0:3], v[226:229], v[210:213], v[0:3]
	v_mfma_f32_16x16x32_bf16 v[56:59], v[222:225], v[190:193], v[56:59]
	v_mfma_f32_16x16x32_bf16 v[48:51], v[230:233], v[190:193], v[48:51]
	v_mfma_f32_16x16x32_bf16 v[40:43], v[222:225], v[198:201], v[40:43]
	v_mfma_f32_16x16x32_bf16 v[32:35], v[230:233], v[198:201], v[32:35]
	v_mfma_f32_16x16x32_bf16 v[24:27], v[222:225], v[206:209], v[24:27]
	v_mfma_f32_16x16x32_bf16 v[16:19], v[230:233], v[206:209], v[16:19]
	v_mfma_f32_16x16x32_bf16 v[8:11], v[222:225], v[214:217], v[8:11]
	v_mfma_f32_16x16x32_bf16 v[0:3], v[230:233], v[214:217], v[0:3]
	s_setprio 0
	s_add_i32 s20, 0, 0x18000
	v_add_u32_e32 v158, s20, v147
	s_barrier
	ds_read_b128 v[140:143], v158
	ds_read_b128 v[150:153], v158 offset:1024
	ds_read_b128 v[154:157], v158 offset:2048
	ds_read_b128 v[158:161], v158 offset:3072
	s_add_u32 s24, s54, 0x80000
	s_addc_u32 s25, s55, 0
	s_mov_b32 m0, s68
	v_lshl_add_u64 v[218:219], s[24:25], 0, v[128:129]
	ds_read_b128 v[162:165], v149 offset:32768
	ds_read_b128 v[190:193], v149 offset:33792
	ds_read_b128 v[194:197], v149 offset:34816
	ds_read_b128 v[198:201], v149 offset:35840
	ds_read_b128 v[202:205], v149 offset:36864
	ds_read_b128 v[206:209], v149 offset:37888
	ds_read_b128 v[210:213], v149 offset:38912
	ds_read_b128 v[214:217], v149 offset:39936
	global_load_lds_dwordx4 v[218:219], off
	v_lshl_add_u64 v[218:219], s[24:25], 0, v[134:135]
	s_mov_b32 m0, s69
	s_nop 0
	global_load_lds_dwordx4 v[218:219], off
	s_waitcnt lgkmcnt(8)
	s_barrier
	s_waitcnt lgkmcnt(0)
	s_setprio 1
	s_waitcnt lgkmcnt(0)
	v_mfma_f32_16x16x32_bf16 v[124:127], v[140:143], v[162:165], v[124:127]
	v_mfma_f32_16x16x32_bf16 v[116:119], v[154:157], v[162:165], v[116:119]
	v_mfma_f32_16x16x32_bf16 v[108:111], v[140:143], v[194:197], v[108:111]
	v_mfma_f32_16x16x32_bf16 v[100:103], v[154:157], v[194:197], v[100:103]
	v_mfma_f32_16x16x32_bf16 v[92:95], v[140:143], v[202:205], v[92:95]
	v_mfma_f32_16x16x32_bf16 v[84:87], v[154:157], v[202:205], v[84:87]
	v_mfma_f32_16x16x32_bf16 v[76:79], v[140:143], v[210:213], v[76:79]
	v_mfma_f32_16x16x32_bf16 v[68:71], v[154:157], v[210:213], v[68:71]
	v_mfma_f32_16x16x32_bf16 v[124:127], v[150:153], v[190:193], v[124:127]
	v_mfma_f32_16x16x32_bf16 v[116:119], v[158:161], v[190:193], v[116:119]
	v_mfma_f32_16x16x32_bf16 v[108:111], v[150:153], v[198:201], v[108:111]
	v_mfma_f32_16x16x32_bf16 v[100:103], v[158:161], v[198:201], v[100:103]
	v_mfma_f32_16x16x32_bf16 v[92:95], v[150:153], v[206:209], v[92:95]
	v_mfma_f32_16x16x32_bf16 v[84:87], v[158:161], v[206:209], v[84:87]
	v_mfma_f32_16x16x32_bf16 v[76:79], v[150:153], v[214:217], v[76:79]
	v_mfma_f32_16x16x32_bf16 v[68:71], v[158:161], v[214:217], v[68:71]
	s_setprio 0
	s_add_i32 s22, 0, 0x1c000
	s_add_i32 s20, s20, s64
	v_add_u32_e32 v230, s22, v147
	v_lshl_add_u64 v[144:145], v[144:145], 0, s[34:35]
	s_mov_b32 m0, s20
	s_barrier
	ds_read_b128 v[218:221], v230
	ds_read_b128 v[222:225], v230 offset:1024
	ds_read_b128 v[226:229], v230 offset:2048
	ds_read_b128 v[230:233], v230 offset:3072
	global_load_lds_dwordx4 v[144:145], off
	v_lshl_add_u64 v[144:145], v[166:167], 0, s[34:35]
	s_add_i32 m0, s20, 0x2000
	s_nop 0
	global_load_lds_dwordx4 v[144:145], off
	s_barrier
	s_waitcnt lgkmcnt(0)
	s_setprio 1
	s_waitcnt lgkmcnt(0)
	v_mfma_f32_16x16x32_bf16 v[120:123], v[218:221], v[162:165], v[120:123]
	v_mfma_f32_16x16x32_bf16 v[112:115], v[226:229], v[162:165], v[112:115]
	v_mfma_f32_16x16x32_bf16 v[104:107], v[218:221], v[194:197], v[104:107]
	v_mfma_f32_16x16x32_bf16 v[96:99], v[226:229], v[194:197], v[96:99]
	v_mfma_f32_16x16x32_bf16 v[88:91], v[218:221], v[202:205], v[88:91]
	v_mfma_f32_16x16x32_bf16 v[80:83], v[226:229], v[202:205], v[80:83]
	v_mfma_f32_16x16x32_bf16 v[72:75], v[218:221], v[210:213], v[72:75]
	v_mfma_f32_16x16x32_bf16 v[64:67], v[226:229], v[210:213], v[64:67]
	v_mfma_f32_16x16x32_bf16 v[120:123], v[222:225], v[190:193], v[120:123]
	v_mfma_f32_16x16x32_bf16 v[112:115], v[230:233], v[190:193], v[112:115]
	v_mfma_f32_16x16x32_bf16 v[104:107], v[222:225], v[198:201], v[104:107]
	v_mfma_f32_16x16x32_bf16 v[96:99], v[230:233], v[198:201], v[96:99]
	v_mfma_f32_16x16x32_bf16 v[88:91], v[222:225], v[206:209], v[88:91]
	v_mfma_f32_16x16x32_bf16 v[80:83], v[230:233], v[206:209], v[80:83]
	v_mfma_f32_16x16x32_bf16 v[72:75], v[222:225], v[214:217], v[72:75]
	v_mfma_f32_16x16x32_bf16 v[64:67], v[230:233], v[214:217], v[64:67]
	s_setprio 0
	s_mov_b32 m0, s71
	v_lshl_add_u64 v[144:145], v[234:235], 0, s[34:35]
	s_barrier
	ds_read_b128 v[162:165], v149 offset:49152
	ds_read_b128 v[190:193], v149 offset:50176
	ds_read_b128 v[194:197], v149 offset:51200
	ds_read_b128 v[198:201], v149 offset:52224
	ds_read_b128 v[202:205], v149 offset:53248
	ds_read_b128 v[206:209], v149 offset:54272
	ds_read_b128 v[210:213], v149 offset:55296
	ds_read_b128 v[214:217], v149 offset:56320
	global_load_lds_dwordx4 v[144:145], off
	v_lshl_add_u64 v[144:145], v[236:237], 0, s[34:35]
	s_mov_b32 m0, s72
	s_nop 0
	global_load_lds_dwordx4 v[144:145], off
	s_barrier
; __device__ __forceinline__ float siluf_(float x) { return x / (1.f + __expf(-x)); }
; __device__ __forceinline__ unsigned pk_bf16(float lo, float hi) { return (unsigned)f2bf(lo) | ((unsigned)f2bf(hi) << 16); }
; #define G_STAGE(bufoff, gbase, voff) do { _Pragma("unroll") for (int _i = 0; _i < 2; ++_i) \
;     __builtin_amdgcn_global_load_lds((const unsigned*)((const char*)(gbase) + (voff)[_i]), (LAS unsigned*)(lds + (bufoff) + ldsw + _i * 8192), 16, 0, 0); } while (0)
; #define G_LDA(dst, b, h) do { _Pragma("unroll") for (int m = 0; m < 4; ++m) _Pragma("unroll") for (int k = 0; k < 2; ++k) dst[m][k] = *(const LAS bf16x8*)(lds + G_SA(b, h) + aoff + m * 2048 + k * 1024); } while (0)
; #define G_WAIT_V(n) asm volatile("s_waitcnt vmcnt(" #n ")" ::: "memory")
; #define G_WAIT_L(n) asm volatile("s_waitcnt lgkmcnt(" #n ")" ::: "memory")
;   __device__ __forceinline__ void operator()(const f32x4 (&acc)[2][2][4][2], const Unit& u, int wr, int wc, int fr, int fq) const {
;     const int row0 = u.pm * BM + wr * 64 + fr, col0 = u.pn * HALF + wc * 32 + 4 * fq;
; #pragma unroll
;     for (int ai = 0; ai < 2; ++ai)
; #pragma unroll
;       for (int m = 0; m < 4; ++m) {
;         u16* rowp = O + (size_t)(row0 + ai * HALF + m * 16) * FFN + col0;
; #pragma unroll
;         for (int n = 0; n < 2; ++n) {
;           f32x4 g = acc[ai][0][m][n], up = acc[ai][1][m][n];
;           uint2 w;
;           w.x = pk_bf16(siluf_(g[0]) * up[0], siluf_(g[1]) * up[1]);
;           w.y = pk_bf16(siluf_(g[2]) * up[2], siluf_(g[3]) * up[3]);
;           *reinterpret_cast<uint2*>(rowp + n * 16) = w;
;         }
;       }
;   }
; template <class Epi>
; __device__ __forceinline__ void gemm_phase(LAS unsigned char* lds, const u16* gA, const u16* gBt, int M, int N, int K, const Epi& E) {
;     ...
;       G_WAIT_V(6); G_BAR; G_MMA(1, 1, At, B1); G_BAR;
;       G_LDB(B0, 1, 0); G_SCHED; G_LDA(At, 1, 0); G_STAGE(G_SA(0, 1), a2 + hstep, voffA);
;       G_WAIT_L(8); G_BAR; G_WAIT_L(0); G_MMA(0, 0, At, B0); G_BAR; G_SCHED;
;       G_LDB(B1, 1, 1); G_STAGE(G_SB(1, 0), b3, voffB);
;       G_BAR; G_WAIT_L(0); G_MMA(0, 1, At, B1); G_BAR;
;       G_LDA(At, 1, 1); G_STAGE(G_SA(1, 0), a3, voffA);
;       G_BAR; G_WAIT_L(0); G_MMA(1, 0, At, B0); G_BAR; G_SCHED;
;       G_STAGE(G_SB(1, 1), b3 + hstep, voffB);
;       G_WAIT_V(6); G_BAR; G_MMA(1, 1, At, B1); G_BAR;
;     }
;     E(acc, cur, wr, wc, fr, fq);
	s_waitcnt lgkmcnt(0)
	s_setprio 1
	s_waitcnt lgkmcnt(0)
	v_mfma_f32_16x16x32_bf16 v[60:63], v[140:143], v[162:165], v[60:63]
	v_mfma_f32_16x16x32_bf16 v[52:55], v[154:157], v[162:165], v[52:55]
	v_mfma_f32_16x16x32_bf16 v[44:47], v[140:143], v[194:197], v[44:47]
	v_mfma_f32_16x16x32_bf16 v[36:39], v[154:157], v[194:197], v[36:39]
	v_mfma_f32_16x16x32_bf16 v[28:31], v[140:143], v[202:205], v[28:31]
	v_mfma_f32_16x16x32_bf16 v[20:23], v[154:157], v[202:205], v[20:23]
	v_mfma_f32_16x16x32_bf16 v[12:15], v[140:143], v[210:213], v[12:15]
	v_mfma_f32_16x16x32_bf16 v[4:7], v[154:157], v[210:213], v[4:7]
	v_mfma_f32_16x16x32_bf16 v[60:63], v[150:153], v[190:193], v[60:63]
	v_mfma_f32_16x16x32_bf16 v[52:55], v[158:161], v[190:193], v[52:55]
	v_mfma_f32_16x16x32_bf16 v[44:47], v[150:153], v[198:201], v[44:47]
	v_mfma_f32_16x16x32_bf16 v[36:39], v[158:161], v[198:201], v[36:39]
	v_mfma_f32_16x16x32_bf16 v[28:31], v[150:153], v[206:209], v[28:31]
	v_mfma_f32_16x16x32_bf16 v[20:23], v[158:161], v[206:209], v[20:23]
	v_mfma_f32_16x16x32_bf16 v[12:15], v[150:153], v[214:217], v[12:15]
	v_mfma_f32_16x16x32_bf16 v[4:7], v[158:161], v[214:217], v[4:7]
	s_setprio 0
	s_add_u32 s24, s52, 0x80080
	s_addc_u32 s25, s53, 0
	s_add_i32 s20, s22, s64
	v_lshl_add_u64 v[140:141], s[24:25], 0, v[128:129]
	s_mov_b32 m0, s20
	s_barrier
	s_nop 0
	global_load_lds_dwordx4 v[140:141], off
	v_lshl_add_u64 v[140:141], s[24:25], 0, v[134:135]
	s_add_i32 m0, s20, 0x2000
	s_nop 0
	global_load_lds_dwordx4 v[140:141], off
	s_waitcnt vmcnt(6)
	s_barrier
	s_setprio 1
	v_mfma_f32_16x16x32_bf16 v[56:59], v[218:221], v[162:165], v[56:59]
	v_mfma_f32_16x16x32_bf16 v[48:51], v[226:229], v[162:165], v[48:51]
	v_mfma_f32_16x16x32_bf16 v[40:43], v[218:221], v[194:197], v[40:43]
	v_mfma_f32_16x16x32_bf16 v[32:35], v[226:229], v[194:197], v[32:35]
	v_mfma_f32_16x16x32_bf16 v[24:27], v[218:221], v[202:205], v[24:27]
	v_mfma_f32_16x16x32_bf16 v[16:19], v[226:229], v[202:205], v[16:19]
	v_mfma_f32_16x16x32_bf16 v[8:11], v[218:221], v[210:213], v[8:11]
	v_mfma_f32_16x16x32_bf16 v[0:3], v[226:229], v[210:213], v[0:3]
	v_mfma_f32_16x16x32_bf16 v[56:59], v[222:225], v[190:193], v[56:59]
	v_mfma_f32_16x16x32_bf16 v[48:51], v[230:233], v[190:193], v[48:51]
	v_mfma_f32_16x16x32_bf16 v[40:43], v[222:225], v[198:201], v[40:43]
	v_mfma_f32_16x16x32_bf16 v[32:35], v[230:233], v[198:201], v[32:35]
	v_mfma_f32_16x16x32_bf16 v[24:27], v[222:225], v[206:209], v[24:27]
	v_mfma_f32_16x16x32_bf16 v[16:19], v[230:233], v[206:209], v[16:19]
	v_mfma_f32_16x16x32_bf16 v[8:11], v[222:225], v[214:217], v[8:11]
	v_mfma_f32_16x16x32_bf16 v[0:3], v[230:233], v[214:217], v[0:3]
	s_setprio 0
	s_add_i32 s45, s45, 2
	s_add_u32 s50, s50, 0x100
	s_addc_u32 s51, s51, 0
	s_add_u32 s33, s33, 0x100
	s_addc_u32 s41, s41, 0
	s_cmp_gt_u32 s45, 29
	s_barrier
	s_cbranch_scc0 .LBB0_56
	v_mul_f32_e32 v151, 0xbfb8aa3b, v124
	v_exp_f32_e32 v152, v151
	v_mul_f32_e32 v151, 0xbfb8aa3b, v125
	v_exp_f32_e32 v154, v151
	v_mul_f32_e32 v151, 0xbfb8aa3b, v126
	v_exp_f32_e32 v153, v151
	v_mul_f32_e32 v151, 0xbfb8aa3b, v127
	v_lshl_or_b32 v142, s23, 7, v148
	v_bfe_u32 v252, v168, 4, 1
	v_mul_u32_u24_e32 v252, 12, v252
	v_add_u32_e32 v142, v142, v252
	v_exp_f32_e32 v155, v151
	v_pk_add_f32 v[152:153], v[152:153], 1.0 op_sel_hi:[1,0]
	v_lshl_add_u32 v150, s2, 8, v146
	v_pk_add_f32 v[154:155], v[154:155], 1.0 op_sel_hi:[1,0]
	v_ashrrev_i32_e32 v143, 31, v142
	v_mov_b64_e32 v[140:141], s[94:95]
	v_rcp_f32_e32 v151, v153
	s_nop 0
	v_mul_f32_e32 v153, v126, v151
	s_movk_i32 s2, 0x2c00
	v_mad_i64_i32 v[144:145], s[22:23], v150, s2, v[140:141]
	v_mov_b32_e32 v156, v120
	v_mov_b32_e32 v157, v122
	v_rcp_f32_e32 v126, v152
	s_nop 0
	v_mul_f32_e32 v152, v124, v126
	v_pk_mul_f32 v[152:153], v[152:153], v[156:157]
	v_lshlrev_b64 v[142:143], 1, v[142:143]
	v_rcp_f32_e32 v120, v155
	s_nop 0
	v_mul_f32_e32 v127, v127, v120
	v_lshl_add_u64 v[144:145], v[144:145], 0, v[142:143]
	s_mov_b64 s[52:53], s[48:49]
	s_mov_b64 s[50:51], s[46:47]
	v_rcp_f32_e32 v120, v154
	s_nop 0
	v_mul_f32_e32 v126, v125, v120
	v_mov_b32_e32 v122, v121
	v_pk_mul_f32 v[120:121], v[126:127], v[122:123]
	s_nop 0
	v_cvt_pk_bf16_f32 v245, v153, v121
	v_cvt_pk_bf16_f32 v244, v152, v120
	v_mul_f32_e32 v121, 0xbfb8aa3b, v117
	v_mul_f32_e32 v120, 0xbfb8aa3b, v116
	v_exp_f32_e32 v122, v121
	v_mul_f32_e32 v121, 0xbfb8aa3b, v118
	v_exp_f32_e32 v120, v120
	v_exp_f32_e32 v121, v121
	v_mul_f32_e32 v123, 0xbfb8aa3b, v119
	v_exp_f32_e32 v123, v123
	v_pk_add_f32 v[120:121], v[120:121], 1.0 op_sel_hi:[1,0]
	s_nop 0
	v_pk_add_f32 v[122:123], v[122:123], 1.0 op_sel_hi:[1,0]
	v_rcp_f32_e32 v124, v121
	s_nop 0
	v_mul_f32_e32 v121, v118, v124
	s_nop 0
	v_mov_b32_e32 v124, v112
	v_mov_b32_e32 v125, v114
	v_rcp_f32_e32 v118, v120
	s_nop 0
	v_mul_f32_e32 v120, v116, v118
	v_pk_mul_f32 v[120:121], v[120:121], v[124:125]
	v_rcp_f32_e32 v112, v123
	s_nop 0
	v_mul_f32_e32 v119, v119, v112
	s_nop 0
	v_rcp_f32_e32 v112, v122
	s_nop 0
	v_mul_f32_e32 v118, v117, v112
	v_mov_b32_e32 v114, v113
	v_pk_mul_f32 v[112:113], v[118:119], v[114:115]
	s_nop 0
	v_cvt_pk_bf16_f32 v246, v120, v112
	v_mul_f32_e32 v115, 0xbfb8aa3b, v109
	v_cvt_pk_bf16_f32 v247, v121, v113
	v_mul_f32_e32 v114, 0xbfb8aa3b, v108
	v_exp_f32_e32 v116, v115
	v_mul_f32_e32 v115, 0xbfb8aa3b, v110
	v_exp_f32_e32 v114, v114
	v_exp_f32_e32 v115, v115
	v_mul_f32_e32 v117, 0xbfb8aa3b, v111
	v_exp_f32_e32 v117, v117
	s_nop 1
	v_permlane16_swap_b32_e32 v244, v246
	v_permlane16_swap_b32_e32 v245, v247
	global_store_dwordx4 v[144:145], v[244:247], off
	v_pk_add_f32 v[114:115], v[114:115], 1.0 op_sel_hi:[1,0]
	v_or_b32_e32 v112, 16, v150
	v_pk_add_f32 v[116:117], v[116:117], 1.0 op_sel_hi:[1,0]
; __device__ __forceinline__ float siluf_(float x) { return x / (1.f + __expf(-x)); }
; __device__ __forceinline__ unsigned pk_bf16(float lo, float hi) { return (unsigned)f2bf(lo) | ((unsigned)f2bf(hi) << 16); }
;   __device__ __forceinline__ void operator()(const f32x4 (&acc)[2][2][4][2], const Unit& u, int wr, int wc, int fr, int fq) const {
;     const int row0 = u.pm * BM + wr * 64 + fr, col0 = u.pn * HALF + wc * 32 + 4 * fq;
; #pragma unroll
;     for (int ai = 0; ai < 2; ++ai)
; #pragma unroll
;       for (int m = 0; m < 4; ++m) {
;         u16* rowp = O + (size_t)(row0 + ai * HALF + m * 16) * FFN + col0;
; #pragma unroll
;         for (int n = 0; n < 2; ++n) {
;           f32x4 g = acc[ai][0][m][n], up = acc[ai][1][m][n];
;           uint2 w;
;           w.x = pk_bf16(siluf_(g[0]) * up[0], siluf_(g[1]) * up[1]);
;           w.y = pk_bf16(siluf_(g[2]) * up[2], siluf_(g[3]) * up[3]);
;           *reinterpret_cast<uint2*>(rowp + n * 16) = w;
;         }
;       }
;   }
	v_mad_i64_i32 v[112:113], s[22:23], v112, s2, v[140:141]
	v_rcp_f32_e32 v118, v115
	s_nop 0
	v_mul_f32_e32 v115, v110, v118
	v_lshl_add_u64 v[112:113], v[112:113], 0, v[142:143]
	v_mov_b32_e32 v118, v104
	v_mov_b32_e32 v119, v106
	v_rcp_f32_e32 v110, v114
	s_nop 0
	v_mul_f32_e32 v114, v108, v110
	v_pk_mul_f32 v[114:115], v[114:115], v[118:119]
	v_rcp_f32_e32 v104, v117
	s_nop 0
	v_mul_f32_e32 v111, v111, v104
	s_nop 0
	v_rcp_f32_e32 v104, v116
	s_nop 0
	v_mul_f32_e32 v110, v109, v104
	v_mov_b32_e32 v106, v105
	v_pk_mul_f32 v[104:105], v[110:111], v[106:107]
	s_nop 0
	v_cvt_pk_bf16_f32 v249, v115, v105
	v_cvt_pk_bf16_f32 v248, v114, v104
	v_mul_f32_e32 v105, 0xbfb8aa3b, v101
	v_mul_f32_e32 v104, 0xbfb8aa3b, v100
	v_exp_f32_e32 v106, v105
	v_mul_f32_e32 v105, 0xbfb8aa3b, v102
	v_exp_f32_e32 v104, v104
	v_exp_f32_e32 v105, v105
	v_mul_f32_e32 v107, 0xbfb8aa3b, v103
	v_exp_f32_e32 v107, v107
	v_pk_add_f32 v[104:105], v[104:105], 1.0 op_sel_hi:[1,0]
	s_nop 0
	v_pk_add_f32 v[106:107], v[106:107], 1.0 op_sel_hi:[1,0]
	v_rcp_f32_e32 v108, v105
	s_nop 0
	v_mul_f32_e32 v105, v102, v108
	s_nop 0
	v_mov_b32_e32 v108, v96
	v_mov_b32_e32 v109, v98
	v_rcp_f32_e32 v102, v104
	s_nop 0
	v_mul_f32_e32 v104, v100, v102
	v_pk_mul_f32 v[104:105], v[104:105], v[108:109]
	v_rcp_f32_e32 v96, v107
	s_nop 0
	v_mul_f32_e32 v103, v103, v96
	s_nop 0
	v_rcp_f32_e32 v96, v106
	s_nop 0
	v_mul_f32_e32 v102, v101, v96
	v_mov_b32_e32 v98, v97
	v_pk_mul_f32 v[96:97], v[102:103], v[98:99]
	s_nop 0
	v_cvt_pk_bf16_f32 v250, v104, v96
	v_mul_f32_e32 v99, 0xbfb8aa3b, v93
	v_cvt_pk_bf16_f32 v251, v105, v97
	v_mul_f32_e32 v98, 0xbfb8aa3b, v92
	v_exp_f32_e32 v100, v99
	v_mul_f32_e32 v99, 0xbfb8aa3b, v94
	v_exp_f32_e32 v98, v98
	v_exp_f32_e32 v99, v99
	v_mul_f32_e32 v101, 0xbfb8aa3b, v95
	v_exp_f32_e32 v101, v101
	s_nop 1
	v_permlane16_swap_b32_e32 v248, v250
	v_permlane16_swap_b32_e32 v249, v251
	global_store_dwordx4 v[112:113], v[248:251], off
	v_pk_add_f32 v[98:99], v[98:99], 1.0 op_sel_hi:[1,0]
	v_or_b32_e32 v96, 32, v150
	v_pk_add_f32 v[100:101], v[100:101], 1.0 op_sel_hi:[1,0]
	v_mad_i64_i32 v[96:97], s[22:23], v96, s2, v[140:141]
	v_rcp_f32_e32 v102, v99
	s_nop 0
	v_mul_f32_e32 v99, v94, v102
	v_lshl_add_u64 v[96:97], v[96:97], 0, v[142:143]
	v_mov_b32_e32 v102, v88
	v_mov_b32_e32 v103, v90
	v_rcp_f32_e32 v94, v98
	s_nop 0
	v_mul_f32_e32 v98, v92, v94
	v_pk_mul_f32 v[98:99], v[98:99], v[102:103]
	v_rcp_f32_e32 v88, v101
	s_nop 0
	v_mul_f32_e32 v95, v95, v88
	s_nop 0
	v_rcp_f32_e32 v88, v100
	s_nop 0
	v_mul_f32_e32 v94, v93, v88
	v_mov_b32_e32 v90, v89
	v_pk_mul_f32 v[88:89], v[94:95], v[90:91]
	s_nop 0
	v_cvt_pk_bf16_f32 v245, v99, v89
	v_cvt_pk_bf16_f32 v244, v98, v88
	v_mul_f32_e32 v89, 0xbfb8aa3b, v85
	v_mul_f32_e32 v88, 0xbfb8aa3b, v84
	v_exp_f32_e32 v90, v89
	v_mul_f32_e32 v89, 0xbfb8aa3b, v86
	v_exp_f32_e32 v88, v88
	v_exp_f32_e32 v89, v89
	v_mul_f32_e32 v91, 0xbfb8aa3b, v87
	v_exp_f32_e32 v91, v91
	v_pk_add_f32 v[88:89], v[88:89], 1.0 op_sel_hi:[1,0]
	s_nop 0
	v_pk_add_f32 v[90:91], v[90:91], 1.0 op_sel_hi:[1,0]
	v_rcp_f32_e32 v92, v89
	s_nop 0
	v_mul_f32_e32 v89, v86, v92
	s_nop 0
	v_mov_b32_e32 v92, v80
	v_mov_b32_e32 v93, v82
	v_rcp_f32_e32 v86, v88
	s_nop 0
	v_mul_f32_e32 v88, v84, v86
	v_pk_mul_f32 v[88:89], v[88:89], v[92:93]
	v_rcp_f32_e32 v80, v91
	s_nop 0
	v_mul_f32_e32 v87, v87, v80
	s_nop 0
	v_rcp_f32_e32 v80, v90
	s_nop 0
	v_mul_f32_e32 v86, v85, v80
	v_mov_b32_e32 v82, v81
	v_pk_mul_f32 v[80:81], v[86:87], v[82:83]
	s_nop 0
	v_cvt_pk_bf16_f32 v246, v88, v80
	v_mul_f32_e32 v83, 0xbfb8aa3b, v77
	v_cvt_pk_bf16_f32 v247, v89, v81
	v_mul_f32_e32 v82, 0xbfb8aa3b, v76
	v_exp_f32_e32 v84, v83
	v_mul_f32_e32 v83, 0xbfb8aa3b, v78
	v_exp_f32_e32 v82, v82
	v_exp_f32_e32 v83, v83
	v_mul_f32_e32 v85, 0xbfb8aa3b, v79
	v_exp_f32_e32 v85, v85
	s_nop 1
	v_permlane16_swap_b32_e32 v244, v246
	v_permlane16_swap_b32_e32 v245, v247
	global_store_dwordx4 v[96:97], v[244:247], off
	v_pk_add_f32 v[82:83], v[82:83], 1.0 op_sel_hi:[1,0]
	v_or_b32_e32 v80, 48, v150
	v_pk_add_f32 v[84:85], v[84:85], 1.0 op_sel_hi:[1,0]
	v_mad_i64_i32 v[80:81], s[22:23], v80, s2, v[140:141]
	v_rcp_f32_e32 v86, v83
	s_nop 0
	v_mul_f32_e32 v83, v78, v86
	v_lshl_add_u64 v[80:81], v[80:81], 0, v[142:143]
	v_mov_b32_e32 v86, v72
	v_mov_b32_e32 v87, v74
	v_rcp_f32_e32 v78, v82
	s_nop 0
	v_mul_f32_e32 v82, v76, v78
	v_pk_mul_f32 v[82:83], v[82:83], v[86:87]
	v_rcp_f32_e32 v72, v85
	s_nop 0
	v_mul_f32_e32 v79, v79, v72
	s_nop 0
	v_rcp_f32_e32 v72, v84
	s_nop 0
	v_mul_f32_e32 v78, v77, v72
	v_mov_b32_e32 v74, v73
	v_pk_mul_f32 v[72:73], v[78:79], v[74:75]
	s_nop 0
	v_cvt_pk_bf16_f32 v249, v83, v73
	v_cvt_pk_bf16_f32 v248, v82, v72
	v_mul_f32_e32 v73, 0xbfb8aa3b, v69
	v_mul_f32_e32 v72, 0xbfb8aa3b, v68
	v_exp_f32_e32 v74, v73
	v_mul_f32_e32 v73, 0xbfb8aa3b, v70
	v_exp_f32_e32 v72, v72
	v_exp_f32_e32 v73, v73
	v_mul_f32_e32 v75, 0xbfb8aa3b, v71
	v_exp_f32_e32 v75, v75
	v_pk_add_f32 v[72:73], v[72:73], 1.0 op_sel_hi:[1,0]
	s_nop 0
	v_pk_add_f32 v[74:75], v[74:75], 1.0 op_sel_hi:[1,0]
	v_rcp_f32_e32 v76, v73
	s_nop 0
	v_mul_f32_e32 v73, v70, v76
	s_nop 0
	v_mov_b32_e32 v76, v64
	v_mov_b32_e32 v77, v66
	v_rcp_f32_e32 v70, v72
	s_nop 0
	v_mul_f32_e32 v72, v68, v70
	v_pk_mul_f32 v[72:73], v[72:73], v[76:77]
	v_rcp_f32_e32 v64, v75
	s_nop 0
	v_mul_f32_e32 v71, v71, v64
	s_nop 0
	v_rcp_f32_e32 v64, v74
	s_nop 0
	v_mul_f32_e32 v70, v69, v64
	v_mov_b32_e32 v66, v65
	v_pk_mul_f32 v[64:65], v[70:71], v[66:67]
	s_nop 0
	v_cvt_pk_bf16_f32 v250, v72, v64
	v_mul_f32_e32 v67, 0xbfb8aa3b, v61
	v_cvt_pk_bf16_f32 v251, v73, v65
	v_mul_f32_e32 v66, 0xbfb8aa3b, v60
	v_exp_f32_e32 v68, v67
	v_mul_f32_e32 v67, 0xbfb8aa3b, v62
; __device__ __forceinline__ float siluf_(float x) { return x / (1.f + __expf(-x)); }
; __device__ __forceinline__ unsigned pk_bf16(float lo, float hi) { return (unsigned)f2bf(lo) | ((unsigned)f2bf(hi) << 16); }
;   __device__ __forceinline__ void operator()(const f32x4 (&acc)[2][2][4][2], const Unit& u, int wr, int wc, int fr, int fq) const {
;     const int row0 = u.pm * BM + wr * 64 + fr, col0 = u.pn * HALF + wc * 32 + 4 * fq;
; #pragma unroll
;     for (int ai = 0; ai < 2; ++ai)
; #pragma unroll
;       for (int m = 0; m < 4; ++m) {
;         u16* rowp = O + (size_t)(row0 + ai * HALF + m * 16) * FFN + col0;
; #pragma unroll
;         for (int n = 0; n < 2; ++n) {
;           f32x4 g = acc[ai][0][m][n], up = acc[ai][1][m][n];
;           uint2 w;
;           w.x = pk_bf16(siluf_(g[0]) * up[0], siluf_(g[1]) * up[1]);
;           w.y = pk_bf16(siluf_(g[2]) * up[2], siluf_(g[3]) * up[3]);
;           *reinterpret_cast<uint2*>(rowp + n * 16) = w;
;         }
;       }
;   }
	v_exp_f32_e32 v66, v66
	v_exp_f32_e32 v67, v67
	v_mul_f32_e32 v69, 0xbfb8aa3b, v63
	v_exp_f32_e32 v69, v69
	s_nop 1
	v_permlane16_swap_b32_e32 v248, v250
	v_permlane16_swap_b32_e32 v249, v251
	global_store_dwordx4 v[80:81], v[248:251], off
	v_pk_add_f32 v[66:67], v[66:67], 1.0 op_sel_hi:[1,0]
	v_add_u32_e32 v64, 0x80, v150
	v_pk_add_f32 v[68:69], v[68:69], 1.0 op_sel_hi:[1,0]
	v_mad_i64_i32 v[64:65], s[22:23], v64, s2, v[140:141]
	v_rcp_f32_e32 v70, v67
	s_nop 0
	v_mul_f32_e32 v67, v62, v70
	v_lshl_add_u64 v[64:65], v[64:65], 0, v[142:143]
	v_mov_b32_e32 v70, v56
	v_mov_b32_e32 v71, v58
	v_rcp_f32_e32 v62, v66
	s_nop 0
	v_mul_f32_e32 v66, v60, v62
	v_pk_mul_f32 v[66:67], v[66:67], v[70:71]
	v_rcp_f32_e32 v56, v69
	s_nop 0
	v_mul_f32_e32 v63, v63, v56
	s_nop 0
	v_rcp_f32_e32 v56, v68
	s_nop 0
	v_mul_f32_e32 v62, v61, v56
	v_mov_b32_e32 v58, v57
	v_pk_mul_f32 v[56:57], v[62:63], v[58:59]
	s_nop 0
	v_cvt_pk_bf16_f32 v245, v67, v57
	v_cvt_pk_bf16_f32 v244, v66, v56
	v_mul_f32_e32 v57, 0xbfb8aa3b, v53
	v_mul_f32_e32 v56, 0xbfb8aa3b, v52
	v_exp_f32_e32 v58, v57
	v_mul_f32_e32 v57, 0xbfb8aa3b, v54
	v_exp_f32_e32 v56, v56
	v_exp_f32_e32 v57, v57
	v_mul_f32_e32 v59, 0xbfb8aa3b, v55
	v_exp_f32_e32 v59, v59
	v_pk_add_f32 v[56:57], v[56:57], 1.0 op_sel_hi:[1,0]
	s_nop 0
	v_pk_add_f32 v[58:59], v[58:59], 1.0 op_sel_hi:[1,0]
	v_rcp_f32_e32 v60, v57
	s_nop 0
	v_mul_f32_e32 v57, v54, v60
	s_nop 0
	v_mov_b32_e32 v60, v48
	v_mov_b32_e32 v61, v50
	v_rcp_f32_e32 v54, v56
	s_nop 0
	v_mul_f32_e32 v56, v52, v54
	v_pk_mul_f32 v[56:57], v[56:57], v[60:61]
	v_rcp_f32_e32 v48, v59
	s_nop 0
	v_mul_f32_e32 v55, v55, v48
	s_nop 0
	v_rcp_f32_e32 v48, v58
	s_nop 0
	v_mul_f32_e32 v54, v53, v48
	v_mov_b32_e32 v50, v49
	v_pk_mul_f32 v[48:49], v[54:55], v[50:51]
	s_nop 0
	v_cvt_pk_bf16_f32 v246, v56, v48
	v_mul_f32_e32 v51, 0xbfb8aa3b, v45
	v_cvt_pk_bf16_f32 v247, v57, v49
	v_mul_f32_e32 v50, 0xbfb8aa3b, v44
	v_exp_f32_e32 v52, v51
	v_mul_f32_e32 v51, 0xbfb8aa3b, v46
	v_exp_f32_e32 v50, v50
	v_exp_f32_e32 v51, v51
	v_mul_f32_e32 v53, 0xbfb8aa3b, v47
	v_exp_f32_e32 v53, v53
	s_nop 1
	v_permlane16_swap_b32_e32 v244, v246
	v_permlane16_swap_b32_e32 v245, v247
	global_store_dwordx4 v[64:65], v[244:247], off
	v_pk_add_f32 v[50:51], v[50:51], 1.0 op_sel_hi:[1,0]
	v_add_u32_e32 v48, 0x90, v150
	v_pk_add_f32 v[52:53], v[52:53], 1.0 op_sel_hi:[1,0]
	v_mad_i64_i32 v[48:49], s[22:23], v48, s2, v[140:141]
	v_rcp_f32_e32 v54, v51
	s_nop 0
	v_mul_f32_e32 v51, v46, v54
	v_lshl_add_u64 v[48:49], v[48:49], 0, v[142:143]
	v_mov_b32_e32 v54, v40
	v_mov_b32_e32 v55, v42
	v_rcp_f32_e32 v46, v50
	s_nop 0
	v_mul_f32_e32 v50, v44, v46
	v_pk_mul_f32 v[50:51], v[50:51], v[54:55]
	v_rcp_f32_e32 v40, v53
	s_nop 0
	v_mul_f32_e32 v47, v47, v40
	s_nop 0
	v_rcp_f32_e32 v40, v52
	s_nop 0
	v_mul_f32_e32 v46, v45, v40
	v_mov_b32_e32 v42, v41
	v_pk_mul_f32 v[40:41], v[46:47], v[42:43]
	s_nop 0
	v_cvt_pk_bf16_f32 v249, v51, v41
	v_cvt_pk_bf16_f32 v248, v50, v40
	v_mul_f32_e32 v41, 0xbfb8aa3b, v37
	v_mul_f32_e32 v40, 0xbfb8aa3b, v36
	v_exp_f32_e32 v42, v41
	v_mul_f32_e32 v41, 0xbfb8aa3b, v38
	v_exp_f32_e32 v40, v40
	v_exp_f32_e32 v41, v41
	v_mul_f32_e32 v43, 0xbfb8aa3b, v39
	v_exp_f32_e32 v43, v43
	v_pk_add_f32 v[40:41], v[40:41], 1.0 op_sel_hi:[1,0]
	s_nop 0
	v_pk_add_f32 v[42:43], v[42:43], 1.0 op_sel_hi:[1,0]
	v_rcp_f32_e32 v44, v41
	s_nop 0
	v_mul_f32_e32 v41, v38, v44
	s_nop 0
	v_mov_b32_e32 v44, v32
	v_mov_b32_e32 v45, v34
	v_rcp_f32_e32 v38, v40
	s_nop 0
	v_mul_f32_e32 v40, v36, v38
	v_pk_mul_f32 v[40:41], v[40:41], v[44:45]
	v_rcp_f32_e32 v32, v43
	s_nop 0
	v_mul_f32_e32 v39, v39, v32
	s_nop 0
	v_rcp_f32_e32 v32, v42
	s_nop 0
	v_mul_f32_e32 v38, v37, v32
	v_mov_b32_e32 v34, v33
	v_pk_mul_f32 v[32:33], v[38:39], v[34:35]
	s_nop 0
	v_cvt_pk_bf16_f32 v250, v40, v32
	v_mul_f32_e32 v35, 0xbfb8aa3b, v29
	v_cvt_pk_bf16_f32 v251, v41, v33
	v_mul_f32_e32 v34, 0xbfb8aa3b, v28
	v_exp_f32_e32 v36, v35
	v_mul_f32_e32 v35, 0xbfb8aa3b, v30
	v_exp_f32_e32 v34, v34
	v_exp_f32_e32 v35, v35
; __device__ __forceinline__ float siluf_(float x) { return x / (1.f + __expf(-x)); }
; __device__ __forceinline__ unsigned pk_bf16(float lo, float hi) { return (unsigned)f2bf(lo) | ((unsigned)f2bf(hi) << 16); }
;   __device__ __forceinline__ void operator()(const f32x4 (&acc)[2][2][4][2], const Unit& u, int wr, int wc, int fr, int fq) const {
;     const int row0 = u.pm * BM + wr * 64 + fr, col0 = u.pn * HALF + wc * 32 + 4 * fq;
; #pragma unroll
;     for (int ai = 0; ai < 2; ++ai)
; #pragma unroll
;       for (int m = 0; m < 4; ++m) {
;         u16* rowp = O + (size_t)(row0 + ai * HALF + m * 16) * FFN + col0;
; #pragma unroll
;         for (int n = 0; n < 2; ++n) {
;           f32x4 g = acc[ai][0][m][n], up = acc[ai][1][m][n];
;           uint2 w;
;           w.x = pk_bf16(siluf_(g[0]) * up[0], siluf_(g[1]) * up[1]);
;           w.y = pk_bf16(siluf_(g[2]) * up[2], siluf_(g[3]) * up[3]);
;           *reinterpret_cast<uint2*>(rowp + n * 16) = w;
;         }
;       }
;   }
	v_mul_f32_e32 v37, 0xbfb8aa3b, v31
	v_exp_f32_e32 v37, v37
	s_nop 1
	v_permlane16_swap_b32_e32 v248, v250
	v_permlane16_swap_b32_e32 v249, v251
	global_store_dwordx4 v[48:49], v[248:251], off
	v_pk_add_f32 v[34:35], v[34:35], 1.0 op_sel_hi:[1,0]
	v_add_u32_e32 v32, 0xa0, v150
	v_pk_add_f32 v[36:37], v[36:37], 1.0 op_sel_hi:[1,0]
	v_mad_i64_i32 v[32:33], s[22:23], v32, s2, v[140:141]
	v_rcp_f32_e32 v38, v35
	s_nop 0
	v_mul_f32_e32 v35, v30, v38
	v_lshl_add_u64 v[32:33], v[32:33], 0, v[142:143]
	v_mov_b32_e32 v38, v24
	v_mov_b32_e32 v39, v26
	v_rcp_f32_e32 v30, v34
	s_nop 0
	v_mul_f32_e32 v34, v28, v30
	v_pk_mul_f32 v[34:35], v[34:35], v[38:39]
	v_rcp_f32_e32 v24, v37
	s_nop 0
	v_mul_f32_e32 v31, v31, v24
	s_nop 0
	v_rcp_f32_e32 v24, v36
	s_nop 0
	v_mul_f32_e32 v30, v29, v24
	v_mov_b32_e32 v26, v25
	v_pk_mul_f32 v[24:25], v[30:31], v[26:27]
	s_nop 0
	v_cvt_pk_bf16_f32 v245, v35, v25
	v_cvt_pk_bf16_f32 v244, v34, v24
	v_mul_f32_e32 v25, 0xbfb8aa3b, v21
	v_mul_f32_e32 v24, 0xbfb8aa3b, v20
	v_exp_f32_e32 v26, v25
	v_mul_f32_e32 v25, 0xbfb8aa3b, v22
	v_exp_f32_e32 v24, v24
	v_exp_f32_e32 v25, v25
	v_mul_f32_e32 v27, 0xbfb8aa3b, v23
	v_exp_f32_e32 v27, v27
	v_pk_add_f32 v[24:25], v[24:25], 1.0 op_sel_hi:[1,0]
	s_nop 0
	v_pk_add_f32 v[26:27], v[26:27], 1.0 op_sel_hi:[1,0]
	v_rcp_f32_e32 v28, v25
	s_nop 0
	v_mul_f32_e32 v25, v22, v28
	s_nop 0
	v_mov_b32_e32 v28, v16
	v_mov_b32_e32 v29, v18
	v_rcp_f32_e32 v22, v24
	s_nop 0
	v_mul_f32_e32 v24, v20, v22
	v_pk_mul_f32 v[24:25], v[24:25], v[28:29]
	v_rcp_f32_e32 v16, v27
	s_nop 0
	v_mul_f32_e32 v23, v23, v16
	s_nop 0
	v_rcp_f32_e32 v16, v26
	s_nop 0
	v_mul_f32_e32 v22, v21, v16
	v_mov_b32_e32 v18, v17
	v_pk_mul_f32 v[16:17], v[22:23], v[18:19]
	s_nop 0
	v_cvt_pk_bf16_f32 v246, v24, v16
	v_mul_f32_e32 v19, 0xbfb8aa3b, v13
	v_cvt_pk_bf16_f32 v247, v25, v17
	v_mul_f32_e32 v18, 0xbfb8aa3b, v12
	v_exp_f32_e32 v20, v19
	v_mul_f32_e32 v19, 0xbfb8aa3b, v14
	v_exp_f32_e32 v18, v18
	v_exp_f32_e32 v19, v19
	v_mul_f32_e32 v21, 0xbfb8aa3b, v15
	v_exp_f32_e32 v21, v21
	s_nop 1
	v_permlane16_swap_b32_e32 v244, v246
	v_permlane16_swap_b32_e32 v245, v247
	global_store_dwordx4 v[32:33], v[244:247], off
	v_pk_add_f32 v[18:19], v[18:19], 1.0 op_sel_hi:[1,0]
	v_add_u32_e32 v16, 0xb0, v150
	v_pk_add_f32 v[20:21], v[20:21], 1.0 op_sel_hi:[1,0]
	v_mad_i64_i32 v[16:17], s[22:23], v16, s2, v[140:141]
	v_rcp_f32_e32 v22, v19
	s_nop 0
	v_mul_f32_e32 v19, v14, v22
	v_lshl_add_u64 v[16:17], v[16:17], 0, v[142:143]
	s_mov_b32 s2, s44
	v_mov_b32_e32 v22, v8
	v_mov_b32_e32 v23, v10
	v_rcp_f32_e32 v14, v18
	s_nop 0
	v_mul_f32_e32 v18, v12, v14
	v_pk_mul_f32 v[18:19], v[18:19], v[22:23]
	v_rcp_f32_e32 v8, v21
	s_nop 0
	v_mul_f32_e32 v15, v15, v8
	s_nop 0
	v_rcp_f32_e32 v8, v20
	s_nop 0
	v_mul_f32_e32 v14, v13, v8
	v_mov_b32_e32 v10, v9
	v_pk_mul_f32 v[8:9], v[14:15], v[10:11]
	s_nop 0
	v_cvt_pk_bf16_f32 v249, v19, v9
	v_cvt_pk_bf16_f32 v248, v18, v8
	v_mul_f32_e32 v9, 0xbfb8aa3b, v5
	v_mul_f32_e32 v8, 0xbfb8aa3b, v4
	v_exp_f32_e32 v10, v9
	v_mul_f32_e32 v9, 0xbfb8aa3b, v6
	v_exp_f32_e32 v8, v8
	v_exp_f32_e32 v9, v9
	v_mul_f32_e32 v11, 0xbfb8aa3b, v7
	v_exp_f32_e32 v11, v11
	v_pk_add_f32 v[8:9], v[8:9], 1.0 op_sel_hi:[1,0]
	s_nop 0
	v_pk_add_f32 v[10:11], v[10:11], 1.0 op_sel_hi:[1,0]
	v_rcp_f32_e32 v12, v9
	s_nop 0
	v_mul_f32_e32 v9, v6, v12
	s_nop 0
	v_mov_b32_e32 v12, v0
	v_mov_b32_e32 v13, v2
	v_rcp_f32_e32 v6, v8
	s_nop 0
	v_mul_f32_e32 v8, v4, v6
	v_pk_mul_f32 v[8:9], v[8:9], v[12:13]
	v_rcp_f32_e32 v0, v11
	s_nop 0
	v_mul_f32_e32 v7, v7, v0
	s_mov_b32 s23, s40
	v_rcp_f32_e32 v0, v10
	s_nop 0
	v_mul_f32_e32 v6, v5, v0
	v_mov_b32_e32 v2, v1
	v_pk_mul_f32 v[0:1], v[6:7], v[2:3]
	s_nop 0
	v_cvt_pk_bf16_f32 v251, v9, v1
	v_cvt_pk_bf16_f32 v250, v8, v0
	s_and_b64 vcc, exec, s[38:39]
	s_nop 1
	v_permlane16_swap_b32_e32 v248, v250
	v_permlane16_swap_b32_e32 v249, v251
	global_store_dwordx4 v[16:17], v[248:251], off
	s_cbranch_vccz .LBB0_53
	s_waitcnt vmcnt(0)
	s_cmpk_gt_u32 s63, 0xff
	s_cbranch_scc1 .LBB0_60
	s_barrier

; #define G_STAGE(bufoff, gbase, voff) do { _Pragma("unroll") for (int _i = 0; _i < 2; ++_i) \
;     __builtin_amdgcn_global_load_lds((const unsigned*)((const char*)(gbase) + (voff)[_i]), (LAS unsigned*)(lds + (bufoff) + ldsw + _i * 8192), 16, 0, 0); } while (0)
; #define G_LDA(dst, b, h) do { _Pragma("unroll") for (int m = 0; m < 4; ++m) _Pragma("unroll") for (int k = 0; k < 2; ++k) dst[m][k] = *(const LAS bf16x8*)(lds + G_SA(b, h) + aoff + m * 2048 + k * 1024); } while (0)
; #define G_LDB(dst, b, h) do { _Pragma("unroll") for (int n = 0; n < 2; ++n) _Pragma("unroll") for (int k = 0; k < 2; ++k) dst[n][k] = *(const LAS bf16x8*)(lds + G_SB(b, h) + boff + n * 2048 + k * 1024); } while (0)
; #define G_WAIT_V(n) asm volatile("s_waitcnt vmcnt(" #n ")" ::: "memory")
; #define G_WAIT_L(n) asm volatile("s_waitcnt lgkmcnt(" #n ")" ::: "memory")
; #define G_BAR __builtin_amdgcn_s_barrier()
; template <class Epi>
; __device__ __forceinline__ void gemm_phase(LAS unsigned char* lds, const u16* gA, const u16* gBt, int M, int N, int K, const Epi& E) {
;     ...
;     for (int t = 0; t < nt; t += 2) {
;       const bool last = (t == nt - 2);
;       const char* a1 = cA + (size_t)(t + 1) * kstep;
;       const char* a2 = last ? nA : cA + (size_t)(t + 2) * kstep; const char* b2 = last ? nB : cB + (size_t)(t + 2) * kstep;
;       const char* a3 = a2 + kstep; const char* b3 = b2 + kstep;
;       G_LDB(B0, 0, 0); G_SCHED; G_LDA(At, 0, 0); G_STAGE(G_SA(1, 1), a1 + hstep, voffA);
;       G_WAIT_L(8); G_BAR; G_WAIT_L(0); G_MMA(0, 0, At, B0); G_BAR; G_SCHED;
;       G_LDB(B1, 0, 1); G_STAGE(G_SB(0, 0), b2, voffB);
;       G_BAR; G_WAIT_L(0); G_MMA(0, 1, At, B1); G_BAR;
;       G_LDA(At, 0, 1); G_STAGE(G_SA(0, 0), a2, voffA);
;       G_BAR; G_WAIT_L(0); G_MMA(1, 0, At, B0); G_BAR; G_SCHED;
;       G_STAGE(G_SB(0, 1), b2 + hstep, voffB);
;       G_WAIT_V(6); G_BAR; G_MMA(1, 1, At, B1); G_BAR;
;       G_LDB(B0, 1, 0); G_SCHED; G_LDA(At, 1, 0); G_STAGE(G_SA(0, 1), a2 + hstep, voffA);
;       G_WAIT_L(8); G_BAR; G_WAIT_L(0); G_MMA(0, 0, At, B0); G_BAR; G_SCHED;
;       G_LDB(B1, 1, 1); G_STAGE(G_SB(1, 0), b3, voffB);
;       G_BAR; G_WAIT_L(0); G_MMA(0, 1, At, B1); G_BAR;
;       G_LDA(At, 1, 1); G_STAGE(G_SA(1, 0), a3, voffA);
;       G_BAR; G_WAIT_L(0); G_MMA(1, 0, At, B0); G_BAR; G_SCHED;
;       G_STAGE(G_SB(1, 1), b3 + hstep, voffB);
;       G_WAIT_V(6); G_BAR; G_MMA(1, 1, At, B1); G_BAR;
.LBB0_81:
	s_add_u32 s48, s46, 0x100
	s_addc_u32 s49, s47, 0
	s_add_i32 s20, 0, 0x10000
	v_add_u32_e32 v140, s20, v143
	ds_read_b128 v[146:149], v140
	ds_read_b128 v[150:153], v140 offset:1024
	ds_read_b128 v[154:157], v140 offset:2048
	ds_read_b128 v[158:161], v140 offset:3072
	s_cmp_eq_u32 s37, 28
	s_cselect_b32 s53, s26, s49
	s_cselect_b32 s52, s27, s48
	s_cselect_b32 s51, s3, s33
	s_cselect_b32 s50, s30, s31
	v_lshl_add_u64 v[140:141], s[46:47], 0, v[136:137]
	s_add_i32 m0, s45, 0xc000
	ds_read_b128 v[162:165], v145
	ds_read_b128 v[190:193], v145 offset:1024
	ds_read_b128 v[194:197], v145 offset:2048
	ds_read_b128 v[198:201], v145 offset:3072
	ds_read_b128 v[202:205], v145 offset:4096
	ds_read_b128 v[206:209], v145 offset:5120
	ds_read_b128 v[210:213], v145 offset:6144
	ds_read_b128 v[214:217], v145 offset:7168
	global_load_lds_dwordx4 v[140:141], off
	v_lshl_add_u64 v[140:141], s[46:47], 0, v[138:139]
	s_add_i32 m0, s45, 0xe000
	s_nop 0
	global_load_lds_dwordx4 v[140:141], off
	s_waitcnt lgkmcnt(8)
	s_barrier
	s_waitcnt lgkmcnt(0)
	s_setprio 1
	s_waitcnt lgkmcnt(0)
	v_mfma_f32_16x16x32_bf16 v[124:127], v[146:149], v[162:165], v[124:127]
	v_mfma_f32_16x16x32_bf16 v[120:123], v[154:157], v[162:165], v[120:123]
	v_mfma_f32_16x16x32_bf16 v[108:111], v[146:149], v[194:197], v[108:111]
	v_mfma_f32_16x16x32_bf16 v[104:107], v[154:157], v[194:197], v[104:107]
	v_mfma_f32_16x16x32_bf16 v[92:95], v[146:149], v[202:205], v[92:95]
	v_mfma_f32_16x16x32_bf16 v[88:91], v[154:157], v[202:205], v[88:91]
	v_mfma_f32_16x16x32_bf16 v[76:79], v[146:149], v[210:213], v[76:79]
	v_mfma_f32_16x16x32_bf16 v[72:75], v[154:157], v[210:213], v[72:75]
	v_mfma_f32_16x16x32_bf16 v[124:127], v[150:153], v[190:193], v[124:127]
	v_mfma_f32_16x16x32_bf16 v[120:123], v[158:161], v[190:193], v[120:123]
	v_mfma_f32_16x16x32_bf16 v[108:111], v[150:153], v[198:201], v[108:111]
	v_mfma_f32_16x16x32_bf16 v[104:107], v[158:161], v[198:201], v[104:107]
	v_mfma_f32_16x16x32_bf16 v[92:95], v[150:153], v[206:209], v[92:95]
	v_mfma_f32_16x16x32_bf16 v[88:91], v[158:161], v[206:209], v[88:91]
	v_mfma_f32_16x16x32_bf16 v[76:79], v[150:153], v[214:217], v[76:79]
	v_mfma_f32_16x16x32_bf16 v[72:75], v[158:161], v[214:217], v[72:75]
	s_setprio 0
	s_add_i32 s22, 0, 0x14000
	v_add_u32_e32 v140, s22, v143
	s_add_i32 s20, s20, s55
	s_barrier
	ds_read_b128 v[218:221], v140
	ds_read_b128 v[222:225], v140 offset:1024
	ds_read_b128 v[226:229], v140 offset:2048
	ds_read_b128 v[230:233], v140 offset:3072
	v_lshl_add_u64 v[140:141], s[50:51], 0, v[128:129]
	s_mov_b32 m0, s20
	v_lshl_add_u64 v[166:167], s[50:51], 0, v[134:135]
	global_load_lds_dwordx4 v[140:141], off
	s_add_i32 m0, s20, 0x2000
	s_nop 0
	global_load_lds_dwordx4 v[166:167], off
	s_barrier
	s_waitcnt lgkmcnt(0)
	s_setprio 1
	s_waitcnt lgkmcnt(0)
	v_mfma_f32_16x16x32_bf16 v[116:119], v[218:221], v[162:165], v[116:119]
	v_mfma_f32_16x16x32_bf16 v[112:115], v[226:229], v[162:165], v[112:115]
	v_mfma_f32_16x16x32_bf16 v[100:103], v[218:221], v[194:197], v[100:103]
	v_mfma_f32_16x16x32_bf16 v[96:99], v[226:229], v[194:197], v[96:99]
	v_mfma_f32_16x16x32_bf16 v[84:87], v[218:221], v[202:205], v[84:87]
	v_mfma_f32_16x16x32_bf16 v[80:83], v[226:229], v[202:205], v[80:83]
	v_mfma_f32_16x16x32_bf16 v[68:71], v[218:221], v[210:213], v[68:71]
	v_mfma_f32_16x16x32_bf16 v[64:67], v[226:229], v[210:213], v[64:67]
	v_mfma_f32_16x16x32_bf16 v[116:119], v[222:225], v[190:193], v[116:119]
	v_mfma_f32_16x16x32_bf16 v[112:115], v[230:233], v[190:193], v[112:115]
	v_mfma_f32_16x16x32_bf16 v[100:103], v[222:225], v[198:201], v[100:103]
	v_mfma_f32_16x16x32_bf16 v[96:99], v[230:233], v[198:201], v[96:99]
	v_mfma_f32_16x16x32_bf16 v[84:87], v[222:225], v[206:209], v[84:87]
	v_mfma_f32_16x16x32_bf16 v[80:83], v[230:233], v[206:209], v[80:83]
	v_mfma_f32_16x16x32_bf16 v[68:71], v[222:225], v[214:217], v[68:71]
	v_mfma_f32_16x16x32_bf16 v[64:67], v[230:233], v[214:217], v[64:67]
	s_setprio 0
	s_mov_b32 m0, s45
	v_lshl_add_u64 v[234:235], s[52:53], 0, v[128:129]
	s_barrier
	ds_read_b128 v[162:165], v145 offset:16384
	ds_read_b128 v[190:193], v145 offset:17408
	ds_read_b128 v[194:197], v145 offset:18432
	ds_read_b128 v[198:201], v145 offset:19456
	ds_read_b128 v[202:205], v145 offset:20480
	ds_read_b128 v[206:209], v145 offset:21504
	ds_read_b128 v[210:213], v145 offset:22528
	ds_read_b128 v[214:217], v145 offset:23552
	global_load_lds_dwordx4 v[234:235], off
	v_lshl_add_u64 v[236:237], s[52:53], 0, v[134:135]
	s_mov_b32 m0, s60
	s_nop 0
	global_load_lds_dwordx4 v[236:237], off
	s_barrier
	s_waitcnt lgkmcnt(0)
	s_setprio 1
	s_waitcnt lgkmcnt(0)
	v_mfma_f32_16x16x32_bf16 v[60:63], v[146:149], v[162:165], v[60:63]
	v_mfma_f32_16x16x32_bf16 v[56:59], v[154:157], v[162:165], v[56:59]
	v_mfma_f32_16x16x32_bf16 v[44:47], v[146:149], v[194:197], v[44:47]
	v_mfma_f32_16x16x32_bf16 v[40:43], v[154:157], v[194:197], v[40:43]
	v_mfma_f32_16x16x32_bf16 v[28:31], v[146:149], v[202:205], v[28:31]
	v_mfma_f32_16x16x32_bf16 v[24:27], v[154:157], v[202:205], v[24:27]
	v_mfma_f32_16x16x32_bf16 v[12:15], v[146:149], v[210:213], v[12:15]
	v_mfma_f32_16x16x32_bf16 v[8:11], v[154:157], v[210:213], v[8:11]
	v_mfma_f32_16x16x32_bf16 v[60:63], v[150:153], v[190:193], v[60:63]
	v_mfma_f32_16x16x32_bf16 v[56:59], v[158:161], v[190:193], v[56:59]
	v_mfma_f32_16x16x32_bf16 v[44:47], v[150:153], v[198:201], v[44:47]
	v_mfma_f32_16x16x32_bf16 v[40:43], v[158:161], v[198:201], v[40:43]
	v_mfma_f32_16x16x32_bf16 v[28:31], v[150:153], v[206:209], v[28:31]
	v_mfma_f32_16x16x32_bf16 v[24:27], v[158:161], v[206:209], v[24:27]
	v_mfma_f32_16x16x32_bf16 v[12:15], v[150:153], v[214:217], v[12:15]
	v_mfma_f32_16x16x32_bf16 v[8:11], v[158:161], v[214:217], v[8:11]
	s_setprio 0
	s_add_u32 s24, s50, 0x80000
	s_addc_u32 s25, s51, 0
	s_add_i32 s20, s22, s55
	v_lshl_add_u64 v[146:147], s[24:25], 0, v[128:129]
	s_mov_b32 m0, s20
	s_barrier
; #define G_STAGE(bufoff, gbase, voff) do { _Pragma("unroll") for (int _i = 0; _i < 2; ++_i) \
;     __builtin_amdgcn_global_load_lds((const unsigned*)((const char*)(gbase) + (voff)[_i]), (LAS unsigned*)(lds + (bufoff) + ldsw + _i * 8192), 16, 0, 0); } while (0)
; #define G_LDA(dst, b, h) do { _Pragma("unroll") for (int m = 0; m < 4; ++m) _Pragma("unroll") for (int k = 0; k < 2; ++k) dst[m][k] = *(const LAS bf16x8*)(lds + G_SA(b, h) + aoff + m * 2048 + k * 1024); } while (0)
; #define G_LDB(dst, b, h) do { _Pragma("unroll") for (int n = 0; n < 2; ++n) _Pragma("unroll") for (int k = 0; k < 2; ++k) dst[n][k] = *(const LAS bf16x8*)(lds + G_SB(b, h) + boff + n * 2048 + k * 1024); } while (0)
; #define G_MMA(ai, bj, At, Bt) do { __builtin_amdgcn_s_setprio(1); _Pragma("unroll") for (int m = 0; m < 4; ++m) _Pragma("unroll") for (int n = 0; n < 2; ++n) _Pragma("unroll") for (int k = 0; k < 2; ++k) \
;     acc[ai][bj][m][n] = __builtin_amdgcn_mfma_f32_16x16x32_bf16(Bt[n][k], At[m][k], acc[ai][bj][m][n], 0, 0, 0); __builtin_amdgcn_s_setprio(0); } while (0)
; #define G_WAIT_V(n) asm volatile("s_waitcnt vmcnt(" #n ")" ::: "memory")
; #define G_WAIT_L(n) asm volatile("s_waitcnt lgkmcnt(" #n ")" ::: "memory")
; template <class Epi>
; __device__ __forceinline__ void gemm_phase(LAS unsigned char* lds, const u16* gA, const u16* gBt, int M, int N, int K, const Epi& E) {
;     ...
;       G_LDB(B0, 0, 0); G_SCHED; G_LDA(At, 0, 0); G_STAGE(G_SA(1, 1), a1 + hstep, voffA);
;       G_WAIT_L(8); G_BAR; G_WAIT_L(0); G_MMA(0, 0, At, B0); G_BAR; G_SCHED;
;       G_LDB(B1, 0, 1); G_STAGE(G_SB(0, 0), b2, voffB);
;       G_BAR; G_WAIT_L(0); G_MMA(0, 1, At, B1); G_BAR;
;       G_LDA(At, 0, 1); G_STAGE(G_SA(0, 0), a2, voffA);
;       G_BAR; G_WAIT_L(0); G_MMA(1, 0, At, B0); G_BAR; G_SCHED;
;       G_STAGE(G_SB(0, 1), b2 + hstep, voffB);
;       G_WAIT_V(6); G_BAR; G_MMA(1, 1, At, B1); G_BAR;
;       G_LDB(B0, 1, 0); G_SCHED; G_LDA(At, 1, 0); G_STAGE(G_SA(0, 1), a2 + hstep, voffA);
;       G_WAIT_L(8); G_BAR; G_WAIT_L(0); G_MMA(0, 0, At, B0); G_BAR; G_SCHED;
;       G_LDB(B1, 1, 1); G_STAGE(G_SB(1, 0), b3, voffB);
;       G_BAR; G_WAIT_L(0); G_MMA(0, 1, At, B1); G_BAR;
;       G_LDA(At, 1, 1); G_STAGE(G_SA(1, 0), a3, voffA);
;       G_BAR; G_WAIT_L(0); G_MMA(1, 0, At, B0); G_BAR; G_SCHED;
;       G_STAGE(G_SB(1, 1), b3 + hstep, voffB);
;       G_WAIT_V(6); G_BAR; G_MMA(1, 1, At, B1); G_BAR;
	s_nop 0
	global_load_lds_dwordx4 v[146:147], off
	v_lshl_add_u64 v[146:147], s[24:25], 0, v[134:135]
	s_add_i32 m0, s20, 0x2000
	s_nop 0
	global_load_lds_dwordx4 v[146:147], off
	s_waitcnt vmcnt(6)
	s_barrier
	s_setprio 1
	v_mfma_f32_16x16x32_bf16 v[52:55], v[218:221], v[162:165], v[52:55]
	v_mfma_f32_16x16x32_bf16 v[48:51], v[226:229], v[162:165], v[48:51]
	v_mfma_f32_16x16x32_bf16 v[36:39], v[218:221], v[194:197], v[36:39]
	v_mfma_f32_16x16x32_bf16 v[32:35], v[226:229], v[194:197], v[32:35]
	v_mfma_f32_16x16x32_bf16 v[20:23], v[218:221], v[202:205], v[20:23]
	v_mfma_f32_16x16x32_bf16 v[16:19], v[226:229], v[202:205], v[16:19]
	v_mfma_f32_16x16x32_bf16 v[4:7], v[218:221], v[210:213], v[4:7]
	v_mfma_f32_16x16x32_bf16 v[0:3], v[226:229], v[210:213], v[0:3]
	v_mfma_f32_16x16x32_bf16 v[52:55], v[222:225], v[190:193], v[52:55]
	v_mfma_f32_16x16x32_bf16 v[48:51], v[230:233], v[190:193], v[48:51]
	v_mfma_f32_16x16x32_bf16 v[36:39], v[222:225], v[198:201], v[36:39]
	v_mfma_f32_16x16x32_bf16 v[32:35], v[230:233], v[198:201], v[32:35]
	v_mfma_f32_16x16x32_bf16 v[20:23], v[222:225], v[206:209], v[20:23]
	v_mfma_f32_16x16x32_bf16 v[16:19], v[230:233], v[206:209], v[16:19]
	v_mfma_f32_16x16x32_bf16 v[4:7], v[222:225], v[214:217], v[4:7]
	v_mfma_f32_16x16x32_bf16 v[0:3], v[230:233], v[214:217], v[0:3]
	s_setprio 0
	s_add_i32 s20, 0, 0x18000
	v_add_u32_e32 v158, s20, v143
	s_barrier
	ds_read_b128 v[146:149], v158
	ds_read_b128 v[150:153], v158 offset:1024
	ds_read_b128 v[154:157], v158 offset:2048
	ds_read_b128 v[158:161], v158 offset:3072
	s_add_u32 s24, s52, 0x80000
	s_addc_u32 s25, s53, 0
	s_mov_b32 m0, s61
	v_lshl_add_u64 v[218:219], s[24:25], 0, v[128:129]
	ds_read_b128 v[162:165], v145 offset:32768
	ds_read_b128 v[190:193], v145 offset:33792
	ds_read_b128 v[194:197], v145 offset:34816
	ds_read_b128 v[198:201], v145 offset:35840
	ds_read_b128 v[202:205], v145 offset:36864
	ds_read_b128 v[206:209], v145 offset:37888
	ds_read_b128 v[210:213], v145 offset:38912
	ds_read_b128 v[214:217], v145 offset:39936
	global_load_lds_dwordx4 v[218:219], off
	v_lshl_add_u64 v[218:219], s[24:25], 0, v[134:135]
	s_mov_b32 m0, s62
	s_nop 0
	global_load_lds_dwordx4 v[218:219], off
	s_waitcnt lgkmcnt(8)
	s_barrier
	s_waitcnt lgkmcnt(0)
	s_setprio 1
	s_waitcnt lgkmcnt(0)
	v_mfma_f32_16x16x32_bf16 v[124:127], v[146:149], v[162:165], v[124:127]
	v_mfma_f32_16x16x32_bf16 v[120:123], v[154:157], v[162:165], v[120:123]
	v_mfma_f32_16x16x32_bf16 v[108:111], v[146:149], v[194:197], v[108:111]
	v_mfma_f32_16x16x32_bf16 v[104:107], v[154:157], v[194:197], v[104:107]
	v_mfma_f32_16x16x32_bf16 v[92:95], v[146:149], v[202:205], v[92:95]
	v_mfma_f32_16x16x32_bf16 v[88:91], v[154:157], v[202:205], v[88:91]
	v_mfma_f32_16x16x32_bf16 v[76:79], v[146:149], v[210:213], v[76:79]
	v_mfma_f32_16x16x32_bf16 v[72:75], v[154:157], v[210:213], v[72:75]
	v_mfma_f32_16x16x32_bf16 v[124:127], v[150:153], v[190:193], v[124:127]
	v_mfma_f32_16x16x32_bf16 v[120:123], v[158:161], v[190:193], v[120:123]
	v_mfma_f32_16x16x32_bf16 v[108:111], v[150:153], v[198:201], v[108:111]
	v_mfma_f32_16x16x32_bf16 v[104:107], v[158:161], v[198:201], v[104:107]
	v_mfma_f32_16x16x32_bf16 v[92:95], v[150:153], v[206:209], v[92:95]
	v_mfma_f32_16x16x32_bf16 v[88:91], v[158:161], v[206:209], v[88:91]
	v_mfma_f32_16x16x32_bf16 v[76:79], v[150:153], v[214:217], v[76:79]
	v_mfma_f32_16x16x32_bf16 v[72:75], v[158:161], v[214:217], v[72:75]
	s_setprio 0
	s_add_i32 s22, 0, 0x1c000
	s_add_i32 s20, s20, s55
	v_add_u32_e32 v230, s22, v143
	v_lshl_add_u64 v[140:141], v[140:141], 0, s[34:35]
	s_mov_b32 m0, s20
	s_barrier
	ds_read_b128 v[218:221], v230
	ds_read_b128 v[222:225], v230 offset:1024
	ds_read_b128 v[226:229], v230 offset:2048
	ds_read_b128 v[230:233], v230 offset:3072
	global_load_lds_dwordx4 v[140:141], off
	v_lshl_add_u64 v[140:141], v[166:167], 0, s[34:35]
	s_add_i32 m0, s20, 0x2000
	s_nop 0
	global_load_lds_dwordx4 v[140:141], off
	s_barrier
	s_waitcnt lgkmcnt(0)
	s_setprio 1
	s_waitcnt lgkmcnt(0)
	v_mfma_f32_16x16x32_bf16 v[116:119], v[218:221], v[162:165], v[116:119]
	v_mfma_f32_16x16x32_bf16 v[112:115], v[226:229], v[162:165], v[112:115]
	v_mfma_f32_16x16x32_bf16 v[100:103], v[218:221], v[194:197], v[100:103]
	v_mfma_f32_16x16x32_bf16 v[96:99], v[226:229], v[194:197], v[96:99]
	v_mfma_f32_16x16x32_bf16 v[84:87], v[218:221], v[202:205], v[84:87]
	v_mfma_f32_16x16x32_bf16 v[80:83], v[226:229], v[202:205], v[80:83]
	v_mfma_f32_16x16x32_bf16 v[68:71], v[218:221], v[210:213], v[68:71]
	v_mfma_f32_16x16x32_bf16 v[64:67], v[226:229], v[210:213], v[64:67]
	v_mfma_f32_16x16x32_bf16 v[116:119], v[222:225], v[190:193], v[116:119]
	v_mfma_f32_16x16x32_bf16 v[112:115], v[230:233], v[190:193], v[112:115]
	v_mfma_f32_16x16x32_bf16 v[100:103], v[222:225], v[198:201], v[100:103]
	v_mfma_f32_16x16x32_bf16 v[96:99], v[230:233], v[198:201], v[96:99]
	v_mfma_f32_16x16x32_bf16 v[84:87], v[222:225], v[206:209], v[84:87]
	v_mfma_f32_16x16x32_bf16 v[80:83], v[230:233], v[206:209], v[80:83]
	v_mfma_f32_16x16x32_bf16 v[68:71], v[222:225], v[214:217], v[68:71]
	v_mfma_f32_16x16x32_bf16 v[64:67], v[230:233], v[214:217], v[64:67]
	s_setprio 0
	s_mov_b32 m0, s67
	v_lshl_add_u64 v[140:141], v[234:235], 0, s[34:35]
	s_barrier
	ds_read_b128 v[162:165], v145 offset:49152
	ds_read_b128 v[190:193], v145 offset:50176
	ds_read_b128 v[194:197], v145 offset:51200
	ds_read_b128 v[198:201], v145 offset:52224
	ds_read_b128 v[202:205], v145 offset:53248
	ds_read_b128 v[206:209], v145 offset:54272
	ds_read_b128 v[210:213], v145 offset:55296
	ds_read_b128 v[214:217], v145 offset:56320
	global_load_lds_dwordx4 v[140:141], off
	v_lshl_add_u64 v[140:141], v[236:237], 0, s[34:35]
	s_mov_b32 m0, s68
	s_nop 0
	global_load_lds_dwordx4 v[140:141], off
	s_barrier
; #define G_STAGE(bufoff, gbase, voff) do { _Pragma("unroll") for (int _i = 0; _i < 2; ++_i) \
;     __builtin_amdgcn_global_load_lds((const unsigned*)((const char*)(gbase) + (voff)[_i]), (LAS unsigned*)(lds + (bufoff) + ldsw + _i * 8192), 16, 0, 0); } while (0)
; #define G_LDA(dst, b, h) do { _Pragma("unroll") for (int m = 0; m < 4; ++m) _Pragma("unroll") for (int k = 0; k < 2; ++k) dst[m][k] = *(const LAS bf16x8*)(lds + G_SA(b, h) + aoff + m * 2048 + k * 1024); } while (0)
;   __device__ __forceinline__ void operator()(const f32x4 (&acc)[2][2][4][2], const Unit& u, int wr, int wc, int fr, int fq) const {
;     const int row0 = u.pm * BM + wr * 64 + fr, col0 = u.pn * BM + wc * 32 + 4 * fq;
; #pragma unroll
;     for (int ai = 0; ai < 2; ++ai)
; #pragma unroll
;       for (int m = 0; m < 4; ++m) {
;         const int row = row0 + ai * HALF + m * 16;
;         const float* gp = gate + (size_t)condof(row) * 6 * D + col0;
;         const float* hold; float* hnew;
;         if (row < NX) { hnew = out + (size_t)row * D + col0; hold = xin ? xin + (size_t)row * D + col0 : hnew; }
;         else { hnew = hc + (size_t)(row - NX) * D + col0; hold = cin ? cin + (size_t)(row - NX) * D + col0 : hnew; }
; #pragma unroll
;         for (int bj = 0; bj < 2; ++bj)
; #pragma unroll
;           for (int n = 0; n < 2; ++n) {
;             f32x4 h = *reinterpret_cast<const f32x4*>(hold + bj * HALF + n * 16);
;             f32x4 g = *reinterpret_cast<const f32x4*>(gp + bj * HALF + n * 16);
;             *reinterpret_cast<f32x4*>(hnew + bj * HALF + n * 16) = h + g * acc[ai][bj][m][n];
;           }
;       }
; template <class Epi>
; __device__ __forceinline__ void gemm_phase(LAS unsigned char* lds, const u16* gA, const u16* gBt, int M, int N, int K, const Epi& E) {
;     ...
;       G_WAIT_V(6); G_BAR; G_MMA(1, 1, At, B1); G_BAR;
;       G_LDB(B0, 1, 0); G_SCHED; G_LDA(At, 1, 0); G_STAGE(G_SA(0, 1), a2 + hstep, voffA);
;       G_WAIT_L(8); G_BAR; G_WAIT_L(0); G_MMA(0, 0, At, B0); G_BAR; G_SCHED;
;       G_LDB(B1, 1, 1); G_STAGE(G_SB(1, 0), b3, voffB);
;       G_BAR; G_WAIT_L(0); G_MMA(0, 1, At, B1); G_BAR;
;       G_LDA(At, 1, 1); G_STAGE(G_SA(1, 0), a3, voffA);
;       G_BAR; G_WAIT_L(0); G_MMA(1, 0, At, B0); G_BAR; G_SCHED;
;       G_STAGE(G_SB(1, 1), b3 + hstep, voffB);
;       G_WAIT_V(6); G_BAR; G_MMA(1, 1, At, B1); G_BAR;
;     }
;     E(acc, cur, wr, wc, fr, fq);
	s_waitcnt lgkmcnt(0)
	s_setprio 1
	s_waitcnt lgkmcnt(0)
	v_mfma_f32_16x16x32_bf16 v[60:63], v[146:149], v[162:165], v[60:63]
	v_mfma_f32_16x16x32_bf16 v[56:59], v[154:157], v[162:165], v[56:59]
	v_mfma_f32_16x16x32_bf16 v[44:47], v[146:149], v[194:197], v[44:47]
	v_mfma_f32_16x16x32_bf16 v[40:43], v[154:157], v[194:197], v[40:43]
	v_mfma_f32_16x16x32_bf16 v[28:31], v[146:149], v[202:205], v[28:31]
	v_mfma_f32_16x16x32_bf16 v[24:27], v[154:157], v[202:205], v[24:27]
	v_mfma_f32_16x16x32_bf16 v[12:15], v[146:149], v[210:213], v[12:15]
	v_mfma_f32_16x16x32_bf16 v[8:11], v[154:157], v[210:213], v[8:11]
	v_mfma_f32_16x16x32_bf16 v[60:63], v[150:153], v[190:193], v[60:63]
	v_mfma_f32_16x16x32_bf16 v[56:59], v[158:161], v[190:193], v[56:59]
	v_mfma_f32_16x16x32_bf16 v[44:47], v[150:153], v[198:201], v[44:47]
	v_mfma_f32_16x16x32_bf16 v[40:43], v[158:161], v[198:201], v[40:43]
	v_mfma_f32_16x16x32_bf16 v[28:31], v[150:153], v[206:209], v[28:31]
	v_mfma_f32_16x16x32_bf16 v[24:27], v[158:161], v[206:209], v[24:27]
	v_mfma_f32_16x16x32_bf16 v[12:15], v[150:153], v[214:217], v[12:15]
	v_mfma_f32_16x16x32_bf16 v[8:11], v[158:161], v[214:217], v[8:11]
	s_setprio 0
	s_add_u32 s24, s50, 0x80080
	s_addc_u32 s25, s51, 0
	s_add_i32 s20, s22, s55
	v_lshl_add_u64 v[140:141], s[24:25], 0, v[128:129]
	s_mov_b32 m0, s20
	s_barrier
	s_nop 0
	global_load_lds_dwordx4 v[140:141], off
	v_lshl_add_u64 v[140:141], s[24:25], 0, v[134:135]
	s_add_i32 m0, s20, 0x2000
	s_nop 0
	global_load_lds_dwordx4 v[140:141], off
	s_waitcnt vmcnt(6)
	s_barrier
	s_setprio 1
	v_mfma_f32_16x16x32_bf16 v[52:55], v[218:221], v[162:165], v[52:55]
	v_mfma_f32_16x16x32_bf16 v[48:51], v[226:229], v[162:165], v[48:51]
	v_mfma_f32_16x16x32_bf16 v[36:39], v[218:221], v[194:197], v[36:39]
	v_mfma_f32_16x16x32_bf16 v[32:35], v[226:229], v[194:197], v[32:35]
	v_mfma_f32_16x16x32_bf16 v[20:23], v[218:221], v[202:205], v[20:23]
	v_mfma_f32_16x16x32_bf16 v[16:19], v[226:229], v[202:205], v[16:19]
	v_mfma_f32_16x16x32_bf16 v[4:7], v[218:221], v[210:213], v[4:7]
	v_mfma_f32_16x16x32_bf16 v[0:3], v[226:229], v[210:213], v[0:3]
	v_mfma_f32_16x16x32_bf16 v[52:55], v[222:225], v[190:193], v[52:55]
	v_mfma_f32_16x16x32_bf16 v[48:51], v[230:233], v[190:193], v[48:51]
	v_mfma_f32_16x16x32_bf16 v[36:39], v[222:225], v[198:201], v[36:39]
	v_mfma_f32_16x16x32_bf16 v[32:35], v[230:233], v[198:201], v[32:35]
	v_mfma_f32_16x16x32_bf16 v[20:23], v[222:225], v[206:209], v[20:23]
	v_mfma_f32_16x16x32_bf16 v[16:19], v[230:233], v[206:209], v[16:19]
	v_mfma_f32_16x16x32_bf16 v[4:7], v[222:225], v[214:217], v[4:7]
	v_mfma_f32_16x16x32_bf16 v[0:3], v[230:233], v[214:217], v[0:3]
	s_setprio 0
	s_add_i32 s37, s37, 2
	s_add_u32 s31, s31, 0x100
	s_addc_u32 s33, s33, 0
	s_cmp_gt_u32 s37, 29
	s_mov_b64 s[46:47], s[48:49]
	s_barrier
	s_cbranch_scc0 .LBB0_81
	v_lshl_add_u32 v146, s44, 8, v142
	v_min_i32_e32 v147, 0x4000, v146
	v_lshl_or_b32 v140, s23, 8, v144
	v_ashrrev_i32_e32 v147, 12, v147
	v_ashrrev_i32_e32 v141, 31, v140
	v_mul_hi_i32_i24_e32 v149, 0xc000, v147
	v_mul_i32_i24_e32 v148, 0xc000, v147
	v_lshl_add_u64 v[148:149], s[0:1], 0, v[148:149]
	v_lshlrev_b64 v[140:141], 2, v[140:141]
	s_movk_i32 s3, 0x4000
	v_lshl_add_u64 v[248:249], v[148:149], 0, v[140:141]
	global_load_dwordx4 v[190:193], v[248:249], off
	global_load_dwordx4 v[194:197], v[248:249], off offset:64
	global_load_dwordx4 v[198:201], v[248:249], off offset:512
	global_load_dwordx4 v[202:205], v[248:249], off offset:576
	v_cmp_gt_i32_e32 vcc, s3, v146
	v_add_u32_e32 v155, 0xffffc000, v146
	v_mov_b32_e32 v147, s7
	v_mov_b32_e32 v148, s83
	v_mov_b32_e32 v149, s6
	v_mov_b32_e32 v150, s82
	v_mov_b32_e32 v151, s58
	v_mov_b32_e32 v152, s65
	v_mov_b32_e32 v153, s59
	v_mov_b32_e32 v154, s66
	v_cndmask_b32_e32 v158, v155, v146, vcc
	v_cndmask_b32_e32 v165, v147, v148, vcc
	v_cndmask_b32_e32 v164, v149, v150, vcc
	v_cndmask_b32_e32 v163, v151, v152, vcc
	v_cndmask_b32_e32 v162, v153, v154, vcc
	v_mov_b32_e32 v157, 0
	v_lshl_add_u64 v[164:165], v[164:165], 0, v[140:141]
	v_lshl_add_u64 v[162:163], v[162:163], 0, v[140:141]
	s_mov_b32 s23, s2
	s_mov_b32 s44, s36
	s_mov_b64 s[48:49], s[42:43]
	s_mov_b64 s[46:47], s[40:41]
	v_mov_b32_e32 v156, v158
	v_lshlrev_b64 v[160:161], 13, v[156:157]
	v_lshl_add_u64 v[244:245], v[160:161], 0, v[162:163]
	global_load_dwordx4 v[206:209], v[244:245], off
	global_load_dwordx4 v[210:213], v[244:245], off offset:64
	global_load_dwordx4 v[214:217], v[244:245], off offset:512
	global_load_dwordx4 v[218:221], v[244:245], off offset:576
	v_add_u32_e32 v156, 0x10, v158
	v_lshlrev_b64 v[160:161], 13, v[156:157]
	v_lshl_add_u64 v[244:245], v[160:161], 0, v[162:163]
	global_load_dwordx4 v[222:225], v[244:245], off
	global_load_dwordx4 v[226:229], v[244:245], off offset:64
	global_load_dwordx4 v[230:233], v[244:245], off offset:512
	global_load_dwordx4 v[234:237], v[244:245], off offset:576
	v_mov_b32_e32 v156, v158
	v_lshlrev_b64 v[160:161], 13, v[156:157]
	v_lshl_add_u64 v[246:247], v[160:161], 0, v[164:165]
	s_waitcnt vmcnt(4)
	v_pk_fma_f32 v[126:127], v[126:127], v[192:193], v[208:209]
	v_pk_fma_f32 v[124:125], v[124:125], v[190:191], v[206:207]
	v_pk_fma_f32 v[122:123], v[122:123], v[196:197], v[212:213]
	v_pk_fma_f32 v[120:121], v[120:121], v[194:195], v[210:211]
	v_pk_fma_f32 v[118:119], v[118:119], v[200:201], v[216:217]
	v_pk_fma_f32 v[116:117], v[116:117], v[198:199], v[214:215]
	v_pk_fma_f32 v[114:115], v[114:115], v[204:205], v[220:221]
	v_pk_fma_f32 v[112:113], v[112:113], v[202:203], v[218:219]
	global_store_dwordx4 v[246:247], v[124:127], off
	global_store_dwordx4 v[246:247], v[120:123], off offset:64
	global_store_dwordx4 v[246:247], v[116:119], off offset:512
	global_store_dwordx4 v[246:247], v[112:115], off offset:576
	v_add_u32_e32 v156, 0x20, v158
	v_lshlrev_b64 v[160:161], 13, v[156:157]
	v_lshl_add_u64 v[244:245], v[160:161], 0, v[162:163]
	global_load_dwordx4 v[206:209], v[244:245], off
	global_load_dwordx4 v[210:213], v[244:245], off offset:64
	global_load_dwordx4 v[214:217], v[244:245], off offset:512
	global_load_dwordx4 v[218:221], v[244:245], off offset:576
	v_add_u32_e32 v156, 0x10, v158
	v_lshlrev_b64 v[160:161], 13, v[156:157]
	v_lshl_add_u64 v[246:247], v[160:161], 0, v[164:165]
	s_waitcnt vmcnt(4)
;   __device__ __forceinline__ void operator()(const f32x4 (&acc)[2][2][4][2], const Unit& u, int wr, int wc, int fr, int fq) const {
;     ...
; #pragma unroll
;     for (int ai = 0; ai < 2; ++ai)
; #pragma unroll
;       for (int m = 0; m < 4; ++m) {
;         const int row = row0 + ai * HALF + m * 16;
;         const float* gp = gate + (size_t)condof(row) * 6 * D + col0;
;         const float* hold; float* hnew;
;         if (row < NX) { hnew = out + (size_t)row * D + col0; hold = xin ? xin + (size_t)row * D + col0 : hnew; }
;         else { hnew = hc + (size_t)(row - NX) * D + col0; hold = cin ? cin + (size_t)(row - NX) * D + col0 : hnew; }
; #pragma unroll
;         for (int bj = 0; bj < 2; ++bj)
; #pragma unroll
;           for (int n = 0; n < 2; ++n) {
;             f32x4 h = *reinterpret_cast<const f32x4*>(hold + bj * HALF + n * 16);
;             f32x4 g = *reinterpret_cast<const f32x4*>(gp + bj * HALF + n * 16);
;             *reinterpret_cast<f32x4*>(hnew + bj * HALF + n * 16) = h + g * acc[ai][bj][m][n];
;           }
;       }
	v_pk_fma_f32 v[110:111], v[110:111], v[192:193], v[224:225]
	v_pk_fma_f32 v[108:109], v[108:109], v[190:191], v[222:223]
	v_pk_fma_f32 v[106:107], v[106:107], v[196:197], v[228:229]
	v_pk_fma_f32 v[104:105], v[104:105], v[194:195], v[226:227]
	v_pk_fma_f32 v[102:103], v[102:103], v[200:201], v[232:233]
	v_pk_fma_f32 v[100:101], v[100:101], v[198:199], v[230:231]
	v_pk_fma_f32 v[98:99], v[98:99], v[204:205], v[236:237]
	v_pk_fma_f32 v[96:97], v[96:97], v[202:203], v[234:235]
	global_store_dwordx4 v[246:247], v[108:111], off
	global_store_dwordx4 v[246:247], v[104:107], off offset:64
	global_store_dwordx4 v[246:247], v[100:103], off offset:512
	global_store_dwordx4 v[246:247], v[96:99], off offset:576
	v_add_u32_e32 v156, 0x30, v158
	v_lshlrev_b64 v[160:161], 13, v[156:157]
	v_lshl_add_u64 v[244:245], v[160:161], 0, v[162:163]
	global_load_dwordx4 v[222:225], v[244:245], off
	global_load_dwordx4 v[226:229], v[244:245], off offset:64
	global_load_dwordx4 v[230:233], v[244:245], off offset:512
	global_load_dwordx4 v[234:237], v[244:245], off offset:576
	v_add_u32_e32 v156, 0x20, v158
	v_lshlrev_b64 v[160:161], 13, v[156:157]
	v_lshl_add_u64 v[246:247], v[160:161], 0, v[164:165]
	s_waitcnt vmcnt(4)
	v_pk_fma_f32 v[94:95], v[94:95], v[192:193], v[208:209]
	v_pk_fma_f32 v[92:93], v[92:93], v[190:191], v[206:207]
	v_pk_fma_f32 v[90:91], v[90:91], v[196:197], v[212:213]
	v_pk_fma_f32 v[88:89], v[88:89], v[194:195], v[210:211]
	v_pk_fma_f32 v[86:87], v[86:87], v[200:201], v[216:217]
	v_pk_fma_f32 v[84:85], v[84:85], v[198:199], v[214:215]
	v_pk_fma_f32 v[82:83], v[82:83], v[204:205], v[220:221]
	v_pk_fma_f32 v[80:81], v[80:81], v[202:203], v[218:219]
	global_store_dwordx4 v[246:247], v[92:95], off
	global_store_dwordx4 v[246:247], v[88:91], off offset:64
	global_store_dwordx4 v[246:247], v[84:87], off offset:512
	global_store_dwordx4 v[246:247], v[80:83], off offset:576
	v_add_u32_e32 v156, 0x80, v158
	v_lshlrev_b64 v[160:161], 13, v[156:157]
	v_lshl_add_u64 v[244:245], v[160:161], 0, v[162:163]
	global_load_dwordx4 v[206:209], v[244:245], off
	global_load_dwordx4 v[210:213], v[244:245], off offset:64
	global_load_dwordx4 v[214:217], v[244:245], off offset:512
	global_load_dwordx4 v[218:221], v[244:245], off offset:576
	v_add_u32_e32 v156, 0x30, v158
	v_lshlrev_b64 v[160:161], 13, v[156:157]
	v_lshl_add_u64 v[246:247], v[160:161], 0, v[164:165]
	s_waitcnt vmcnt(4)
	v_pk_fma_f32 v[78:79], v[78:79], v[192:193], v[224:225]
	v_pk_fma_f32 v[76:77], v[76:77], v[190:191], v[222:223]
	v_pk_fma_f32 v[74:75], v[74:75], v[196:197], v[228:229]
	v_pk_fma_f32 v[72:73], v[72:73], v[194:195], v[226:227]
	v_pk_fma_f32 v[70:71], v[70:71], v[200:201], v[232:233]
	v_pk_fma_f32 v[68:69], v[68:69], v[198:199], v[230:231]
	v_pk_fma_f32 v[66:67], v[66:67], v[204:205], v[236:237]
	v_pk_fma_f32 v[64:65], v[64:65], v[202:203], v[234:235]
	global_store_dwordx4 v[246:247], v[76:79], off
	global_store_dwordx4 v[246:247], v[72:75], off offset:64
	global_store_dwordx4 v[246:247], v[68:71], off offset:512
	global_store_dwordx4 v[246:247], v[64:67], off offset:576
	v_add_u32_e32 v156, 0x90, v158
	v_lshlrev_b64 v[160:161], 13, v[156:157]
	v_lshl_add_u64 v[244:245], v[160:161], 0, v[162:163]
	global_load_dwordx4 v[222:225], v[244:245], off
	global_load_dwordx4 v[226:229], v[244:245], off offset:64
	global_load_dwordx4 v[230:233], v[244:245], off offset:512
	global_load_dwordx4 v[234:237], v[244:245], off offset:576
	v_add_u32_e32 v156, 0x80, v158
	v_lshlrev_b64 v[160:161], 13, v[156:157]
	v_lshl_add_u64 v[246:247], v[160:161], 0, v[164:165]
	s_waitcnt vmcnt(4)
; #define G_WAIT_V(n) asm volatile("s_waitcnt vmcnt(" #n ")" ::: "memory")
; #define G_BAR __builtin_amdgcn_s_barrier()
;   __device__ __forceinline__ void operator()(const f32x4 (&acc)[2][2][4][2], const Unit& u, int wr, int wc, int fr, int fq) const {
;     ...
; #pragma unroll
;     for (int ai = 0; ai < 2; ++ai)
; #pragma unroll
;       for (int m = 0; m < 4; ++m) {
;         const int row = row0 + ai * HALF + m * 16;
;         const float* gp = gate + (size_t)condof(row) * 6 * D + col0;
;         const float* hold; float* hnew;
;         if (row < NX) { hnew = out + (size_t)row * D + col0; hold = xin ? xin + (size_t)row * D + col0 : hnew; }
;         else { hnew = hc + (size_t)(row - NX) * D + col0; hold = cin ? cin + (size_t)(row - NX) * D + col0 : hnew; }
; #pragma unroll
;         for (int bj = 0; bj < 2; ++bj)
; #pragma unroll
;           for (int n = 0; n < 2; ++n) {
;             f32x4 h = *reinterpret_cast<const f32x4*>(hold + bj * HALF + n * 16);
;             f32x4 g = *reinterpret_cast<const f32x4*>(gp + bj * HALF + n * 16);
;             *reinterpret_cast<f32x4*>(hnew + bj * HALF + n * 16) = h + g * acc[ai][bj][m][n];
;           }
;       }
; template <class Epi>
; __device__ __forceinline__ void gemm_phase(LAS unsigned char* lds, const u16* gA, const u16* gBt, int M, int N, int K, const Epi& E) {
;     ...
;   G_WAIT_V(0);
;   if (wr == 0) G_BAR;
;   G_BAR;
	v_pk_fma_f32 v[62:63], v[62:63], v[192:193], v[208:209]
	v_pk_fma_f32 v[60:61], v[60:61], v[190:191], v[206:207]
	v_pk_fma_f32 v[58:59], v[58:59], v[196:197], v[212:213]
	v_pk_fma_f32 v[56:57], v[56:57], v[194:195], v[210:211]
	v_pk_fma_f32 v[54:55], v[54:55], v[200:201], v[216:217]
	v_pk_fma_f32 v[52:53], v[52:53], v[198:199], v[214:215]
	v_pk_fma_f32 v[50:51], v[50:51], v[204:205], v[220:221]
	v_pk_fma_f32 v[48:49], v[48:49], v[202:203], v[218:219]
	global_store_dwordx4 v[246:247], v[60:63], off
	global_store_dwordx4 v[246:247], v[56:59], off offset:64
	global_store_dwordx4 v[246:247], v[52:55], off offset:512
	global_store_dwordx4 v[246:247], v[48:51], off offset:576
	v_add_u32_e32 v156, 0xa0, v158
	v_lshlrev_b64 v[160:161], 13, v[156:157]
	v_lshl_add_u64 v[244:245], v[160:161], 0, v[162:163]
	global_load_dwordx4 v[206:209], v[244:245], off
	global_load_dwordx4 v[210:213], v[244:245], off offset:64
	global_load_dwordx4 v[214:217], v[244:245], off offset:512
	global_load_dwordx4 v[218:221], v[244:245], off offset:576
	v_add_u32_e32 v156, 0x90, v158
	v_lshlrev_b64 v[160:161], 13, v[156:157]
	v_lshl_add_u64 v[246:247], v[160:161], 0, v[164:165]
	s_waitcnt vmcnt(4)
	v_pk_fma_f32 v[46:47], v[46:47], v[192:193], v[224:225]
	v_pk_fma_f32 v[44:45], v[44:45], v[190:191], v[222:223]
	v_pk_fma_f32 v[42:43], v[42:43], v[196:197], v[228:229]
	v_pk_fma_f32 v[40:41], v[40:41], v[194:195], v[226:227]
	v_pk_fma_f32 v[38:39], v[38:39], v[200:201], v[232:233]
	v_pk_fma_f32 v[36:37], v[36:37], v[198:199], v[230:231]
	v_pk_fma_f32 v[34:35], v[34:35], v[204:205], v[236:237]
	v_pk_fma_f32 v[32:33], v[32:33], v[202:203], v[234:235]
	global_store_dwordx4 v[246:247], v[44:47], off
	global_store_dwordx4 v[246:247], v[40:43], off offset:64
	global_store_dwordx4 v[246:247], v[36:39], off offset:512
	global_store_dwordx4 v[246:247], v[32:35], off offset:576
	v_add_u32_e32 v156, 0xb0, v158
	v_lshlrev_b64 v[160:161], 13, v[156:157]
	v_lshl_add_u64 v[244:245], v[160:161], 0, v[162:163]
	global_load_dwordx4 v[222:225], v[244:245], off
	global_load_dwordx4 v[226:229], v[244:245], off offset:64
	global_load_dwordx4 v[230:233], v[244:245], off offset:512
	global_load_dwordx4 v[234:237], v[244:245], off offset:576
	v_add_u32_e32 v156, 0xa0, v158
	v_lshlrev_b64 v[160:161], 13, v[156:157]
	v_lshl_add_u64 v[246:247], v[160:161], 0, v[164:165]
	s_waitcnt vmcnt(4)
	v_pk_fma_f32 v[30:31], v[30:31], v[192:193], v[208:209]
	v_pk_fma_f32 v[28:29], v[28:29], v[190:191], v[206:207]
	v_pk_fma_f32 v[26:27], v[26:27], v[196:197], v[212:213]
	v_pk_fma_f32 v[24:25], v[24:25], v[194:195], v[210:211]
	v_pk_fma_f32 v[22:23], v[22:23], v[200:201], v[216:217]
	v_pk_fma_f32 v[20:21], v[20:21], v[198:199], v[214:215]
	v_pk_fma_f32 v[18:19], v[18:19], v[204:205], v[220:221]
	v_pk_fma_f32 v[16:17], v[16:17], v[202:203], v[218:219]
	global_store_dwordx4 v[246:247], v[28:31], off
	global_store_dwordx4 v[246:247], v[24:27], off offset:64
	global_store_dwordx4 v[246:247], v[20:23], off offset:512
	global_store_dwordx4 v[246:247], v[16:19], off offset:576
	v_add_u32_e32 v156, 0xb0, v158
	v_lshlrev_b64 v[160:161], 13, v[156:157]
	v_lshl_add_u64 v[246:247], v[160:161], 0, v[164:165]
	s_waitcnt vmcnt(0)
	v_pk_fma_f32 v[14:15], v[14:15], v[192:193], v[224:225]
	v_pk_fma_f32 v[12:13], v[12:13], v[190:191], v[222:223]
	v_pk_fma_f32 v[10:11], v[10:11], v[196:197], v[228:229]
	v_pk_fma_f32 v[8:9], v[8:9], v[194:195], v[226:227]
	v_pk_fma_f32 v[6:7], v[6:7], v[200:201], v[232:233]
	v_pk_fma_f32 v[4:5], v[4:5], v[198:199], v[230:231]
	v_pk_fma_f32 v[2:3], v[2:3], v[204:205], v[236:237]
	v_pk_fma_f32 v[0:1], v[0:1], v[202:203], v[234:235]
	global_store_dwordx4 v[246:247], v[12:15], off
	global_store_dwordx4 v[246:247], v[8:11], off offset:64
	global_store_dwordx4 v[246:247], v[4:7], off offset:512
	global_store_dwordx4 v[246:247], v[0:3], off offset:576
	s_and_b64 vcc, exec, s[38:39]
	s_cbranch_vccz .LBB0_78
	s_waitcnt vmcnt(0)
	v_readlane_b32 s70, v238, 38
	v_readlane_b32 s64, v238, 52
	s_cmpk_gt_u32 s54, 0xff
	v_readlane_b32 s71, v238, 39
	s_movk_i32 s75, 0x3000
	s_movk_i32 s78, 0x2000
	v_readlane_b32 s65, v238, 53
	s_cbranch_scc1 .LBB0_85
	s_barrier

; #define G_STAGE(bufoff, gbase, voff) do { _Pragma("unroll") for (int _i = 0; _i < 2; ++_i) \
;     __builtin_amdgcn_global_load_lds((const unsigned*)((const char*)(gbase) + (voff)[_i]), (LAS unsigned*)(lds + (bufoff) + ldsw + _i * 8192), 16, 0, 0); } while (0)
; #define G_LDA(dst, b, h) do { _Pragma("unroll") for (int m = 0; m < 4; ++m) _Pragma("unroll") for (int k = 0; k < 2; ++k) dst[m][k] = *(const LAS bf16x8*)(lds + G_SA(b, h) + aoff + m * 2048 + k * 1024); } while (0)
; #define G_LDB(dst, b, h) do { _Pragma("unroll") for (int n = 0; n < 2; ++n) _Pragma("unroll") for (int k = 0; k < 2; ++k) dst[n][k] = *(const LAS bf16x8*)(lds + G_SB(b, h) + boff + n * 2048 + k * 1024); } while (0)
; #define G_WAIT_V(n) asm volatile("s_waitcnt vmcnt(" #n ")" ::: "memory")
; #define G_WAIT_L(n) asm volatile("s_waitcnt lgkmcnt(" #n ")" ::: "memory")
; #define G_BAR __builtin_amdgcn_s_barrier()
; template <class Epi>
; __device__ __forceinline__ void gemm_phase(LAS unsigned char* lds, const u16* gA, const u16* gBt, int M, int N, int K, const Epi& E) {
;     ...
;     for (int t = 0; t < nt; t += 2) {
;       const bool last = (t == nt - 2);
;       const char* a1 = cA + (size_t)(t + 1) * kstep;
;       const char* a2 = last ? nA : cA + (size_t)(t + 2) * kstep; const char* b2 = last ? nB : cB + (size_t)(t + 2) * kstep;
;       const char* a3 = a2 + kstep; const char* b3 = b2 + kstep;
;       G_LDB(B0, 0, 0); G_SCHED; G_LDA(At, 0, 0); G_STAGE(G_SA(1, 1), a1 + hstep, voffA);
;       G_WAIT_L(8); G_BAR; G_WAIT_L(0); G_MMA(0, 0, At, B0); G_BAR; G_SCHED;
;       G_LDB(B1, 0, 1); G_STAGE(G_SB(0, 0), b2, voffB);
;       G_BAR; G_WAIT_L(0); G_MMA(0, 1, At, B1); G_BAR;
;       G_LDA(At, 0, 1); G_STAGE(G_SA(0, 0), a2, voffA);
;       G_BAR; G_WAIT_L(0); G_MMA(1, 0, At, B0); G_BAR; G_SCHED;
;       G_STAGE(G_SB(0, 1), b2 + hstep, voffB);
;       G_WAIT_V(6); G_BAR; G_MMA(1, 1, At, B1); G_BAR;
;       G_LDB(B0, 1, 0); G_SCHED; G_LDA(At, 1, 0); G_STAGE(G_SA(0, 1), a2 + hstep, voffA);
;       G_WAIT_L(8); G_BAR; G_WAIT_L(0); G_MMA(0, 0, At, B0); G_BAR; G_SCHED;
;       G_LDB(B1, 1, 1); G_STAGE(G_SB(1, 0), b3, voffB);
;       G_BAR; G_WAIT_L(0); G_MMA(0, 1, At, B1); G_BAR;
;       G_LDA(At, 1, 1); G_STAGE(G_SA(1, 0), a3, voffA);
;       G_BAR; G_WAIT_L(0); G_MMA(1, 0, At, B0); G_BAR; G_SCHED;
;       G_STAGE(G_SB(1, 1), b3 + hstep, voffB);
;       G_WAIT_V(6); G_BAR; G_MMA(1, 1, At, B1); G_BAR;
.LBB0_370:
	s_add_u32 s20, s42, 0xfff80080
	s_addc_u32 s22, s43, -1
	s_add_i32 s24, 0, 0x10000
	v_add_u32_e32 v156, s24, v145
	ds_read_b128 v[140:143], v156
	ds_read_b128 v[148:151], v156 offset:1024
	ds_read_b128 v[152:155], v156 offset:2048
	ds_read_b128 v[156:159], v156 offset:3072
	s_cmp_eq_u32 s58, 28
	s_cselect_b32 s47, s3, s22
	s_cselect_b32 s46, s54, s20
	s_cselect_b32 s45, s1, s57
	s_cselect_b32 s44, s55, s56
	v_lshl_add_u64 v[214:215], s[42:43], 0, v[136:137]
	s_add_i32 m0, s27, 0xc000
	ds_read_b128 v[160:163], v147
	ds_read_b128 v[164:167], v147 offset:1024
	ds_read_b128 v[190:193], v147 offset:2048
	ds_read_b128 v[194:197], v147 offset:3072
	ds_read_b128 v[198:201], v147 offset:4096
	ds_read_b128 v[202:205], v147 offset:5120
	ds_read_b128 v[206:209], v147 offset:6144
	ds_read_b128 v[210:213], v147 offset:7168
	global_load_lds_dwordx4 v[214:215], off
	v_lshl_add_u64 v[214:215], s[42:43], 0, v[138:139]
	s_add_i32 m0, s27, 0xe000
	s_nop 0
	global_load_lds_dwordx4 v[214:215], off
	s_waitcnt lgkmcnt(8)
	s_barrier
	s_waitcnt lgkmcnt(0)
	s_setprio 1
	s_waitcnt lgkmcnt(0)
	v_mfma_f32_16x16x32_bf16 v[124:127], v[140:143], v[160:163], v[124:127]
	v_mfma_f32_16x16x32_bf16 v[120:123], v[152:155], v[160:163], v[120:123]
	v_mfma_f32_16x16x32_bf16 v[112:115], v[140:143], v[190:193], v[112:115]
	v_mfma_f32_16x16x32_bf16 v[104:107], v[152:155], v[190:193], v[104:107]
	v_mfma_f32_16x16x32_bf16 v[96:99], v[140:143], v[198:201], v[96:99]
	v_mfma_f32_16x16x32_bf16 v[88:91], v[152:155], v[198:201], v[88:91]
	v_mfma_f32_16x16x32_bf16 v[80:83], v[140:143], v[206:209], v[80:83]
	v_mfma_f32_16x16x32_bf16 v[72:75], v[152:155], v[206:209], v[72:75]
	v_mfma_f32_16x16x32_bf16 v[124:127], v[148:151], v[164:167], v[124:127]
	v_mfma_f32_16x16x32_bf16 v[120:123], v[156:159], v[164:167], v[120:123]
	v_mfma_f32_16x16x32_bf16 v[112:115], v[148:151], v[194:197], v[112:115]
	v_mfma_f32_16x16x32_bf16 v[104:107], v[156:159], v[194:197], v[104:107]
	v_mfma_f32_16x16x32_bf16 v[96:99], v[148:151], v[202:205], v[96:99]
	v_mfma_f32_16x16x32_bf16 v[88:91], v[156:159], v[202:205], v[88:91]
	v_mfma_f32_16x16x32_bf16 v[80:83], v[148:151], v[210:213], v[80:83]
	v_mfma_f32_16x16x32_bf16 v[72:75], v[156:159], v[210:213], v[72:75]
	s_setprio 0
	s_add_i32 s20, 0, 0x14000
	s_add_i32 s22, s24, s26
	v_add_u32_e32 v226, s20, v145
	v_lshl_add_u64 v[230:231], s[44:45], 0, v[128:129]
	s_mov_b32 m0, s22
	s_barrier
	ds_read_b128 v[214:217], v226
	ds_read_b128 v[218:221], v226 offset:1024
	ds_read_b128 v[222:225], v226 offset:2048
	ds_read_b128 v[226:229], v226 offset:3072
	global_load_lds_dwordx4 v[230:231], off
	v_lshl_add_u64 v[232:233], s[44:45], 0, v[134:135]
	s_add_i32 m0, s22, 0x2000
	s_nop 0
	global_load_lds_dwordx4 v[232:233], off
	s_barrier
	s_waitcnt lgkmcnt(0)
	s_setprio 1
	s_waitcnt lgkmcnt(0)
	v_mfma_f32_16x16x32_bf16 v[116:119], v[214:217], v[160:163], v[116:119]
	v_mfma_f32_16x16x32_bf16 v[108:111], v[222:225], v[160:163], v[108:111]
	v_mfma_f32_16x16x32_bf16 v[100:103], v[214:217], v[190:193], v[100:103]
	v_mfma_f32_16x16x32_bf16 v[92:95], v[222:225], v[190:193], v[92:95]
	v_mfma_f32_16x16x32_bf16 v[84:87], v[214:217], v[198:201], v[84:87]
	v_mfma_f32_16x16x32_bf16 v[76:79], v[222:225], v[198:201], v[76:79]
	v_mfma_f32_16x16x32_bf16 v[68:71], v[214:217], v[206:209], v[68:71]
	v_mfma_f32_16x16x32_bf16 v[64:67], v[222:225], v[206:209], v[64:67]
	v_mfma_f32_16x16x32_bf16 v[116:119], v[218:221], v[164:167], v[116:119]
	v_mfma_f32_16x16x32_bf16 v[108:111], v[226:229], v[164:167], v[108:111]
	v_mfma_f32_16x16x32_bf16 v[100:103], v[218:221], v[194:197], v[100:103]
	v_mfma_f32_16x16x32_bf16 v[92:95], v[226:229], v[194:197], v[92:95]
	v_mfma_f32_16x16x32_bf16 v[84:87], v[218:221], v[202:205], v[84:87]
	v_mfma_f32_16x16x32_bf16 v[76:79], v[226:229], v[202:205], v[76:79]
	v_mfma_f32_16x16x32_bf16 v[68:71], v[218:221], v[210:213], v[68:71]
	v_mfma_f32_16x16x32_bf16 v[64:67], v[226:229], v[210:213], v[64:67]
	s_setprio 0
	s_mov_b32 m0, s27
	v_lshl_add_u64 v[234:235], s[46:47], 0, v[128:129]
	s_barrier
	ds_read_b128 v[160:163], v147 offset:16384
	ds_read_b128 v[164:167], v147 offset:17408
	ds_read_b128 v[190:193], v147 offset:18432
	ds_read_b128 v[194:197], v147 offset:19456
	ds_read_b128 v[198:201], v147 offset:20480
	ds_read_b128 v[202:205], v147 offset:21504
	ds_read_b128 v[206:209], v147 offset:22528
	ds_read_b128 v[210:213], v147 offset:23552
	global_load_lds_dwordx4 v[234:235], off
	v_lshl_add_u64 v[236:237], s[46:47], 0, v[134:135]
	s_mov_b32 m0, s28
	s_nop 0
	global_load_lds_dwordx4 v[236:237], off
	s_barrier
	s_waitcnt lgkmcnt(0)
	s_setprio 1
	s_waitcnt lgkmcnt(0)
	v_mfma_f32_16x16x32_bf16 v[60:63], v[140:143], v[160:163], v[60:63]
	v_mfma_f32_16x16x32_bf16 v[56:59], v[152:155], v[160:163], v[56:59]
	v_mfma_f32_16x16x32_bf16 v[48:51], v[140:143], v[190:193], v[48:51]
	v_mfma_f32_16x16x32_bf16 v[40:43], v[152:155], v[190:193], v[40:43]
	v_mfma_f32_16x16x32_bf16 v[32:35], v[140:143], v[198:201], v[32:35]
	v_mfma_f32_16x16x32_bf16 v[24:27], v[152:155], v[198:201], v[24:27]
	v_mfma_f32_16x16x32_bf16 v[16:19], v[140:143], v[206:209], v[16:19]
	v_mfma_f32_16x16x32_bf16 v[8:11], v[152:155], v[206:209], v[8:11]
	v_mfma_f32_16x16x32_bf16 v[60:63], v[148:151], v[164:167], v[60:63]
	v_mfma_f32_16x16x32_bf16 v[56:59], v[156:159], v[164:167], v[56:59]
	v_mfma_f32_16x16x32_bf16 v[48:51], v[148:151], v[194:197], v[48:51]
	v_mfma_f32_16x16x32_bf16 v[40:43], v[156:159], v[194:197], v[40:43]
	v_mfma_f32_16x16x32_bf16 v[32:35], v[148:151], v[202:205], v[32:35]
	v_mfma_f32_16x16x32_bf16 v[24:27], v[156:159], v[202:205], v[24:27]
	v_mfma_f32_16x16x32_bf16 v[16:19], v[148:151], v[210:213], v[16:19]
	v_mfma_f32_16x16x32_bf16 v[8:11], v[156:159], v[210:213], v[8:11]
	s_setprio 0
	s_add_u32 s24, s44, 0x80000
	s_addc_u32 s25, s45, 0
	s_add_i32 s20, s20, s26
	v_lshl_add_u64 v[140:141], s[24:25], 0, v[128:129]
	s_mov_b32 m0, s20
	s_barrier
; #define G_STAGE(bufoff, gbase, voff) do { _Pragma("unroll") for (int _i = 0; _i < 2; ++_i) \
;     __builtin_amdgcn_global_load_lds((const unsigned*)((const char*)(gbase) + (voff)[_i]), (LAS unsigned*)(lds + (bufoff) + ldsw + _i * 8192), 16, 0, 0); } while (0)
; #define G_LDA(dst, b, h) do { _Pragma("unroll") for (int m = 0; m < 4; ++m) _Pragma("unroll") for (int k = 0; k < 2; ++k) dst[m][k] = *(const LAS bf16x8*)(lds + G_SA(b, h) + aoff + m * 2048 + k * 1024); } while (0)
; #define G_LDB(dst, b, h) do { _Pragma("unroll") for (int n = 0; n < 2; ++n) _Pragma("unroll") for (int k = 0; k < 2; ++k) dst[n][k] = *(const LAS bf16x8*)(lds + G_SB(b, h) + boff + n * 2048 + k * 1024); } while (0)
; #define G_MMA(ai, bj, At, Bt) do { __builtin_amdgcn_s_setprio(1); _Pragma("unroll") for (int m = 0; m < 4; ++m) _Pragma("unroll") for (int n = 0; n < 2; ++n) _Pragma("unroll") for (int k = 0; k < 2; ++k) \
;     acc[ai][bj][m][n] = __builtin_amdgcn_mfma_f32_16x16x32_bf16(Bt[n][k], At[m][k], acc[ai][bj][m][n], 0, 0, 0); __builtin_amdgcn_s_setprio(0); } while (0)
; #define G_WAIT_V(n) asm volatile("s_waitcnt vmcnt(" #n ")" ::: "memory")
; #define G_WAIT_L(n) asm volatile("s_waitcnt lgkmcnt(" #n ")" ::: "memory")
; template <class Epi>
; __device__ __forceinline__ void gemm_phase(LAS unsigned char* lds, const u16* gA, const u16* gBt, int M, int N, int K, const Epi& E) {
;     ...
;       G_LDB(B0, 0, 0); G_SCHED; G_LDA(At, 0, 0); G_STAGE(G_SA(1, 1), a1 + hstep, voffA);
;       G_WAIT_L(8); G_BAR; G_WAIT_L(0); G_MMA(0, 0, At, B0); G_BAR; G_SCHED;
;       G_LDB(B1, 0, 1); G_STAGE(G_SB(0, 0), b2, voffB);
;       G_BAR; G_WAIT_L(0); G_MMA(0, 1, At, B1); G_BAR;
;       G_LDA(At, 0, 1); G_STAGE(G_SA(0, 0), a2, voffA);
;       G_BAR; G_WAIT_L(0); G_MMA(1, 0, At, B0); G_BAR; G_SCHED;
;       G_STAGE(G_SB(0, 1), b2 + hstep, voffB);
;       G_WAIT_V(6); G_BAR; G_MMA(1, 1, At, B1); G_BAR;
;       G_LDB(B0, 1, 0); G_SCHED; G_LDA(At, 1, 0); G_STAGE(G_SA(0, 1), a2 + hstep, voffA);
;       G_WAIT_L(8); G_BAR; G_WAIT_L(0); G_MMA(0, 0, At, B0); G_BAR; G_SCHED;
;       G_LDB(B1, 1, 1); G_STAGE(G_SB(1, 0), b3, voffB);
;       G_BAR; G_WAIT_L(0); G_MMA(0, 1, At, B1); G_BAR;
;       G_LDA(At, 1, 1); G_STAGE(G_SA(1, 0), a3, voffA);
;       G_BAR; G_WAIT_L(0); G_MMA(1, 0, At, B0); G_BAR; G_SCHED;
;       G_STAGE(G_SB(1, 1), b3 + hstep, voffB);
;       G_WAIT_V(6); G_BAR; G_MMA(1, 1, At, B1); G_BAR;
	s_nop 0
	global_load_lds_dwordx4 v[140:141], off
	v_lshl_add_u64 v[140:141], s[24:25], 0, v[134:135]
	s_add_i32 m0, s20, 0x2000
	s_nop 0
	global_load_lds_dwordx4 v[140:141], off
	s_waitcnt vmcnt(6)
	s_barrier
	s_setprio 1
	v_mfma_f32_16x16x32_bf16 v[52:55], v[214:217], v[160:163], v[52:55]
	v_mfma_f32_16x16x32_bf16 v[44:47], v[222:225], v[160:163], v[44:47]
	v_mfma_f32_16x16x32_bf16 v[36:39], v[214:217], v[190:193], v[36:39]
	v_mfma_f32_16x16x32_bf16 v[28:31], v[222:225], v[190:193], v[28:31]
	v_mfma_f32_16x16x32_bf16 v[20:23], v[214:217], v[198:201], v[20:23]
	v_mfma_f32_16x16x32_bf16 v[12:15], v[222:225], v[198:201], v[12:15]
	v_mfma_f32_16x16x32_bf16 v[4:7], v[214:217], v[206:209], v[4:7]
	v_mfma_f32_16x16x32_bf16 v[0:3], v[222:225], v[206:209], v[0:3]
	v_mfma_f32_16x16x32_bf16 v[52:55], v[218:221], v[164:167], v[52:55]
	v_mfma_f32_16x16x32_bf16 v[44:47], v[226:229], v[164:167], v[44:47]
	v_mfma_f32_16x16x32_bf16 v[36:39], v[218:221], v[194:197], v[36:39]
	v_mfma_f32_16x16x32_bf16 v[28:31], v[226:229], v[194:197], v[28:31]
	v_mfma_f32_16x16x32_bf16 v[20:23], v[218:221], v[202:205], v[20:23]
	v_mfma_f32_16x16x32_bf16 v[12:15], v[226:229], v[202:205], v[12:15]
	v_mfma_f32_16x16x32_bf16 v[4:7], v[218:221], v[210:213], v[4:7]
	v_mfma_f32_16x16x32_bf16 v[0:3], v[226:229], v[210:213], v[0:3]
	s_setprio 0
	s_add_i32 s20, 0, 0x18000
	v_add_u32_e32 v156, s20, v145
	s_barrier
	ds_read_b128 v[140:143], v156
	ds_read_b128 v[148:151], v156 offset:1024
	ds_read_b128 v[152:155], v156 offset:2048
	ds_read_b128 v[156:159], v156 offset:3072
	s_add_u32 s24, s46, 0x80000
	s_addc_u32 s25, s47, 0
	s_mov_b32 m0, s33
	v_lshl_add_u64 v[214:215], s[24:25], 0, v[128:129]
	ds_read_b128 v[160:163], v147 offset:32768
	ds_read_b128 v[164:167], v147 offset:33792
	ds_read_b128 v[190:193], v147 offset:34816
	ds_read_b128 v[194:197], v147 offset:35840
	ds_read_b128 v[198:201], v147 offset:36864
	ds_read_b128 v[202:205], v147 offset:37888
	ds_read_b128 v[206:209], v147 offset:38912
	ds_read_b128 v[210:213], v147 offset:39936
	global_load_lds_dwordx4 v[214:215], off
	v_lshl_add_u64 v[214:215], s[24:25], 0, v[134:135]
	s_mov_b32 m0, s48
	s_nop 0
	global_load_lds_dwordx4 v[214:215], off
	s_waitcnt lgkmcnt(8)
	s_barrier
	s_waitcnt lgkmcnt(0)
	s_setprio 1
	s_waitcnt lgkmcnt(0)
	v_mfma_f32_16x16x32_bf16 v[124:127], v[140:143], v[160:163], v[124:127]
	v_mfma_f32_16x16x32_bf16 v[120:123], v[152:155], v[160:163], v[120:123]
	v_mfma_f32_16x16x32_bf16 v[112:115], v[140:143], v[190:193], v[112:115]
	v_mfma_f32_16x16x32_bf16 v[104:107], v[152:155], v[190:193], v[104:107]
	v_mfma_f32_16x16x32_bf16 v[96:99], v[140:143], v[198:201], v[96:99]
	v_mfma_f32_16x16x32_bf16 v[88:91], v[152:155], v[198:201], v[88:91]
	v_mfma_f32_16x16x32_bf16 v[80:83], v[140:143], v[206:209], v[80:83]
	v_mfma_f32_16x16x32_bf16 v[72:75], v[152:155], v[206:209], v[72:75]
	v_mfma_f32_16x16x32_bf16 v[124:127], v[148:151], v[164:167], v[124:127]
	v_mfma_f32_16x16x32_bf16 v[120:123], v[156:159], v[164:167], v[120:123]
	v_mfma_f32_16x16x32_bf16 v[112:115], v[148:151], v[194:197], v[112:115]
	v_mfma_f32_16x16x32_bf16 v[104:107], v[156:159], v[194:197], v[104:107]
	v_mfma_f32_16x16x32_bf16 v[96:99], v[148:151], v[202:205], v[96:99]
	v_mfma_f32_16x16x32_bf16 v[88:91], v[156:159], v[202:205], v[88:91]
	v_mfma_f32_16x16x32_bf16 v[80:83], v[148:151], v[210:213], v[80:83]
	v_mfma_f32_16x16x32_bf16 v[72:75], v[156:159], v[210:213], v[72:75]
	s_setprio 0
	s_add_i32 s22, 0, 0x1c000
	s_add_i32 s20, s20, s26
	v_add_u32_e32 v226, s22, v145
	v_lshl_add_u64 v[230:231], v[230:231], 0, s[34:35]
	s_mov_b32 m0, s20
	s_barrier
	ds_read_b128 v[214:217], v226
	ds_read_b128 v[218:221], v226 offset:1024
	ds_read_b128 v[222:225], v226 offset:2048
	ds_read_b128 v[226:229], v226 offset:3072
	global_load_lds_dwordx4 v[230:231], off
	v_lshl_add_u64 v[230:231], v[232:233], 0, s[34:35]
	s_add_i32 m0, s20, 0x2000
	s_nop 0
	global_load_lds_dwordx4 v[230:231], off
	s_barrier
	s_waitcnt lgkmcnt(0)
	s_setprio 1
	s_waitcnt lgkmcnt(0)
	v_mfma_f32_16x16x32_bf16 v[116:119], v[214:217], v[160:163], v[116:119]
	v_mfma_f32_16x16x32_bf16 v[108:111], v[222:225], v[160:163], v[108:111]
	v_mfma_f32_16x16x32_bf16 v[100:103], v[214:217], v[190:193], v[100:103]
	v_mfma_f32_16x16x32_bf16 v[92:95], v[222:225], v[190:193], v[92:95]
	v_mfma_f32_16x16x32_bf16 v[84:87], v[214:217], v[198:201], v[84:87]
	v_mfma_f32_16x16x32_bf16 v[76:79], v[222:225], v[198:201], v[76:79]
	v_mfma_f32_16x16x32_bf16 v[68:71], v[214:217], v[206:209], v[68:71]
	v_mfma_f32_16x16x32_bf16 v[64:67], v[222:225], v[206:209], v[64:67]
	v_mfma_f32_16x16x32_bf16 v[116:119], v[218:221], v[164:167], v[116:119]
	v_mfma_f32_16x16x32_bf16 v[108:111], v[226:229], v[164:167], v[108:111]
	v_mfma_f32_16x16x32_bf16 v[100:103], v[218:221], v[194:197], v[100:103]
	v_mfma_f32_16x16x32_bf16 v[92:95], v[226:229], v[194:197], v[92:95]
	v_mfma_f32_16x16x32_bf16 v[84:87], v[218:221], v[202:205], v[84:87]
	v_mfma_f32_16x16x32_bf16 v[76:79], v[226:229], v[202:205], v[76:79]
	v_mfma_f32_16x16x32_bf16 v[68:71], v[218:221], v[210:213], v[68:71]
	v_mfma_f32_16x16x32_bf16 v[64:67], v[226:229], v[210:213], v[64:67]
	s_setprio 0
	s_mov_b32 m0, s50
	v_lshl_add_u64 v[230:231], v[234:235], 0, s[34:35]
	s_barrier
	ds_read_b128 v[160:163], v147 offset:49152
	ds_read_b128 v[164:167], v147 offset:50176
	ds_read_b128 v[190:193], v147 offset:51200
	ds_read_b128 v[194:197], v147 offset:52224
	ds_read_b128 v[198:201], v147 offset:53248
	ds_read_b128 v[202:205], v147 offset:54272
	ds_read_b128 v[206:209], v147 offset:55296
	ds_read_b128 v[210:213], v147 offset:56320
	global_load_lds_dwordx4 v[230:231], off
	v_lshl_add_u64 v[230:231], v[236:237], 0, s[34:35]
	s_mov_b32 m0, s51
	s_nop 0
	global_load_lds_dwordx4 v[230:231], off
	s_barrier
; #define G_STAGE(bufoff, gbase, voff) do { _Pragma("unroll") for (int _i = 0; _i < 2; ++_i) \
;     __builtin_amdgcn_global_load_lds((const unsigned*)((const char*)(gbase) + (voff)[_i]), (LAS unsigned*)(lds + (bufoff) + ldsw + _i * 8192), 16, 0, 0); } while (0)
; #define G_LDA(dst, b, h) do { _Pragma("unroll") for (int m = 0; m < 4; ++m) _Pragma("unroll") for (int k = 0; k < 2; ++k) dst[m][k] = *(const LAS bf16x8*)(lds + G_SA(b, h) + aoff + m * 2048 + k * 1024); } while (0)
; #define G_LDB(dst, b, h) do { _Pragma("unroll") for (int n = 0; n < 2; ++n) _Pragma("unroll") for (int k = 0; k < 2; ++k) dst[n][k] = *(const LAS bf16x8*)(lds + G_SB(b, h) + boff + n * 2048 + k * 1024); } while (0)
; #define G_MMA(ai, bj, At, Bt) do { __builtin_amdgcn_s_setprio(1); _Pragma("unroll") for (int m = 0; m < 4; ++m) _Pragma("unroll") for (int n = 0; n < 2; ++n) _Pragma("unroll") for (int k = 0; k < 2; ++k) \
;     acc[ai][bj][m][n] = __builtin_amdgcn_mfma_f32_16x16x32_bf16(Bt[n][k], At[m][k], acc[ai][bj][m][n], 0, 0, 0); __builtin_amdgcn_s_setprio(0); } while (0)
; #define G_WAIT_V(n) asm volatile("s_waitcnt vmcnt(" #n ")" ::: "memory")
; #define G_WAIT_L(n) asm volatile("s_waitcnt lgkmcnt(" #n ")" ::: "memory")
; #define G_BAR __builtin_amdgcn_s_barrier()
; #define G_SCHED __builtin_amdgcn_sched_barrier(0)
; template <class Epi>
; __device__ __forceinline__ void gemm_phase(LAS unsigned char* lds, const u16* gA, const u16* gBt, int M, int N, int K, const Epi& E) {
;     ...
;       G_WAIT_V(6); G_BAR; G_MMA(1, 1, At, B1); G_BAR;
;       G_LDB(B0, 1, 0); G_SCHED; G_LDA(At, 1, 0); G_STAGE(G_SA(0, 1), a2 + hstep, voffA);
;       G_WAIT_L(8); G_BAR; G_WAIT_L(0); G_MMA(0, 0, At, B0); G_BAR; G_SCHED;
;       G_LDB(B1, 1, 1); G_STAGE(G_SB(1, 0), b3, voffB);
;       G_BAR; G_WAIT_L(0); G_MMA(0, 1, At, B1); G_BAR;
;       G_LDA(At, 1, 1); G_STAGE(G_SA(1, 0), a3, voffA);
;       G_BAR; G_WAIT_L(0); G_MMA(1, 0, At, B0); G_BAR; G_SCHED;
;       G_STAGE(G_SB(1, 1), b3 + hstep, voffB);
;       G_WAIT_V(6); G_BAR; G_MMA(1, 1, At, B1); G_BAR;
	s_waitcnt lgkmcnt(0)
	s_setprio 1
	s_waitcnt lgkmcnt(0)
	v_mfma_f32_16x16x32_bf16 v[60:63], v[140:143], v[160:163], v[60:63]
	v_mfma_f32_16x16x32_bf16 v[56:59], v[152:155], v[160:163], v[56:59]
	v_mfma_f32_16x16x32_bf16 v[48:51], v[140:143], v[190:193], v[48:51]
	v_mfma_f32_16x16x32_bf16 v[40:43], v[152:155], v[190:193], v[40:43]
	v_mfma_f32_16x16x32_bf16 v[32:35], v[140:143], v[198:201], v[32:35]
	v_mfma_f32_16x16x32_bf16 v[24:27], v[152:155], v[198:201], v[24:27]
	v_mfma_f32_16x16x32_bf16 v[16:19], v[140:143], v[206:209], v[16:19]
	v_mfma_f32_16x16x32_bf16 v[8:11], v[152:155], v[206:209], v[8:11]
	v_mfma_f32_16x16x32_bf16 v[60:63], v[148:151], v[164:167], v[60:63]
	v_mfma_f32_16x16x32_bf16 v[56:59], v[156:159], v[164:167], v[56:59]
	v_mfma_f32_16x16x32_bf16 v[48:51], v[148:151], v[194:197], v[48:51]
	v_mfma_f32_16x16x32_bf16 v[40:43], v[156:159], v[194:197], v[40:43]
	v_mfma_f32_16x16x32_bf16 v[32:35], v[148:151], v[202:205], v[32:35]
	v_mfma_f32_16x16x32_bf16 v[24:27], v[156:159], v[202:205], v[24:27]
	v_mfma_f32_16x16x32_bf16 v[16:19], v[148:151], v[210:213], v[16:19]
	v_mfma_f32_16x16x32_bf16 v[8:11], v[156:159], v[210:213], v[8:11]
	s_setprio 0
	s_add_u32 s24, s44, 0x80080
	s_addc_u32 s25, s45, 0
	s_add_i32 s20, s22, s26
	v_lshl_add_u64 v[140:141], s[24:25], 0, v[128:129]
	s_mov_b32 m0, s20
	s_barrier
	s_nop 0
	global_load_lds_dwordx4 v[140:141], off
	v_lshl_add_u64 v[140:141], s[24:25], 0, v[134:135]
	s_add_i32 m0, s20, 0x2000
	s_nop 0
	global_load_lds_dwordx4 v[140:141], off
	s_waitcnt vmcnt(6)
	s_barrier
	s_setprio 1
	v_mfma_f32_16x16x32_bf16 v[52:55], v[214:217], v[160:163], v[52:55]
	v_mfma_f32_16x16x32_bf16 v[44:47], v[222:225], v[160:163], v[44:47]
	v_mfma_f32_16x16x32_bf16 v[36:39], v[214:217], v[190:193], v[36:39]
	v_mfma_f32_16x16x32_bf16 v[28:31], v[222:225], v[190:193], v[28:31]
	v_mfma_f32_16x16x32_bf16 v[20:23], v[214:217], v[198:201], v[20:23]
	v_mfma_f32_16x16x32_bf16 v[12:15], v[222:225], v[198:201], v[12:15]
	v_mfma_f32_16x16x32_bf16 v[4:7], v[214:217], v[206:209], v[4:7]
	v_mfma_f32_16x16x32_bf16 v[0:3], v[222:225], v[206:209], v[0:3]
	v_mfma_f32_16x16x32_bf16 v[52:55], v[218:221], v[164:167], v[52:55]
	v_mfma_f32_16x16x32_bf16 v[44:47], v[226:229], v[164:167], v[44:47]
	v_mfma_f32_16x16x32_bf16 v[36:39], v[218:221], v[194:197], v[36:39]
	v_mfma_f32_16x16x32_bf16 v[28:31], v[226:229], v[194:197], v[28:31]
	v_mfma_f32_16x16x32_bf16 v[20:23], v[218:221], v[202:205], v[20:23]
	v_mfma_f32_16x16x32_bf16 v[12:15], v[226:229], v[202:205], v[12:15]
	v_mfma_f32_16x16x32_bf16 v[4:7], v[218:221], v[210:213], v[4:7]
	v_mfma_f32_16x16x32_bf16 v[0:3], v[226:229], v[210:213], v[0:3]
	s_setprio 0
	s_add_i32 s58, s58, 2
	s_add_u32 s42, s42, 0x100
	s_addc_u32 s43, s43, 0
	s_add_u32 s56, s56, 0x100
	s_addc_u32 s57, s57, 0
	s_cmp_gt_u32 s58, 29
	s_barrier
	s_cbranch_scc0 .LBB0_370
; __device__ __forceinline__ unsigned pk_bf16(float lo, float hi) { return (unsigned)f2bf(lo) | ((unsigned)f2bf(hi) << 16); }
;   __device__ __forceinline__ void operator()(const f32x4 (&acc)[2][2][4][2], const Unit& u, int wr, int wc, int fr, int fq) const {
;     const int row0 = u.pm * BM + wr * 64 + fr, col0 = u.pn * BM + wc * 32 + 4 * fq;
; #pragma unroll
;     for (int ai = 0; ai < 2; ++ai)
; #pragma unroll
;       for (int m = 0; m < 4; ++m) {
;         u16* rowp = O + (size_t)(row0 + ai * HALF + m * 16) * PROJP + col0;
; #pragma unroll
;         for (int bj = 0; bj < 2; ++bj)
; #pragma unroll
;           for (int n = 0; n < 2; ++n) {
;             f32x4 v = acc[ai][bj][m][n];
;             uint2 w; w.x = pk_bf16(v[0], v[1]); w.y = pk_bf16(v[2], v[3]);
;             *reinterpret_cast<uint2*>(rowp + bj * HALF + n * 16) = w;
;           }
;       }
;   }
; template <class Epi>
; __device__ __forceinline__ void gemm_phase(LAS unsigned char* lds, const u16* gA, const u16* gBt, int M, int N, int K, const Epi& E) {
;     ...
;     E(acc, cur, wr, wc, fr, fq);
;     if (!has_next) break;
	v_lshl_or_b32 v142, s30, 8, v146
	v_lshl_add_u32 v150, s31, 8, v144
	v_bfe_u32 v151, v168, 4, 1
	v_mul_u32_u24_e32 v151, 12, v151
	v_add_u32_e32 v142, v142, v151
	v_ashrrev_i32_e32 v143, 31, v142
	v_mov_b64_e32 v[140:141], s[94:95]
	s_movk_i32 s1, 0x3600
	v_lshlrev_b64 v[142:143], 1, v[142:143]
	v_mad_i64_i32 v[148:149], s[24:25], v150, s1, v[140:141]
	v_lshl_add_u64 v[148:149], v[148:149], 0, v[142:143]
	v_cvt_pk_bf16_f32 v124, v124, v125
	v_cvt_pk_bf16_f32 v125, v126, v127
	v_cvt_pk_bf16_f32 v126, v120, v121
	v_cvt_pk_bf16_f32 v127, v122, v123
	s_nop 1
	v_permlane16_swap_b32_e32 v124, v126
	v_permlane16_swap_b32_e32 v125, v127
	global_store_dwordx4 v[148:149], v[124:127], off
	v_cvt_pk_bf16_f32 v116, v116, v117
	v_cvt_pk_bf16_f32 v117, v118, v119
	v_cvt_pk_bf16_f32 v118, v108, v109
	v_cvt_pk_bf16_f32 v119, v110, v111
	s_nop 1
	v_permlane16_swap_b32_e32 v116, v118
	v_permlane16_swap_b32_e32 v117, v119
	global_store_dwordx4 v[148:149], v[116:119], off offset:256
	v_add_u32_e32 v152, 0x10, v150
	v_mad_i64_i32 v[148:149], s[24:25], v152, s1, v[140:141]
	v_lshl_add_u64 v[148:149], v[148:149], 0, v[142:143]
	v_cvt_pk_bf16_f32 v112, v112, v113
	v_cvt_pk_bf16_f32 v113, v114, v115
	v_cvt_pk_bf16_f32 v114, v104, v105
	v_cvt_pk_bf16_f32 v115, v106, v107
	s_nop 1
	v_permlane16_swap_b32_e32 v112, v114
	v_permlane16_swap_b32_e32 v113, v115
	global_store_dwordx4 v[148:149], v[112:115], off
	v_cvt_pk_bf16_f32 v100, v100, v101
	v_cvt_pk_bf16_f32 v101, v102, v103
	v_cvt_pk_bf16_f32 v102, v92, v93
	v_cvt_pk_bf16_f32 v103, v94, v95
	s_nop 1
	v_permlane16_swap_b32_e32 v100, v102
	v_permlane16_swap_b32_e32 v101, v103
	global_store_dwordx4 v[148:149], v[100:103], off offset:256
	v_add_u32_e32 v152, 0x20, v150
	v_mad_i64_i32 v[148:149], s[24:25], v152, s1, v[140:141]
	v_lshl_add_u64 v[148:149], v[148:149], 0, v[142:143]
	v_cvt_pk_bf16_f32 v96, v96, v97
	v_cvt_pk_bf16_f32 v97, v98, v99
	v_cvt_pk_bf16_f32 v98, v88, v89
	v_cvt_pk_bf16_f32 v99, v90, v91
	s_nop 1
	v_permlane16_swap_b32_e32 v96, v98
	v_permlane16_swap_b32_e32 v97, v99
	global_store_dwordx4 v[148:149], v[96:99], off
	v_cvt_pk_bf16_f32 v84, v84, v85
	v_cvt_pk_bf16_f32 v85, v86, v87
	v_cvt_pk_bf16_f32 v86, v76, v77
	v_cvt_pk_bf16_f32 v87, v78, v79
	s_nop 1
	v_permlane16_swap_b32_e32 v84, v86
	v_permlane16_swap_b32_e32 v85, v87
	global_store_dwordx4 v[148:149], v[84:87], off offset:256
	v_add_u32_e32 v152, 0x30, v150
	v_mad_i64_i32 v[148:149], s[24:25], v152, s1, v[140:141]
	v_lshl_add_u64 v[148:149], v[148:149], 0, v[142:143]
	v_cvt_pk_bf16_f32 v80, v80, v81
	v_cvt_pk_bf16_f32 v81, v82, v83
	v_cvt_pk_bf16_f32 v82, v72, v73
	v_cvt_pk_bf16_f32 v83, v74, v75
	s_nop 1
	v_permlane16_swap_b32_e32 v80, v82
	v_permlane16_swap_b32_e32 v81, v83
	global_store_dwordx4 v[148:149], v[80:83], off
	v_cvt_pk_bf16_f32 v68, v68, v69
	v_cvt_pk_bf16_f32 v69, v70, v71
	v_cvt_pk_bf16_f32 v70, v64, v65
	v_cvt_pk_bf16_f32 v71, v66, v67
	s_nop 1
	v_permlane16_swap_b32_e32 v68, v70
	v_permlane16_swap_b32_e32 v69, v71
	global_store_dwordx4 v[148:149], v[68:71], off offset:256
	v_add_u32_e32 v152, 0x80, v150
	v_mad_i64_i32 v[148:149], s[24:25], v152, s1, v[140:141]
	v_lshl_add_u64 v[148:149], v[148:149], 0, v[142:143]
	v_cvt_pk_bf16_f32 v60, v60, v61
	v_cvt_pk_bf16_f32 v61, v62, v63
	v_cvt_pk_bf16_f32 v62, v56, v57
	v_cvt_pk_bf16_f32 v63, v58, v59
	s_nop 1
	v_permlane16_swap_b32_e32 v60, v62
	v_permlane16_swap_b32_e32 v61, v63
	global_store_dwordx4 v[148:149], v[60:63], off
	v_cvt_pk_bf16_f32 v52, v52, v53
	v_cvt_pk_bf16_f32 v53, v54, v55
	v_cvt_pk_bf16_f32 v54, v44, v45
	v_cvt_pk_bf16_f32 v55, v46, v47
	s_nop 1
	v_permlane16_swap_b32_e32 v52, v54
	v_permlane16_swap_b32_e32 v53, v55
	global_store_dwordx4 v[148:149], v[52:55], off offset:256
	v_add_u32_e32 v152, 0x90, v150
	v_mad_i64_i32 v[148:149], s[24:25], v152, s1, v[140:141]
	v_lshl_add_u64 v[148:149], v[148:149], 0, v[142:143]
	v_cvt_pk_bf16_f32 v48, v48, v49
	v_cvt_pk_bf16_f32 v49, v50, v51
	v_cvt_pk_bf16_f32 v50, v40, v41
	v_cvt_pk_bf16_f32 v51, v42, v43
	s_nop 1
	v_permlane16_swap_b32_e32 v48, v50
	v_permlane16_swap_b32_e32 v49, v51
	global_store_dwordx4 v[148:149], v[48:51], off
	v_cvt_pk_bf16_f32 v36, v36, v37
	v_cvt_pk_bf16_f32 v37, v38, v39
	v_cvt_pk_bf16_f32 v38, v28, v29
	v_cvt_pk_bf16_f32 v39, v30, v31
	s_nop 1
	v_permlane16_swap_b32_e32 v36, v38
	v_permlane16_swap_b32_e32 v37, v39
	global_store_dwordx4 v[148:149], v[36:39], off offset:256
	v_add_u32_e32 v152, 0xa0, v150
	v_mad_i64_i32 v[148:149], s[24:25], v152, s1, v[140:141]
	v_lshl_add_u64 v[148:149], v[148:149], 0, v[142:143]
	v_cvt_pk_bf16_f32 v32, v32, v33
	v_cvt_pk_bf16_f32 v33, v34, v35
	v_cvt_pk_bf16_f32 v34, v24, v25
	v_cvt_pk_bf16_f32 v35, v26, v27
	s_nop 1
	v_permlane16_swap_b32_e32 v32, v34
	v_permlane16_swap_b32_e32 v33, v35
	global_store_dwordx4 v[148:149], v[32:35], off
	v_cvt_pk_bf16_f32 v20, v20, v21
	v_cvt_pk_bf16_f32 v21, v22, v23
	v_cvt_pk_bf16_f32 v22, v12, v13
	v_cvt_pk_bf16_f32 v23, v14, v15
	s_nop 1
	v_permlane16_swap_b32_e32 v20, v22
	v_permlane16_swap_b32_e32 v21, v23
	global_store_dwordx4 v[148:149], v[20:23], off offset:256
	v_add_u32_e32 v152, 0xb0, v150
	v_mad_i64_i32 v[148:149], s[24:25], v152, s1, v[140:141]
	v_lshl_add_u64 v[148:149], v[148:149], 0, v[142:143]
	v_cvt_pk_bf16_f32 v16, v16, v17
	v_cvt_pk_bf16_f32 v17, v18, v19
	v_cvt_pk_bf16_f32 v18, v8, v9
	v_cvt_pk_bf16_f32 v19, v10, v11
	s_nop 1
	v_permlane16_swap_b32_e32 v16, v18
	v_permlane16_swap_b32_e32 v17, v19
	global_store_dwordx4 v[148:149], v[16:19], off
	v_cvt_pk_bf16_f32 v4, v4, v5
	v_cvt_pk_bf16_f32 v5, v6, v7
	v_cvt_pk_bf16_f32 v6, v0, v1
	v_cvt_pk_bf16_f32 v7, v2, v3
	s_nop 1
	v_permlane16_swap_b32_e32 v4, v6
	v_permlane16_swap_b32_e32 v5, v7
	global_store_dwordx4 v[148:149], v[4:7], off offset:256
	s_and_b64 vcc, exec, s[38:39]
	s_mov_b32 s30, s0
	s_mov_b32 s31, s2
	s_mov_b64 s[44:45], s[40:41]
	s_mov_b64 s[42:43], s[36:37]
	s_cbranch_vccz .LBB0_363
	s_waitcnt vmcnt(0)
	s_cmpk_gt_u32 s23, 0xff
	s_cbranch_scc1 .LBB0_374
	s_barrier
